# gdnprep: triangular-solve LDS reads ring-buffered 13 deep + x-init global loads batched; bpost: invariant norm-weight loads hoisted, per-head inputs prefetched per token
# speedup vs baseline: 1.0229x; 1.0229x over previous
; DI int otid() { int t = (int)__builtin_amdgcn_workitem_id_x(); asm volatile("" : "+v"(t)); return t; }
; DI float bf2f(unsigned h) { return __uint_as_float(h << 16); }
; DI void bpost_item(const Params& p, int l, int b, int item, bf16_t* lds) {
;   const int lane = otid() & 63, wid = otid() >> 6;
;   const int t0 = item * 16;
;   const bf16_t* RB = (const bf16_t*)(p.ws + OFF_RB);
;   const bf16_t* YQ = (const bf16_t*)(p.ws + OFF_YQ);
;   const bf16_t* YKV = (const bf16_t*)(p.ws + OFF_HB);
;   bf16_t* QB = (bf16_t*)(p.ws + OFF_QB); bf16_t* KB = (bf16_t*)(p.ws + OFF_KB);
;   float* srs = (float*)(lds + 64 * 130);
;   float invf = 1.000000000e+00f;
;   {
;     const int fi = lane & 15;
;     invf = (fi == 1) ? 5.623413324e-01f : invf;
;     invf = (fi == 2) ? 3.162277639e-01f : invf;
;     invf = (fi == 3) ? 1.778279394e-01f : invf;
;     invf = (fi == 4) ? 1.000000015e-01f : invf;
;     invf = (fi == 5) ? 5.623413250e-02f : invf;
;     invf = (fi == 6) ? 3.162277490e-02f : invf;
;     invf = (fi == 7) ? 1.778279431e-02f : invf;
;     invf = (fi == 8) ? 9.999999776e-03f : invf;
;     invf = (fi == 9) ? 5.623413250e-03f : invf;
;     invf = (fi == 10) ? 3.162277630e-03f : invf;
;     invf = (fi == 11) ? 1.778279431e-03f : invf;
;     invf = (fi == 12) ? 1.000000047e-03f : invf;
;     invf = (fi == 13) ? 5.623413017e-04f : invf;
;     invf = (fi == 14) ? 3.162277571e-04f : invf;
;     invf = (fi == 15) ? 1.778279402e-04f : invf;
;   }
;   __syncthreads();
;   for (int rr = 0; rr < 4; ++rr) {
;     const int t = t0 + wid * 4 + rr;
;     float ssq = 0.f, sskv = 0.f;
;     {
;       const bf16_t* q = RB + (size_t)t * 768;
; #pragma unroll
;       for (int j = 0; j < 6; ++j) { float v = bf2f(q[lane + 64 * j]); ssq += v * v; }
; #pragma unroll
;       for (int j = 0; j < 4; ++j) { float v = bf2f(q[384 + lane + 64 * j]); sskv += v * v; }
;     }
;     ssq = wave_sum(ssq); sskv = wave_sum(sskv);
;     const float rq = rsqrtf(ssq * (1.f / 384.f) + EPS), rkv = rsqrtf(sskv * (1.f / 256.f) + EPS);
;     if (lane == 0) srs[wid * 4 + rr] = rkv;
;     const float ang = (float)p.pos[(size_t)b * TT + t] * invf;
;     float sn, cs; sincosf(ang, &sn, &cs);
;     const float kr = lane < 32 ? bf2f(RB[(size_t)t * 768 + 640 + lane]) : 0.f;
.LBB0_450:
	s_cmpk_gt_i32 s96, 0x3ff
	s_mov_b64 s[0:1], -1
	s_cbranch_scc0 .LBB0_510
	v_mov_b32_e32 v0, v201
	v_mov_b32_e32 v2, v201
	v_and_b32_e32 v6, 63, v0
	v_lshlrev_b32_e32 v8, 2, v6
	s_barrier
	global_load_dword v28, v8, s[14:15]
	global_load_dword v29, v8, s[90:91]
	v_and_b32_e32 v0, 15, v0
	v_cmp_eq_u32_e32 vcc, 1, v0
	v_mov_b32_e32 v3, 0x3f0ff59a
	v_mov_b32_e32 v4, 0x3ea1e89b
	v_cndmask_b32_e32 v3, 1.0, v3, vcc
	v_cmp_ne_u32_e32 vcc, 2, v0
	v_ashrrev_i32_e32 v14, 4, v2
	v_xor_b32_e32 v2, 32, v227
	v_cndmask_b32_e32 v3, v4, v3, vcc
	v_cmp_ne_u32_e32 vcc, 3, v0
	v_mov_b32_e32 v4, 0x3e361887
	v_and_b32_e32 v15, -4, v14
	v_cndmask_b32_e32 v3, v4, v3, vcc
	v_cmp_ne_u32_e32 vcc, 4, v0
	v_mov_b32_e32 v4, 0x3dcccccd
	v_mov_b32_e32 v9, v1
	v_cndmask_b32_e32 v3, v4, v3, vcc
	v_cmp_ne_u32_e32 vcc, 5, v0
	v_mov_b32_e32 v4, 0x3d6655c3
	s_mov_b32 s4, 0
	v_cndmask_b32_e32 v3, v4, v3, vcc
	v_cmp_ne_u32_e32 vcc, 6, v0
	v_mov_b32_e32 v4, 0x3d0186e2
	v_cmp_eq_u32_e64 s[38:39], 0, v6
	v_cndmask_b32_e32 v3, v4, v3, vcc
	v_cmp_ne_u32_e32 vcc, 7, v0
	v_mov_b32_e32 v4, 0x3c91ad39
	v_cmp_gt_u32_e64 s[40:41], 32, v6
	v_cndmask_b32_e32 v3, v4, v3, vcc
	v_cmp_ne_u32_e32 vcc, 8, v0
	v_mov_b32_e32 v4, 0x3c23d70a
	v_cmp_gt_u32_e64 s[42:43], 16, v6
	v_cndmask_b32_e32 v3, v4, v3, vcc
	v_cmp_ne_u32_e32 vcc, 9, v0
	v_mov_b32_e32 v4, 0x3bb8449c
	s_nop 0
	v_cndmask_b32_e32 v3, v4, v3, vcc
	v_cmp_ne_u32_e32 vcc, 10, v0
	v_mov_b32_e32 v4, 0x3b4f3e37
	s_nop 0
	v_cndmask_b32_e32 v3, v4, v3, vcc
	v_cmp_ne_u32_e32 vcc, 11, v0
	v_mov_b32_e32 v4, 0x3ae91528
	s_nop 0
	v_cndmask_b32_e32 v3, v4, v3, vcc
	v_cmp_ne_u32_e32 vcc, 12, v0
	v_mov_b32_e32 v4, 0x3a83126f
	s_nop 0
	v_cndmask_b32_e32 v3, v4, v3, vcc
	v_cmp_ne_u32_e32 vcc, 13, v0
	v_mov_b32_e32 v4, 0x3a136a16
	s_nop 0
	v_cndmask_b32_e32 v3, v4, v3, vcc
	v_cmp_ne_u32_e32 vcc, 14, v0
	v_mov_b32_e32 v4, 0x39a5cb5f
	s_nop 0
	v_cndmask_b32_e32 v3, v4, v3, vcc
	v_cmp_ne_u32_e32 vcc, 15, v0
	v_mov_b32_e32 v0, 0x393a7753
	s_nop 0
	v_cndmask_b32_e32 v30, v0, v3, vcc
	v_and_b32_e32 v0, 64, v227
	v_add_u32_e32 v0, 64, v0
	v_cmp_lt_i32_e32 vcc, v2, v0
	s_nop 1
	v_cndmask_b32_e32 v2, v227, v2, vcc
	v_lshlrev_b32_e32 v31, 2, v2
	v_xor_b32_e32 v2, 16, v227
	v_cmp_lt_i32_e32 vcc, v2, v0
	s_nop 1
	v_cndmask_b32_e32 v2, v227, v2, vcc
	v_lshlrev_b32_e32 v32, 2, v2
	v_xor_b32_e32 v2, 8, v227
	v_cmp_lt_i32_e32 vcc, v2, v0
	s_nop 1
	v_cndmask_b32_e32 v2, v227, v2, vcc
	v_lshlrev_b32_e32 v33, 2, v2
	v_xor_b32_e32 v2, 4, v227
	v_cmp_lt_i32_e32 vcc, v2, v0
	s_nop 1
	v_cndmask_b32_e32 v2, v227, v2, vcc
	v_lshlrev_b32_e32 v34, 2, v2
	v_xor_b32_e32 v2, 2, v227
	v_cmp_lt_i32_e32 vcc, v2, v0
	s_nop 1
	v_cndmask_b32_e32 v2, v227, v2, vcc
	v_lshlrev_b32_e32 v35, 2, v2
	v_xor_b32_e32 v2, 1, v227
	v_cmp_lt_i32_e32 vcc, v2, v0
	s_nop 1
	v_cndmask_b32_e32 v0, v227, v2, vcc
	v_lshlrev_b32_e32 v36, 2, v0
	v_lshlrev_b32_e32 v0, 1, v6
	v_lshl_add_u64 v[2:3], s[94:95], 0, v[0:1]
	v_lshl_add_u64 v[4:5], s[20:21], 0, v[0:1]
	v_lshl_add_u64 v[10:11], s[64:65], 0, v[0:1]
	v_lshl_add_u64 v[12:13], s[66:67], 0, v[0:1]
	v_lshlrev_b32_e32 v0, 2, v14
	v_and_b32_e32 v0, -16, v0
	v_lshl_add_u64 v[6:7], s[14:15], 0, v[8:9]
	v_lshl_add_u64 v[8:9], s[90:91], 0, v[8:9]
	v_add_u32_e32 v37, 0x4100, v0
	v_add_u32_e32 v14, s85, v15
	s_and_saveexec_b64 s[98:99], s[40:41]
	global_load_dword v90, v[6:7], off offset:256
	global_load_dword v91, v[8:9], off offset:256
	s_mov_b64 exec, s[98:99]
	s_branch .LBB0_453

; DI float bf2f(unsigned h) { return __uint_as_float(h << 16); }
; DI bf16_t f2bf(float f) { return (bf16_t)(pk2(f, 0.f) & 0xffffu); }
; DI void bpost_item(const Params& p, int l, int b, int item, bf16_t* lds) {
;     ...
;     const float rq = rsqrtf(ssq * (1.f / 384.f) + EPS), rkv = rsqrtf(sskv * (1.f / 256.f) + EPS);
;     if (lane == 0) srs[wid * 4 + rr] = rkv;
;     const float ang = (float)p.pos[(size_t)b * TT + t] * invf;
;     float sn, cs; sincosf(ang, &sn, &cs);
;     const float kr = lane < 32 ? bf2f(RB[(size_t)t * 768 + 640 + lane]) : 0.f;
; #pragma unroll
;     for (int h = 0; h < 4; ++h) {
; #pragma unroll
;       for (int qk = 0; qk < 2; ++qk) {
;         float e0, e1;
;         if (qk == 0) { e0 = bf2f(YQ[(size_t)t * 384 + h * 96 + lane]) * rq; e1 = lane < 32 ? bf2f(YQ[(size_t)t * 384 + h * 96 + 64 + lane]) * rq : 0.f; }
;         else { e0 = bf2f(YKV[(size_t)t * 768 + h * 192 + lane]) * rkv; e1 = kr; }
;         float ss = wave_sum(e0 * e0 + e1 * e1);
;         const float r = rsqrtf(ss * (1.f / 96.f) + EPS);
;         const float* nw = (qk == 0 ? p.mqn : p.mkn) + l * 96;
;         float n0 = e0 * r * nw[lane];
;         float n1 = lane < 32 ? e1 * r * nw[64 + lane] : 0.f;
;         float pr = __shfl_xor(n1, 16);
;         float ro = (lane < 16) ? (n1 * cs - pr * sn) : (n1 * cs + pr * sn);
;         const float sc = qk == 0 ? 0.10206207261596577f * LOG2E : 1.f;
;         bf16_t* dst = (qk == 0 ? QB : KB) + (size_t)t * 384 + h * 96;
;         dst[lane] = f2bf(n0 * sc);
;         if (lane < 32) dst[64 + lane] = f2bf(ro * sc);
.LBB0_461:
	s_or_b64 exec, exec, s[0:1]
	v_mul_f32_e32 v18, 0x4b800000, v17
	v_cndmask_b32_e32 v17, v17, v18, vcc
	v_rsq_f32_e32 v17, v17
	v_lshl_add_u64 v[20:21], v[12:13], 0, v[22:23]
	v_lshl_add_u64 v[92:93], v[22:23], 1, v[4:5]
	global_load_ushort v95, v[20:21], off offset:192
	global_load_ushort v96, v[20:21], off offset:384
	global_load_ushort v97, v[20:21], off offset:576
	global_load_ushort v98, v[92:93], off
	global_load_ushort v99, v[92:93], off offset:384
	global_load_ushort v100, v[92:93], off offset:768
	global_load_ushort v101, v[92:93], off offset:1152
	s_and_saveexec_b64 s[98:99], s[40:41]
	global_load_ushort v102, v[20:21], off offset:320
	global_load_ushort v103, v[20:21], off offset:512
	global_load_ushort v104, v[20:21], off offset:704
	s_mov_b64 exec, s[98:99]
	v_mul_f32_e32 v18, 0x45800000, v17
	v_cndmask_b32_e32 v39, v17, v18, vcc
	global_load_ushort v17, v[20:21], off
	s_and_saveexec_b64 s[0:1], s[40:41]
	s_cbranch_execz .LBB0_463
	global_load_ushort v18, v[20:21], off offset:128
	s_waitcnt vmcnt(0)
	v_lshlrev_b32_e32 v18, 16, v18
	v_mul_f32_e32 v25, v39, v18
.LBB0_463:
	s_or_b64 exec, exec, s[0:1]
	s_waitcnt vmcnt(0)
	v_lshlrev_b32_e32 v17, 16, v17
	v_mul_f32_e32 v24, v39, v17
	v_pk_mul_f32 v[18:19], v[24:25], v[24:25]
	s_nop 0
	v_add_f32_e32 v17, v18, v19
	ds_bpermute_b32 v18, v31, v17
	s_waitcnt lgkmcnt(0)
	v_add_f32_e32 v17, v17, v18
	ds_bpermute_b32 v18, v32, v17
	s_waitcnt lgkmcnt(0)
	v_add_f32_e32 v17, v17, v18
	ds_bpermute_b32 v18, v33, v17
	s_waitcnt lgkmcnt(0)
	v_add_f32_e32 v17, v17, v18
	ds_bpermute_b32 v18, v34, v17
	s_waitcnt lgkmcnt(0)
	v_add_f32_e32 v17, v17, v18
	ds_bpermute_b32 v18, v35, v17
	s_waitcnt lgkmcnt(0)
	v_add_f32_e32 v17, v17, v18
	ds_bpermute_b32 v18, v36, v17
	s_waitcnt lgkmcnt(0)
	v_add_f32_e32 v17, v17, v18
	v_fmamk_f32 v17, v17, 0x3c2aaaab, v200
	v_mul_f32_e32 v18, 0x4b800000, v17
	v_cmp_gt_f32_e32 vcc, s58, v17
	s_nop 1
	v_cndmask_b32_e32 v17, v17, v18, vcc
	v_rsq_f32_e32 v17, v17
	s_nop 0
	v_mul_f32_e32 v18, 0x45800000, v17
	v_cndmask_b32_e32 v18, v17, v18, vcc
	v_mov_b32_e32 v17, 0
	s_and_saveexec_b64 s[0:1], s[40:41]
	s_cbranch_execz .LBB0_465
	v_mov_b32_e32 v17, v90
	v_mul_f32_e32 v19, v25, v18
	v_mul_f32_e32 v17, v19, v17

; DI float bf2f(unsigned h) { return __uint_as_float(h << 16); }
; DI bf16_t f2bf(float f) { return (bf16_t)(pk2(f, 0.f) & 0xffffu); }
; DI void bpost_item(const Params& p, int l, int b, int item, bf16_t* lds) {
;     ...
;         float e0, e1;
;         if (qk == 0) { e0 = bf2f(YQ[(size_t)t * 384 + h * 96 + lane]) * rq; e1 = lane < 32 ? bf2f(YQ[(size_t)t * 384 + h * 96 + 64 + lane]) * rq : 0.f; }
;         else { e0 = bf2f(YKV[(size_t)t * 768 + h * 192 + lane]) * rkv; e1 = kr; }
;         float ss = wave_sum(e0 * e0 + e1 * e1);
;         const float r = rsqrtf(ss * (1.f / 96.f) + EPS);
;         const float* nw = (qk == 0 ? p.mqn : p.mkn) + l * 96;
;         float n0 = e0 * r * nw[lane];
;         float n1 = lane < 32 ? e1 * r * nw[64 + lane] : 0.f;
;         float pr = __shfl_xor(n1, 16);
;         float ro = (lane < 16) ? (n1 * cs - pr * sn) : (n1 * cs + pr * sn);
;         const float sc = qk == 0 ? 0.10206207261596577f * LOG2E : 1.f;
;         bf16_t* dst = (qk == 0 ? QB : KB) + (size_t)t * 384 + h * 96;
;         dst[lane] = f2bf(n0 * sc);
;         if (lane < 32) dst[64 + lane] = f2bf(ro * sc);
.LBB0_467:
	s_or_b64 exec, exec, s[0:1]
	v_lshl_add_u64 v[22:23], v[22:23], 1, v[4:5]
	v_mov_b32_e32 v17, v98
	v_lshlrev_b32_e32 v17, 16, v17
	v_mul_f32_e32 v17, v38, v17
	s_waitcnt lgkmcnt(0)
	v_pk_mul_f32 v[24:25], v[16:17], v[16:17]
	s_nop 0
	v_add_f32_e32 v25, v24, v25
	ds_bpermute_b32 v26, v31, v25
	s_waitcnt lgkmcnt(0)
	v_add_f32_e32 v25, v25, v26
	ds_bpermute_b32 v26, v32, v25
	s_waitcnt lgkmcnt(0)
	v_add_f32_e32 v25, v25, v26
	ds_bpermute_b32 v26, v33, v25
	s_waitcnt lgkmcnt(0)
	v_add_f32_e32 v25, v25, v26
	ds_bpermute_b32 v26, v34, v25
	s_waitcnt lgkmcnt(0)
	v_add_f32_e32 v25, v25, v26
	ds_bpermute_b32 v26, v35, v25
	s_waitcnt lgkmcnt(0)
	v_add_f32_e32 v25, v25, v26
	ds_bpermute_b32 v26, v36, v25
	s_waitcnt lgkmcnt(0)
	v_add_f32_e32 v25, v25, v26
	v_fmamk_f32 v25, v25, 0x3c2aaaab, v200
	v_mul_f32_e32 v26, 0x4b800000, v25
	v_cmp_gt_f32_e32 vcc, s58, v25
	s_nop 1
	v_cndmask_b32_e32 v25, v25, v26, vcc
	v_rsq_f32_e32 v25, v25
	s_nop 0
	v_mul_f32_e32 v26, 0x45800000, v25
	v_cndmask_b32_e32 v26, v25, v26, vcc
	v_mov_b32_e32 v25, 0
	s_and_saveexec_b64 s[0:1], s[40:41]
	s_cbranch_execz .LBB0_469
	v_mov_b32_e32 v25, v91
	v_mul_f32_e32 v27, v16, v26
	v_mul_f32_e32 v25, v27, v25

; DI float bf2f(unsigned h) { return __uint_as_float(h << 16); }
; DI bf16_t f2bf(float f) { return (bf16_t)(pk2(f, 0.f) & 0xffffu); }
; DI void bpost_item(const Params& p, int l, int b, int item, bf16_t* lds) {
;     ...
;         float e0, e1;
;         if (qk == 0) { e0 = bf2f(YQ[(size_t)t * 384 + h * 96 + lane]) * rq; e1 = lane < 32 ? bf2f(YQ[(size_t)t * 384 + h * 96 + 64 + lane]) * rq : 0.f; }
;         else { e0 = bf2f(YKV[(size_t)t * 768 + h * 192 + lane]) * rkv; e1 = kr; }
;         float ss = wave_sum(e0 * e0 + e1 * e1);
;         const float r = rsqrtf(ss * (1.f / 96.f) + EPS);
;         const float* nw = (qk == 0 ? p.mqn : p.mkn) + l * 96;
;         float n0 = e0 * r * nw[lane];
;         float n1 = lane < 32 ? e1 * r * nw[64 + lane] : 0.f;
;         float pr = __shfl_xor(n1, 16);
;         float ro = (lane < 16) ? (n1 * cs - pr * sn) : (n1 * cs + pr * sn);
;         const float sc = qk == 0 ? 0.10206207261596577f * LOG2E : 1.f;
;         bf16_t* dst = (qk == 0 ? QB : KB) + (size_t)t * 384 + h * 96;
;         dst[lane] = f2bf(n0 * sc);
;         if (lane < 32) dst[64 + lane] = f2bf(ro * sc);
.LBB0_471:
	s_or_b64 exec, exec, s[0:1]
	v_mov_b32_e32 v25, v95
	s_waitcnt lgkmcnt(0)
	v_mov_b32_e32 v17, 0
	v_mov_b32_e32 v27, 0
	s_and_saveexec_b64 s[0:1], s[40:41]
	s_cbranch_execz .LBB0_473
	v_mov_b32_e32 v26, v102
	v_lshlrev_b32_e32 v26, 16, v26
	v_mul_f32_e32 v27, v39, v26
.LBB0_473:
	s_or_b64 exec, exec, s[0:1]
	s_waitcnt vmcnt(0)
	v_lshlrev_b32_e32 v25, 16, v25
	v_mul_f32_e32 v26, v39, v25
	v_pk_mul_f32 v[40:41], v[26:27], v[26:27]
	s_nop 0
	v_add_f32_e32 v25, v40, v41
	ds_bpermute_b32 v40, v31, v25
	s_waitcnt lgkmcnt(0)
	v_add_f32_e32 v25, v25, v40
	ds_bpermute_b32 v40, v32, v25
	s_waitcnt lgkmcnt(0)
	v_add_f32_e32 v25, v25, v40
	ds_bpermute_b32 v40, v33, v25
	s_waitcnt lgkmcnt(0)
	v_add_f32_e32 v25, v25, v40
	ds_bpermute_b32 v40, v34, v25
	s_waitcnt lgkmcnt(0)
	v_add_f32_e32 v25, v25, v40
	ds_bpermute_b32 v40, v35, v25
	s_waitcnt lgkmcnt(0)
	v_add_f32_e32 v25, v25, v40
	ds_bpermute_b32 v40, v36, v25
	s_waitcnt lgkmcnt(0)
	v_add_f32_e32 v25, v25, v40
	v_fmamk_f32 v25, v25, 0x3c2aaaab, v200
	v_mul_f32_e32 v40, 0x4b800000, v25
	v_cmp_gt_f32_e32 vcc, s58, v25
	s_nop 1
	v_cndmask_b32_e32 v25, v25, v40, vcc
	v_rsq_f32_e32 v25, v25
	s_nop 0
	v_mul_f32_e32 v40, 0x45800000, v25
	v_cndmask_b32_e32 v25, v25, v40, vcc
	s_and_saveexec_b64 s[0:1], s[40:41]
	s_cbranch_execz .LBB0_475
	v_mov_b32_e32 v17, v90
	v_mul_f32_e32 v27, v27, v25
	v_mul_f32_e32 v17, v27, v17

; DI float bf2f(unsigned h) { return __uint_as_float(h << 16); }
; DI bf16_t f2bf(float f) { return (bf16_t)(pk2(f, 0.f) & 0xffffu); }
; DI void bpost_item(const Params& p, int l, int b, int item, bf16_t* lds) {
;     ...
;         float e0, e1;
;         if (qk == 0) { e0 = bf2f(YQ[(size_t)t * 384 + h * 96 + lane]) * rq; e1 = lane < 32 ? bf2f(YQ[(size_t)t * 384 + h * 96 + 64 + lane]) * rq : 0.f; }
;         else { e0 = bf2f(YKV[(size_t)t * 768 + h * 192 + lane]) * rkv; e1 = kr; }
;         float ss = wave_sum(e0 * e0 + e1 * e1);
;         const float r = rsqrtf(ss * (1.f / 96.f) + EPS);
;         const float* nw = (qk == 0 ? p.mqn : p.mkn) + l * 96;
;         float n0 = e0 * r * nw[lane];
;         float n1 = lane < 32 ? e1 * r * nw[64 + lane] : 0.f;
;         float pr = __shfl_xor(n1, 16);
;         float ro = (lane < 16) ? (n1 * cs - pr * sn) : (n1 * cs + pr * sn);
;         const float sc = qk == 0 ? 0.10206207261596577f * LOG2E : 1.f;
;         bf16_t* dst = (qk == 0 ? QB : KB) + (size_t)t * 384 + h * 96;
;         dst[lane] = f2bf(n0 * sc);
;         if (lane < 32) dst[64 + lane] = f2bf(ro * sc);
.LBB0_477:
	s_or_b64 exec, exec, s[0:1]
	v_mov_b32_e32 v17, v99
	v_lshlrev_b32_e32 v17, 16, v17
	v_mul_f32_e32 v17, v38, v17
	s_waitcnt lgkmcnt(0)
	v_fma_f32 v25, v17, v17, v24
	ds_bpermute_b32 v26, v31, v25
	s_waitcnt lgkmcnt(0)
	v_add_f32_e32 v25, v25, v26
	ds_bpermute_b32 v26, v32, v25
	s_waitcnt lgkmcnt(0)
	v_add_f32_e32 v25, v25, v26
	ds_bpermute_b32 v26, v33, v25
	s_waitcnt lgkmcnt(0)
	v_add_f32_e32 v25, v25, v26
	ds_bpermute_b32 v26, v34, v25
	s_waitcnt lgkmcnt(0)
	v_add_f32_e32 v25, v25, v26
	ds_bpermute_b32 v26, v35, v25
	s_waitcnt lgkmcnt(0)
	v_add_f32_e32 v25, v25, v26
	ds_bpermute_b32 v26, v36, v25
	s_waitcnt lgkmcnt(0)
	v_add_f32_e32 v25, v25, v26
	v_fmamk_f32 v25, v25, 0x3c2aaaab, v200
	v_mul_f32_e32 v26, 0x4b800000, v25
	v_cmp_gt_f32_e32 vcc, s58, v25
	s_nop 1
	v_cndmask_b32_e32 v25, v25, v26, vcc
	v_rsq_f32_e32 v25, v25
	s_nop 0
	v_mul_f32_e32 v26, 0x45800000, v25
	v_cndmask_b32_e32 v26, v25, v26, vcc
	v_mov_b32_e32 v25, 0
	s_and_saveexec_b64 s[0:1], s[40:41]
	s_cbranch_execz .LBB0_479
	v_mov_b32_e32 v25, v91
	v_mul_f32_e32 v27, v16, v26
	v_mul_f32_e32 v25, v27, v25

; DI float bf2f(unsigned h) { return __uint_as_float(h << 16); }
; DI bf16_t f2bf(float f) { return (bf16_t)(pk2(f, 0.f) & 0xffffu); }
; DI void bpost_item(const Params& p, int l, int b, int item, bf16_t* lds) {
;     ...
;         float e0, e1;
;         if (qk == 0) { e0 = bf2f(YQ[(size_t)t * 384 + h * 96 + lane]) * rq; e1 = lane < 32 ? bf2f(YQ[(size_t)t * 384 + h * 96 + 64 + lane]) * rq : 0.f; }
;         else { e0 = bf2f(YKV[(size_t)t * 768 + h * 192 + lane]) * rkv; e1 = kr; }
;         float ss = wave_sum(e0 * e0 + e1 * e1);
;         const float r = rsqrtf(ss * (1.f / 96.f) + EPS);
;         const float* nw = (qk == 0 ? p.mqn : p.mkn) + l * 96;
;         float n0 = e0 * r * nw[lane];
;         float n1 = lane < 32 ? e1 * r * nw[64 + lane] : 0.f;
;         float pr = __shfl_xor(n1, 16);
;         float ro = (lane < 16) ? (n1 * cs - pr * sn) : (n1 * cs + pr * sn);
;         const float sc = qk == 0 ? 0.10206207261596577f * LOG2E : 1.f;
;         bf16_t* dst = (qk == 0 ? QB : KB) + (size_t)t * 384 + h * 96;
;         dst[lane] = f2bf(n0 * sc);
;         if (lane < 32) dst[64 + lane] = f2bf(ro * sc);
.LBB0_481:
	s_or_b64 exec, exec, s[0:1]
	v_mov_b32_e32 v25, v96
	s_waitcnt lgkmcnt(0)
	v_mov_b32_e32 v17, 0
	v_mov_b32_e32 v27, 0
	s_and_saveexec_b64 s[0:1], s[40:41]
	s_cbranch_execz .LBB0_483
	v_mov_b32_e32 v26, v103
	v_lshlrev_b32_e32 v26, 16, v26
	v_mul_f32_e32 v27, v39, v26

; DI float bf2f(unsigned h) { return __uint_as_float(h << 16); }
; DI bf16_t f2bf(float f) { return (bf16_t)(pk2(f, 0.f) & 0xffffu); }
; DI void bpost_item(const Params& p, int l, int b, int item, bf16_t* lds) {
;     ...
;         float e0, e1;
;         if (qk == 0) { e0 = bf2f(YQ[(size_t)t * 384 + h * 96 + lane]) * rq; e1 = lane < 32 ? bf2f(YQ[(size_t)t * 384 + h * 96 + 64 + lane]) * rq : 0.f; }
;         else { e0 = bf2f(YKV[(size_t)t * 768 + h * 192 + lane]) * rkv; e1 = kr; }
;         float ss = wave_sum(e0 * e0 + e1 * e1);
;         const float r = rsqrtf(ss * (1.f / 96.f) + EPS);
;         const float* nw = (qk == 0 ? p.mqn : p.mkn) + l * 96;
;         float n0 = e0 * r * nw[lane];
;         float n1 = lane < 32 ? e1 * r * nw[64 + lane] : 0.f;
;         float pr = __shfl_xor(n1, 16);
;         float ro = (lane < 16) ? (n1 * cs - pr * sn) : (n1 * cs + pr * sn);
;         const float sc = qk == 0 ? 0.10206207261596577f * LOG2E : 1.f;
;         bf16_t* dst = (qk == 0 ? QB : KB) + (size_t)t * 384 + h * 96;
;         dst[lane] = f2bf(n0 * sc);
;         if (lane < 32) dst[64 + lane] = f2bf(ro * sc);
.LBB0_487:
	s_or_b64 exec, exec, s[0:1]
	v_mov_b32_e32 v17, v100
	v_lshlrev_b32_e32 v17, 16, v17
	v_mul_f32_e32 v17, v38, v17
	s_waitcnt lgkmcnt(0)
	v_fma_f32 v25, v17, v17, v24
	ds_bpermute_b32 v26, v31, v25
	s_waitcnt lgkmcnt(0)
	v_add_f32_e32 v25, v25, v26
	ds_bpermute_b32 v26, v32, v25
	s_waitcnt lgkmcnt(0)
	v_add_f32_e32 v25, v25, v26
	ds_bpermute_b32 v26, v33, v25
	s_waitcnt lgkmcnt(0)
	v_add_f32_e32 v25, v25, v26
	ds_bpermute_b32 v26, v34, v25
	s_waitcnt lgkmcnt(0)
	v_add_f32_e32 v25, v25, v26
	ds_bpermute_b32 v26, v35, v25
	s_waitcnt lgkmcnt(0)
	v_add_f32_e32 v25, v25, v26
	ds_bpermute_b32 v26, v36, v25
	s_waitcnt lgkmcnt(0)
	v_add_f32_e32 v25, v25, v26
	v_fmamk_f32 v25, v25, 0x3c2aaaab, v200
	v_mul_f32_e32 v26, 0x4b800000, v25
	v_cmp_gt_f32_e32 vcc, s58, v25
	s_nop 1
	v_cndmask_b32_e32 v25, v25, v26, vcc
	v_rsq_f32_e32 v25, v25
	s_nop 0
	v_mul_f32_e32 v26, 0x45800000, v25
	v_cndmask_b32_e32 v26, v25, v26, vcc
	v_mov_b32_e32 v25, 0
	s_and_saveexec_b64 s[0:1], s[40:41]
	s_cbranch_execz .LBB0_489
	v_mov_b32_e32 v25, v91
	v_mul_f32_e32 v27, v16, v26
	v_mul_f32_e32 v25, v27, v25

; DI float bf2f(unsigned h) { return __uint_as_float(h << 16); }
; DI bf16_t f2bf(float f) { return (bf16_t)(pk2(f, 0.f) & 0xffffu); }
; DI void bpost_item(const Params& p, int l, int b, int item, bf16_t* lds) {
;     ...
;         float e0, e1;
;         if (qk == 0) { e0 = bf2f(YQ[(size_t)t * 384 + h * 96 + lane]) * rq; e1 = lane < 32 ? bf2f(YQ[(size_t)t * 384 + h * 96 + 64 + lane]) * rq : 0.f; }
;         else { e0 = bf2f(YKV[(size_t)t * 768 + h * 192 + lane]) * rkv; e1 = kr; }
;         float ss = wave_sum(e0 * e0 + e1 * e1);
;         const float r = rsqrtf(ss * (1.f / 96.f) + EPS);
;         const float* nw = (qk == 0 ? p.mqn : p.mkn) + l * 96;
;         float n0 = e0 * r * nw[lane];
;         float n1 = lane < 32 ? e1 * r * nw[64 + lane] : 0.f;
;         float pr = __shfl_xor(n1, 16);
;         float ro = (lane < 16) ? (n1 * cs - pr * sn) : (n1 * cs + pr * sn);
;         const float sc = qk == 0 ? 0.10206207261596577f * LOG2E : 1.f;
;         bf16_t* dst = (qk == 0 ? QB : KB) + (size_t)t * 384 + h * 96;
;         dst[lane] = f2bf(n0 * sc);
;         if (lane < 32) dst[64 + lane] = f2bf(ro * sc);
.LBB0_491:
	s_or_b64 exec, exec, s[0:1]
	v_mov_b32_e32 v25, v97
	s_waitcnt lgkmcnt(0)
	v_mov_b32_e32 v17, 0
	v_mov_b32_e32 v27, 0
	s_and_saveexec_b64 s[0:1], s[40:41]
	s_cbranch_execz .LBB0_493
	v_mov_b32_e32 v20, v104
	v_lshlrev_b32_e32 v20, 16, v20
	v_mul_f32_e32 v27, v39, v20
.LBB0_493:
	s_or_b64 exec, exec, s[0:1]
	s_waitcnt vmcnt(0)
	v_lshlrev_b32_e32 v20, 16, v25
	v_mul_f32_e32 v26, v39, v20
	v_pk_mul_f32 v[20:21], v[26:27], v[26:27]
	s_nop 0
	v_add_f32_e32 v20, v20, v21
	ds_bpermute_b32 v21, v31, v20
	s_waitcnt lgkmcnt(0)
	v_add_f32_e32 v20, v20, v21
	ds_bpermute_b32 v21, v32, v20
	s_waitcnt lgkmcnt(0)
	v_add_f32_e32 v20, v20, v21
	ds_bpermute_b32 v21, v33, v20
	s_waitcnt lgkmcnt(0)
	v_add_f32_e32 v20, v20, v21
	ds_bpermute_b32 v21, v34, v20
	s_waitcnt lgkmcnt(0)
	v_add_f32_e32 v20, v20, v21
	ds_bpermute_b32 v21, v35, v20
	s_waitcnt lgkmcnt(0)
	v_add_f32_e32 v20, v20, v21
	ds_bpermute_b32 v21, v36, v20
	s_waitcnt lgkmcnt(0)
	v_add_f32_e32 v20, v20, v21
	v_fmamk_f32 v20, v20, 0x3c2aaaab, v200
	v_mul_f32_e32 v21, 0x4b800000, v20
	v_cmp_gt_f32_e32 vcc, s58, v20
	s_nop 1
	v_cndmask_b32_e32 v20, v20, v21, vcc
	v_rsq_f32_e32 v20, v20
	s_nop 0
	v_mul_f32_e32 v21, 0x45800000, v20
	v_cndmask_b32_e32 v20, v20, v21, vcc
	s_and_saveexec_b64 s[0:1], s[40:41]
	s_cbranch_execz .LBB0_495
	v_mov_b32_e32 v17, v90
	v_mul_f32_e32 v21, v27, v20
	v_mul_f32_e32 v17, v21, v17

; DI float bf2f(unsigned h) { return __uint_as_float(h << 16); }
; DI bf16_t f2bf(float f) { return (bf16_t)(pk2(f, 0.f) & 0xffffu); }
; DI void bpost_item(const Params& p, int l, int b, int item, bf16_t* lds) {
;     ...
;         float e0, e1;
;         if (qk == 0) { e0 = bf2f(YQ[(size_t)t * 384 + h * 96 + lane]) * rq; e1 = lane < 32 ? bf2f(YQ[(size_t)t * 384 + h * 96 + 64 + lane]) * rq : 0.f; }
;         else { e0 = bf2f(YKV[(size_t)t * 768 + h * 192 + lane]) * rkv; e1 = kr; }
;         float ss = wave_sum(e0 * e0 + e1 * e1);
;         const float r = rsqrtf(ss * (1.f / 96.f) + EPS);
;         const float* nw = (qk == 0 ? p.mqn : p.mkn) + l * 96;
;         float n0 = e0 * r * nw[lane];
;         float n1 = lane < 32 ? e1 * r * nw[64 + lane] : 0.f;
;         float pr = __shfl_xor(n1, 16);
;         float ro = (lane < 16) ? (n1 * cs - pr * sn) : (n1 * cs + pr * sn);
;         const float sc = qk == 0 ? 0.10206207261596577f * LOG2E : 1.f;
;         bf16_t* dst = (qk == 0 ? QB : KB) + (size_t)t * 384 + h * 96;
;         dst[lane] = f2bf(n0 * sc);
;         if (lane < 32) dst[64 + lane] = f2bf(ro * sc);
.LBB0_497:
	s_or_b64 exec, exec, s[0:1]
	v_mov_b32_e32 v17, v101
	v_lshlrev_b32_e32 v17, 16, v17
	v_mul_f32_e32 v17, v38, v17
	v_fmac_f32_e32 v24, v17, v17
	s_waitcnt lgkmcnt(0)
	ds_bpermute_b32 v20, v31, v24
	s_waitcnt lgkmcnt(0)
	v_add_f32_e32 v20, v24, v20
	ds_bpermute_b32 v21, v32, v20
	s_waitcnt lgkmcnt(0)
	v_add_f32_e32 v20, v20, v21
	ds_bpermute_b32 v21, v33, v20
	s_waitcnt lgkmcnt(0)
	v_add_f32_e32 v20, v20, v21
	ds_bpermute_b32 v21, v34, v20
	s_waitcnt lgkmcnt(0)
	v_add_f32_e32 v20, v20, v21
	ds_bpermute_b32 v21, v35, v20
	s_waitcnt lgkmcnt(0)
	v_add_f32_e32 v20, v20, v21
	ds_bpermute_b32 v21, v36, v20
	s_waitcnt lgkmcnt(0)
	v_add_f32_e32 v20, v20, v21
	v_fmamk_f32 v20, v20, 0x3c2aaaab, v200
	v_mul_f32_e32 v21, 0x4b800000, v20
	v_cmp_gt_f32_e32 vcc, s58, v20
	s_nop 1
	v_cndmask_b32_e32 v20, v20, v21, vcc
	v_rsq_f32_e32 v20, v20
	s_nop 0
	v_mul_f32_e32 v21, 0x45800000, v20
	v_cndmask_b32_e32 v21, v20, v21, vcc
	v_mov_b32_e32 v20, 0
	s_and_saveexec_b64 s[0:1], s[40:41]
	s_cbranch_execz .LBB0_499
	v_mov_b32_e32 v20, v91
	v_mul_f32_e32 v16, v16, v21
	v_mul_f32_e32 v20, v16, v20

; DI float bf2f(unsigned h) { return __uint_as_float(h << 16); }
; DI void gdnprep_item(const Params& p, int item, unsigned char* ldsb) {
;     ...
;   {
;     const int c = tid & 127; const bool isw = tid >= 128;
;     float x[64];
; #pragma unroll
;     for (int i = 0; i < 64; ++i) {
;       if (isw) x[i] = bf2f(sK[i * 136 + c]) * sbeta[i] * __expf(sgc[i]);
;       else x[i] = bf2f(CQ[(size_t)(t0 + i) * 1536 + 1024 + h * 128 + c]) * sbeta[i];
;     }
.LBB0_577:
	s_or_b64 exec, exec, s[0:1]
	ds_write_b32 v67, v0 offset:35008
	v_mul_f32_e32 v0, v5, v2
	v_cvt_pk_bf16_f32 v0, v0, s0
	v_and_b32_e32 v3, 0x7f, v42
	s_movk_i32 s0, 0x80
	s_lshl_b32 s6, s6, 7
	v_cmp_gt_i32_e32 vcc, s0, v42
	v_lshlrev_b32_e32 v2, 1, v3
	global_store_short v[50:51], v0, off offset:72
	s_waitcnt lgkmcnt(0)
	s_barrier
	s_and_saveexec_b64 s[0:1], vcc
	s_cbranch_execz .Lxinit_lds
	s_mul_i32 s8, s5, 0xc00
	s_mul_hi_i32 s7, s5, 0xc00
	s_add_u32 s8, s2, s8
	s_addc_u32 s7, s3, s7
	s_lshl_b32 s9, s6, 1
	s_add_u32 s8, s8, s9
	s_addc_u32 s9, s7, 0
	global_load_ushort v100, v2, s[8:9] offset:2048
	s_or_b32 s7, s5, 1
	s_mul_hi_i32 s8, s7, 0xc00
	s_mulk_i32 s7, 0xc00
	s_add_u32 s7, s2, s7
	s_addc_u32 s9, s3, s8
	s_lshl_b32 s8, s6, 1
	s_add_u32 s8, s7, s8
	s_addc_u32 s9, s9, 0
	global_load_ushort v101, v2, s[8:9] offset:2048
	s_or_b32 s7, s5, 2
	s_mul_hi_i32 s8, s7, 0xc00
	s_mulk_i32 s7, 0xc00
	s_add_u32 s7, s2, s7
	s_addc_u32 s9, s3, s8
	s_lshl_b32 s8, s6, 1
	s_add_u32 s8, s7, s8
	s_addc_u32 s9, s9, 0
	global_load_ushort v102, v2, s[8:9] offset:2048
	s_or_b32 s7, s5, 3
	s_mul_hi_i32 s8, s7, 0xc00
	s_mulk_i32 s7, 0xc00
	s_add_u32 s7, s2, s7
	s_addc_u32 s9, s3, s8
	s_lshl_b32 s8, s6, 1
	s_add_u32 s8, s7, s8
	s_addc_u32 s9, s9, 0
	global_load_ushort v103, v2, s[8:9] offset:2048
	s_or_b32 s7, s5, 4
	s_mul_hi_i32 s8, s7, 0xc00
	s_mulk_i32 s7, 0xc00
	s_add_u32 s7, s2, s7
	s_addc_u32 s9, s3, s8
	s_lshl_b32 s8, s6, 1
	s_add_u32 s8, s7, s8
	s_addc_u32 s9, s9, 0
	global_load_ushort v104, v2, s[8:9] offset:2048
	s_or_b32 s7, s5, 5
	s_mul_hi_i32 s8, s7, 0xc00
	s_mulk_i32 s7, 0xc00
	s_add_u32 s7, s2, s7
	s_addc_u32 s9, s3, s8
	s_lshl_b32 s8, s6, 1
	s_add_u32 s8, s7, s8
	s_addc_u32 s9, s9, 0
	global_load_ushort v105, v2, s[8:9] offset:2048
	s_or_b32 s7, s5, 6
	s_mul_hi_i32 s8, s7, 0xc00
	s_mulk_i32 s7, 0xc00
	s_add_u32 s7, s2, s7
	s_addc_u32 s9, s3, s8
	s_lshl_b32 s8, s6, 1
	s_add_u32 s8, s7, s8
	s_addc_u32 s9, s9, 0
	global_load_ushort v106, v2, s[8:9] offset:2048
	s_or_b32 s7, s5, 7
	s_mul_hi_i32 s8, s7, 0xc00
	s_mulk_i32 s7, 0xc00
	s_add_u32 s7, s2, s7
	s_addc_u32 s9, s3, s8
	s_lshl_b32 s8, s6, 1
	s_add_u32 s8, s7, s8
	s_addc_u32 s9, s9, 0
	global_load_ushort v107, v2, s[8:9] offset:2048
	s_or_b32 s7, s5, 8
	s_mul_hi_i32 s8, s7, 0xc00
	s_mulk_i32 s7, 0xc00
	s_add_u32 s7, s2, s7
	s_addc_u32 s9, s3, s8
	s_lshl_b32 s8, s6, 1
	s_add_u32 s8, s7, s8
	s_addc_u32 s9, s9, 0
	global_load_ushort v108, v2, s[8:9] offset:2048
	s_or_b32 s7, s5, 9
	s_mul_hi_i32 s8, s7, 0xc00
	s_mulk_i32 s7, 0xc00
	s_add_u32 s7, s2, s7
	s_addc_u32 s9, s3, s8
	s_lshl_b32 s8, s6, 1
	s_add_u32 s8, s7, s8
	s_addc_u32 s9, s9, 0
	global_load_ushort v109, v2, s[8:9] offset:2048
	s_or_b32 s7, s5, 10
	s_mul_hi_i32 s8, s7, 0xc00
	s_mulk_i32 s7, 0xc00
	s_add_u32 s7, s2, s7
	s_addc_u32 s9, s3, s8
	s_lshl_b32 s8, s6, 1
	s_add_u32 s8, s7, s8
	s_addc_u32 s9, s9, 0
	global_load_ushort v110, v2, s[8:9] offset:2048
	s_or_b32 s7, s5, 11
	s_mul_hi_i32 s8, s7, 0xc00
	s_mulk_i32 s7, 0xc00
	s_add_u32 s7, s2, s7
	s_addc_u32 s9, s3, s8
	s_lshl_b32 s8, s6, 1
	s_add_u32 s8, s7, s8
	s_addc_u32 s9, s9, 0
	global_load_ushort v111, v2, s[8:9] offset:2048
	s_or_b32 s7, s5, 12
	s_mul_hi_i32 s8, s7, 0xc00
	s_mulk_i32 s7, 0xc00
	s_add_u32 s7, s2, s7
	s_addc_u32 s9, s3, s8
	s_lshl_b32 s8, s6, 1
	s_add_u32 s8, s7, s8
	s_addc_u32 s9, s9, 0
	global_load_ushort v112, v2, s[8:9] offset:2048
	s_or_b32 s7, s5, 13
	s_mul_hi_i32 s8, s7, 0xc00
	s_mulk_i32 s7, 0xc00
	s_add_u32 s7, s2, s7
	s_addc_u32 s9, s3, s8
	s_lshl_b32 s8, s6, 1
	s_add_u32 s8, s7, s8
	s_addc_u32 s9, s9, 0
	global_load_ushort v113, v2, s[8:9] offset:2048
	s_or_b32 s7, s5, 14
	s_mul_hi_i32 s8, s7, 0xc00
	s_mulk_i32 s7, 0xc00
	s_add_u32 s7, s2, s7
	s_addc_u32 s9, s3, s8
	s_lshl_b32 s8, s6, 1
	s_add_u32 s8, s7, s8
	s_addc_u32 s9, s9, 0
	global_load_ushort v114, v2, s[8:9] offset:2048
	s_or_b32 s7, s5, 15
	s_mul_hi_i32 s8, s7, 0xc00
	s_mulk_i32 s7, 0xc00
	s_add_u32 s7, s2, s7
	s_addc_u32 s9, s3, s8
	s_lshl_b32 s8, s6, 1
	s_add_u32 s8, s7, s8
	s_addc_u32 s9, s9, 0
	global_load_ushort v115, v2, s[8:9] offset:2048
	s_or_b32 s7, s5, 16
	s_mul_hi_i32 s8, s7, 0xc00
	s_mulk_i32 s7, 0xc00
	s_add_u32 s7, s2, s7
	s_addc_u32 s9, s3, s8
	s_lshl_b32 s8, s6, 1
	s_add_u32 s8, s7, s8
	s_addc_u32 s9, s9, 0
	global_load_ushort v116, v2, s[8:9] offset:2048
	s_or_b32 s7, s5, 17
	s_mul_hi_i32 s8, s7, 0xc00
	s_mulk_i32 s7, 0xc00
	s_add_u32 s7, s2, s7
	s_addc_u32 s9, s3, s8
	s_lshl_b32 s8, s6, 1
	s_add_u32 s8, s7, s8
	s_addc_u32 s9, s9, 0
	global_load_ushort v117, v2, s[8:9] offset:2048
	s_or_b32 s7, s5, 18
	s_mul_hi_i32 s8, s7, 0xc00
	s_mulk_i32 s7, 0xc00
	s_add_u32 s7, s2, s7
	s_addc_u32 s9, s3, s8
	s_lshl_b32 s8, s6, 1
	s_add_u32 s8, s7, s8
	s_addc_u32 s9, s9, 0
	global_load_ushort v118, v2, s[8:9] offset:2048
	s_or_b32 s7, s5, 19
	s_mul_hi_i32 s8, s7, 0xc00
	s_mulk_i32 s7, 0xc00
	s_add_u32 s7, s2, s7
	s_addc_u32 s9, s3, s8
	s_lshl_b32 s8, s6, 1
	s_add_u32 s8, s7, s8
	s_addc_u32 s9, s9, 0
	global_load_ushort v119, v2, s[8:9] offset:2048
	s_or_b32 s7, s5, 20
	s_mul_hi_i32 s8, s7, 0xc00
	s_mulk_i32 s7, 0xc00
	s_add_u32 s7, s2, s7
	s_addc_u32 s9, s3, s8
	s_lshl_b32 s8, s6, 1
	s_add_u32 s8, s7, s8
	s_addc_u32 s9, s9, 0
	global_load_ushort v120, v2, s[8:9] offset:2048
	s_or_b32 s7, s5, 21
	s_mul_hi_i32 s8, s7, 0xc00
	s_mulk_i32 s7, 0xc00
	s_add_u32 s7, s2, s7
	s_addc_u32 s9, s3, s8
	s_lshl_b32 s8, s6, 1
	s_add_u32 s8, s7, s8
	s_addc_u32 s9, s9, 0
	global_load_ushort v121, v2, s[8:9] offset:2048
	s_or_b32 s7, s5, 22
	s_mul_hi_i32 s8, s7, 0xc00
	s_mulk_i32 s7, 0xc00
	s_add_u32 s7, s2, s7
	s_addc_u32 s9, s3, s8
	s_lshl_b32 s8, s6, 1
	s_add_u32 s8, s7, s8
	s_addc_u32 s9, s9, 0
; DI float bf2f(unsigned h) { return __uint_as_float(h << 16); }
; DI void gdnprep_item(const Params& p, int item, unsigned char* ldsb) {
;     ...
;   {
;     const int c = tid & 127; const bool isw = tid >= 128;
;     float x[64];
; #pragma unroll
;     for (int i = 0; i < 64; ++i) {
;       if (isw) x[i] = bf2f(sK[i * 136 + c]) * sbeta[i] * __expf(sgc[i]);
;       else x[i] = bf2f(CQ[(size_t)(t0 + i) * 1536 + 1024 + h * 128 + c]) * sbeta[i];
;     }
	global_load_ushort v122, v2, s[8:9] offset:2048
	s_or_b32 s7, s5, 23
	s_mul_hi_i32 s8, s7, 0xc00
	s_mulk_i32 s7, 0xc00
	s_add_u32 s7, s2, s7
	s_addc_u32 s9, s3, s8
	s_lshl_b32 s8, s6, 1
	s_add_u32 s8, s7, s8
	s_addc_u32 s9, s9, 0
	global_load_ushort v123, v2, s[8:9] offset:2048
	s_or_b32 s7, s5, 24
	s_mul_hi_i32 s8, s7, 0xc00
	s_mulk_i32 s7, 0xc00
	s_add_u32 s7, s2, s7
	s_addc_u32 s9, s3, s8
	s_lshl_b32 s8, s6, 1
	s_add_u32 s8, s7, s8
	s_addc_u32 s9, s9, 0
	global_load_ushort v124, v2, s[8:9] offset:2048
	s_or_b32 s7, s5, 25
	s_mul_hi_i32 s8, s7, 0xc00
	s_mulk_i32 s7, 0xc00
	s_add_u32 s7, s2, s7
	s_addc_u32 s9, s3, s8
	s_lshl_b32 s8, s6, 1
	s_add_u32 s8, s7, s8
	s_addc_u32 s9, s9, 0
	global_load_ushort v125, v2, s[8:9] offset:2048
	s_or_b32 s7, s5, 26
	s_mul_hi_i32 s8, s7, 0xc00
	s_mulk_i32 s7, 0xc00
	s_add_u32 s7, s2, s7
	s_addc_u32 s9, s3, s8
	s_lshl_b32 s8, s6, 1
	s_add_u32 s8, s7, s8
	s_addc_u32 s9, s9, 0
	global_load_ushort v126, v2, s[8:9] offset:2048
	s_or_b32 s7, s5, 27
	s_mul_hi_i32 s8, s7, 0xc00
	s_mulk_i32 s7, 0xc00
	s_add_u32 s7, s2, s7
	s_addc_u32 s9, s3, s8
	s_lshl_b32 s8, s6, 1
	s_add_u32 s8, s7, s8
	s_addc_u32 s9, s9, 0
	global_load_ushort v127, v2, s[8:9] offset:2048
	s_or_b32 s7, s5, 28
	s_mul_hi_i32 s8, s7, 0xc00
	s_mulk_i32 s7, 0xc00
	s_add_u32 s7, s2, s7
	s_addc_u32 s9, s3, s8
	s_lshl_b32 s8, s6, 1
	s_add_u32 s8, s7, s8
	s_addc_u32 s9, s9, 0
	global_load_ushort v128, v2, s[8:9] offset:2048
	s_or_b32 s7, s5, 29
	s_mul_hi_i32 s8, s7, 0xc00
	s_mulk_i32 s7, 0xc00
	s_add_u32 s7, s2, s7
	s_addc_u32 s9, s3, s8
	s_lshl_b32 s8, s6, 1
	s_add_u32 s8, s7, s8
	s_addc_u32 s9, s9, 0
	global_load_ushort v129, v2, s[8:9] offset:2048
	s_or_b32 s7, s5, 30
	s_mul_hi_i32 s8, s7, 0xc00
	s_mulk_i32 s7, 0xc00
	s_add_u32 s7, s2, s7
	s_addc_u32 s9, s3, s8
	s_lshl_b32 s8, s6, 1
	s_add_u32 s8, s7, s8
	s_addc_u32 s9, s9, 0
	global_load_ushort v130, v2, s[8:9] offset:2048
	s_or_b32 s7, s5, 31
	s_mul_hi_i32 s8, s7, 0xc00
	s_mulk_i32 s7, 0xc00
	s_add_u32 s7, s2, s7
	s_addc_u32 s9, s3, s8
	s_lshl_b32 s8, s6, 1
	s_add_u32 s8, s7, s8
	s_addc_u32 s9, s9, 0
	global_load_ushort v131, v2, s[8:9] offset:2048
	ds_read_b32 v132, v1 offset:51456
	ds_read_b32 v133, v1 offset:51460
	ds_read_b32 v134, v1 offset:51464
	ds_read_b32 v135, v1 offset:51468
	ds_read_b32 v136, v1 offset:51472
	ds_read_b32 v137, v1 offset:51476
	ds_read_b32 v138, v1 offset:51480
	ds_read_b32 v139, v1 offset:51484
	s_waitcnt lgkmcnt(0)
	ds_read_b32 v140, v1 offset:51488
	ds_read_b32 v141, v1 offset:51492
	ds_read_b32 v142, v1 offset:51496
	ds_read_b32 v143, v1 offset:51500
	ds_read_b32 v144, v1 offset:51504
	ds_read_b32 v145, v1 offset:51508
	ds_read_b32 v146, v1 offset:51512
	ds_read_b32 v147, v1 offset:51516
	s_waitcnt lgkmcnt(0)
	ds_read_b32 v148, v1 offset:51520
	ds_read_b32 v149, v1 offset:51524
	ds_read_b32 v150, v1 offset:51528
	ds_read_b32 v151, v1 offset:51532
	ds_read_b32 v152, v1 offset:51536
	ds_read_b32 v153, v1 offset:51540
	ds_read_b32 v154, v1 offset:51544
	ds_read_b32 v155, v1 offset:51548
	s_waitcnt lgkmcnt(0)
	ds_read_b32 v156, v1 offset:51552
	ds_read_b32 v157, v1 offset:51556
	ds_read_b32 v158, v1 offset:51560
	ds_read_b32 v159, v1 offset:51564
	ds_read_b32 v160, v1 offset:51568
	ds_read_b32 v161, v1 offset:51572
	ds_read_b32 v162, v1 offset:51576
	ds_read_b32 v163, v1 offset:51580
	s_waitcnt lgkmcnt(0)
	s_waitcnt vmcnt(0)
	v_lshlrev_b32_e32 v100, 16, v100
	v_mul_f32_e32 v0, v132, v100
	v_lshlrev_b32_e32 v101, 16, v101
	v_mul_f32_e32 v4, v133, v101
	v_lshlrev_b32_e32 v102, 16, v102
	v_mul_f32_e32 v5, v134, v102
	v_lshlrev_b32_e32 v103, 16, v103
	v_mul_f32_e32 v6, v135, v103
	v_lshlrev_b32_e32 v104, 16, v104
	v_mul_f32_e32 v7, v136, v104
	v_lshlrev_b32_e32 v105, 16, v105
	v_mul_f32_e32 v8, v137, v105
	v_lshlrev_b32_e32 v106, 16, v106
	v_mul_f32_e32 v9, v138, v106
	v_lshlrev_b32_e32 v107, 16, v107
	v_mul_f32_e32 v10, v139, v107
	v_lshlrev_b32_e32 v108, 16, v108
	v_mul_f32_e32 v11, v140, v108
	v_lshlrev_b32_e32 v109, 16, v109
	v_mul_f32_e32 v12, v141, v109
	v_lshlrev_b32_e32 v110, 16, v110
	v_mul_f32_e32 v13, v142, v110
	v_lshlrev_b32_e32 v111, 16, v111
	v_mul_f32_e32 v14, v143, v111
	v_lshlrev_b32_e32 v112, 16, v112
	v_mul_f32_e32 v15, v144, v112
	v_lshlrev_b32_e32 v113, 16, v113
	v_mul_f32_e32 v16, v145, v113
	v_lshlrev_b32_e32 v114, 16, v114
	v_mul_f32_e32 v18, v146, v114
	v_lshlrev_b32_e32 v115, 16, v115
	v_mul_f32_e32 v19, v147, v115
	v_lshlrev_b32_e32 v116, 16, v116
	v_mul_f32_e32 v20, v148, v116
	v_lshlrev_b32_e32 v117, 16, v117
	v_mul_f32_e32 v22, v149, v117
	v_lshlrev_b32_e32 v118, 16, v118
	v_mul_f32_e32 v23, v150, v118
	v_lshlrev_b32_e32 v119, 16, v119
	v_mul_f32_e32 v24, v151, v119
	v_lshlrev_b32_e32 v120, 16, v120
	v_mul_f32_e32 v25, v152, v120
	v_lshlrev_b32_e32 v121, 16, v121
	v_mul_f32_e32 v27, v153, v121
	v_lshlrev_b32_e32 v122, 16, v122
	v_mul_f32_e32 v28, v154, v122
	v_lshlrev_b32_e32 v123, 16, v123
	v_mul_f32_e32 v30, v155, v123
	v_lshlrev_b32_e32 v124, 16, v124
	v_mul_f32_e32 v31, v156, v124
	v_lshlrev_b32_e32 v125, 16, v125
	v_mul_f32_e32 v33, v157, v125
	v_lshlrev_b32_e32 v126, 16, v126
	v_mul_f32_e32 v34, v158, v126
	v_lshlrev_b32_e32 v127, 16, v127
	v_mul_f32_e32 v36, v159, v127
	v_lshlrev_b32_e32 v128, 16, v128
	v_mul_f32_e32 v37, v160, v128
	v_lshlrev_b32_e32 v129, 16, v129
	v_mul_f32_e32 v39, v161, v129
	v_lshlrev_b32_e32 v130, 16, v130
	v_mul_f32_e32 v40, v162, v130
	v_lshlrev_b32_e32 v131, 16, v131
	v_mul_f32_e32 v44, v163, v131
	s_or_b32 s7, s5, 32
	s_mul_hi_i32 s8, s7, 0xc00
	s_mulk_i32 s7, 0xc00
	s_add_u32 s7, s2, s7
	s_addc_u32 s9, s3, s8
	s_lshl_b32 s8, s6, 1
	s_add_u32 s8, s7, s8
	s_addc_u32 s9, s9, 0
	global_load_ushort v100, v2, s[8:9] offset:2048
; DI float bf2f(unsigned h) { return __uint_as_float(h << 16); }
; DI void gdnprep_item(const Params& p, int item, unsigned char* ldsb) {
;     ...
;   {
;     const int c = tid & 127; const bool isw = tid >= 128;
;     float x[64];
; #pragma unroll
;     for (int i = 0; i < 64; ++i) {
;       if (isw) x[i] = bf2f(sK[i * 136 + c]) * sbeta[i] * __expf(sgc[i]);
;       else x[i] = bf2f(CQ[(size_t)(t0 + i) * 1536 + 1024 + h * 128 + c]) * sbeta[i];
;     }
	s_or_b32 s7, s5, 33
	s_mul_hi_i32 s8, s7, 0xc00
	s_mulk_i32 s7, 0xc00
	s_add_u32 s7, s2, s7
	s_addc_u32 s9, s3, s8
	s_lshl_b32 s8, s6, 1
	s_add_u32 s8, s7, s8
	s_addc_u32 s9, s9, 0
	global_load_ushort v101, v2, s[8:9] offset:2048
	s_or_b32 s7, s5, 34
	s_mul_hi_i32 s8, s7, 0xc00
	s_mulk_i32 s7, 0xc00
	s_add_u32 s7, s2, s7
	s_addc_u32 s9, s3, s8
	s_lshl_b32 s8, s6, 1
	s_add_u32 s8, s7, s8
	s_addc_u32 s9, s9, 0
	global_load_ushort v102, v2, s[8:9] offset:2048
	s_or_b32 s7, s5, 35
	s_mul_hi_i32 s8, s7, 0xc00
	s_mulk_i32 s7, 0xc00
	s_add_u32 s7, s2, s7
	s_addc_u32 s9, s3, s8
	s_lshl_b32 s8, s6, 1
	s_add_u32 s8, s7, s8
	s_addc_u32 s9, s9, 0
	global_load_ushort v103, v2, s[8:9] offset:2048
	s_or_b32 s7, s5, 36
	s_mul_hi_i32 s8, s7, 0xc00
	s_mulk_i32 s7, 0xc00
	s_add_u32 s7, s2, s7
	s_addc_u32 s9, s3, s8
	s_lshl_b32 s8, s6, 1
	s_add_u32 s8, s7, s8
	s_addc_u32 s9, s9, 0
	global_load_ushort v104, v2, s[8:9] offset:2048
	s_or_b32 s7, s5, 37
	s_mul_hi_i32 s8, s7, 0xc00
	s_mulk_i32 s7, 0xc00
	s_add_u32 s7, s2, s7
	s_addc_u32 s9, s3, s8
	s_lshl_b32 s8, s6, 1
	s_add_u32 s8, s7, s8
	s_addc_u32 s9, s9, 0
	global_load_ushort v105, v2, s[8:9] offset:2048
	s_or_b32 s7, s5, 38
	s_mul_hi_i32 s8, s7, 0xc00
	s_mulk_i32 s7, 0xc00
	s_add_u32 s7, s2, s7
	s_addc_u32 s9, s3, s8
	s_lshl_b32 s8, s6, 1
	s_add_u32 s8, s7, s8
	s_addc_u32 s9, s9, 0
	global_load_ushort v106, v2, s[8:9] offset:2048
	s_or_b32 s7, s5, 39
	s_mul_hi_i32 s8, s7, 0xc00
	s_mulk_i32 s7, 0xc00
	s_add_u32 s7, s2, s7
	s_addc_u32 s9, s3, s8
	s_lshl_b32 s8, s6, 1
	s_add_u32 s8, s7, s8
	s_addc_u32 s9, s9, 0
	global_load_ushort v107, v2, s[8:9] offset:2048
	s_or_b32 s7, s5, 40
	s_mul_hi_i32 s8, s7, 0xc00
	s_mulk_i32 s7, 0xc00
	s_add_u32 s7, s2, s7
	s_addc_u32 s9, s3, s8
	s_lshl_b32 s8, s6, 1
	s_add_u32 s8, s7, s8
	s_addc_u32 s9, s9, 0
	global_load_ushort v108, v2, s[8:9] offset:2048
	s_or_b32 s7, s5, 41
	s_mul_hi_i32 s8, s7, 0xc00
	s_mulk_i32 s7, 0xc00
	s_add_u32 s7, s2, s7
	s_addc_u32 s9, s3, s8
	s_lshl_b32 s8, s6, 1
	s_add_u32 s8, s7, s8
	s_addc_u32 s9, s9, 0
	global_load_ushort v109, v2, s[8:9] offset:2048
	s_or_b32 s7, s5, 42
	s_mul_hi_i32 s8, s7, 0xc00
	s_mulk_i32 s7, 0xc00
	s_add_u32 s7, s2, s7
	s_addc_u32 s9, s3, s8
	s_lshl_b32 s8, s6, 1
	s_add_u32 s8, s7, s8
	s_addc_u32 s9, s9, 0
	global_load_ushort v110, v2, s[8:9] offset:2048
	s_or_b32 s7, s5, 43
	s_mul_hi_i32 s8, s7, 0xc00
	s_mulk_i32 s7, 0xc00
	s_add_u32 s7, s2, s7
	s_addc_u32 s9, s3, s8
	s_lshl_b32 s8, s6, 1
	s_add_u32 s8, s7, s8
	s_addc_u32 s9, s9, 0
	global_load_ushort v111, v2, s[8:9] offset:2048
	s_or_b32 s7, s5, 44
	s_mul_hi_i32 s8, s7, 0xc00
	s_mulk_i32 s7, 0xc00
	s_add_u32 s7, s2, s7
	s_addc_u32 s9, s3, s8
	s_lshl_b32 s8, s6, 1
	s_add_u32 s8, s7, s8
	s_addc_u32 s9, s9, 0
	global_load_ushort v112, v2, s[8:9] offset:2048
	s_or_b32 s7, s5, 45
	s_mul_hi_i32 s8, s7, 0xc00
	s_mulk_i32 s7, 0xc00
	s_add_u32 s7, s2, s7
	s_addc_u32 s9, s3, s8
	s_lshl_b32 s8, s6, 1
	s_add_u32 s8, s7, s8
	s_addc_u32 s9, s9, 0
	global_load_ushort v113, v2, s[8:9] offset:2048
	s_or_b32 s7, s5, 46
	s_mul_hi_i32 s8, s7, 0xc00
	s_mulk_i32 s7, 0xc00
	s_add_u32 s7, s2, s7
	s_addc_u32 s9, s3, s8
	s_lshl_b32 s8, s6, 1
	s_add_u32 s8, s7, s8
	s_addc_u32 s9, s9, 0
	global_load_ushort v114, v2, s[8:9] offset:2048
	s_or_b32 s5, s5, 47
	s_mul_hi_i32 s7, s5, 0xc00
	s_mulk_i32 s5, 0xc00
	s_add_u32 s5, s2, s5
	s_addc_u32 s7, s3, s7
	s_lshl_b32 s8, s6, 1
	s_add_u32 s8, s5, s8
	s_addc_u32 s9, s7, 0
	global_load_ushort v115, v2, s[8:9] offset:2048
	s_or_b32 s5, s4, 48
	s_mul_hi_i32 s7, s5, 0xc00
	s_mulk_i32 s5, 0xc00
	s_add_u32 s5, s2, s5
	s_addc_u32 s7, s3, s7
	s_lshl_b32 s8, s6, 1
	s_add_u32 s8, s5, s8
	s_addc_u32 s9, s7, 0
	global_load_ushort v116, v2, s[8:9] offset:2048
	s_or_b32 s5, s4, 49
	s_mul_hi_i32 s7, s5, 0xc00
	s_mulk_i32 s5, 0xc00
	s_add_u32 s5, s2, s5
	s_addc_u32 s7, s3, s7
	s_lshl_b32 s8, s6, 1
	s_add_u32 s8, s5, s8
	s_addc_u32 s9, s7, 0
	global_load_ushort v117, v2, s[8:9] offset:2048
	s_or_b32 s5, s4, 50
	s_mul_hi_i32 s7, s5, 0xc00
	s_mulk_i32 s5, 0xc00
	s_add_u32 s5, s2, s5
	s_addc_u32 s7, s3, s7
	s_lshl_b32 s8, s6, 1
	s_add_u32 s8, s5, s8
	s_addc_u32 s9, s7, 0
	global_load_ushort v118, v2, s[8:9] offset:2048
	s_or_b32 s5, s4, 51
	s_mul_hi_i32 s7, s5, 0xc00
	s_mulk_i32 s5, 0xc00
	s_add_u32 s5, s2, s5
	s_addc_u32 s7, s3, s7
	s_lshl_b32 s8, s6, 1
	s_add_u32 s8, s5, s8
	s_addc_u32 s9, s7, 0
	global_load_ushort v119, v2, s[8:9] offset:2048
	s_or_b32 s5, s4, 52
	s_mul_hi_i32 s7, s5, 0xc00
	s_mulk_i32 s5, 0xc00
	s_add_u32 s5, s2, s5
	s_addc_u32 s7, s3, s7
	s_lshl_b32 s8, s6, 1
	s_add_u32 s8, s5, s8
	s_addc_u32 s9, s7, 0
	global_load_ushort v120, v2, s[8:9] offset:2048
	s_or_b32 s5, s4, 53
	s_mul_hi_i32 s7, s5, 0xc00
	s_mulk_i32 s5, 0xc00
	s_add_u32 s5, s2, s5
	s_addc_u32 s7, s3, s7
	s_lshl_b32 s8, s6, 1
	s_add_u32 s8, s5, s8
	s_addc_u32 s9, s7, 0
	global_load_ushort v121, v2, s[8:9] offset:2048
	s_or_b32 s5, s4, 54
	s_mul_hi_i32 s7, s5, 0xc00
	s_mulk_i32 s5, 0xc00
	s_add_u32 s5, s2, s5
	s_addc_u32 s7, s3, s7
	s_lshl_b32 s8, s6, 1
	s_add_u32 s8, s5, s8
	s_addc_u32 s9, s7, 0
	global_load_ushort v122, v2, s[8:9] offset:2048
	s_or_b32 s5, s4, 55
	s_mul_hi_i32 s7, s5, 0xc00
	s_mulk_i32 s5, 0xc00
	s_add_u32 s5, s2, s5
	s_addc_u32 s7, s3, s7
	s_lshl_b32 s8, s6, 1
	s_add_u32 s8, s5, s8
	s_addc_u32 s9, s7, 0
	global_load_ushort v123, v2, s[8:9] offset:2048
	s_or_b32 s5, s4, 56
	s_mul_hi_i32 s7, s5, 0xc00
	s_mulk_i32 s5, 0xc00
	s_add_u32 s5, s2, s5
	s_addc_u32 s7, s3, s7
	s_lshl_b32 s8, s6, 1
	s_add_u32 s8, s5, s8
	s_addc_u32 s9, s7, 0
	global_load_ushort v124, v2, s[8:9] offset:2048
	s_or_b32 s5, s4, 57
	s_mul_hi_i32 s7, s5, 0xc00
	s_mulk_i32 s5, 0xc00
	s_add_u32 s5, s2, s5
; DI float bf2f(unsigned h) { return __uint_as_float(h << 16); }
; DI void gdnprep_item(const Params& p, int item, unsigned char* ldsb) {
;     ...
;   {
;     const int c = tid & 127; const bool isw = tid >= 128;
;     float x[64];
; #pragma unroll
;     for (int i = 0; i < 64; ++i) {
;       if (isw) x[i] = bf2f(sK[i * 136 + c]) * sbeta[i] * __expf(sgc[i]);
;       else x[i] = bf2f(CQ[(size_t)(t0 + i) * 1536 + 1024 + h * 128 + c]) * sbeta[i];
;     }
	s_addc_u32 s7, s3, s7
	s_lshl_b32 s8, s6, 1
	s_add_u32 s8, s5, s8
	s_addc_u32 s9, s7, 0
	global_load_ushort v125, v2, s[8:9] offset:2048
	s_or_b32 s5, s4, 58
	s_mul_hi_i32 s7, s5, 0xc00
	s_mulk_i32 s5, 0xc00
	s_add_u32 s5, s2, s5
	s_addc_u32 s7, s3, s7
	s_lshl_b32 s8, s6, 1
	s_add_u32 s8, s5, s8
	s_addc_u32 s9, s7, 0
	global_load_ushort v126, v2, s[8:9] offset:2048
	s_or_b32 s5, s4, 59
	s_mul_hi_i32 s7, s5, 0xc00
	s_mulk_i32 s5, 0xc00
	s_add_u32 s5, s2, s5
	s_addc_u32 s7, s3, s7
	s_lshl_b32 s8, s6, 1
	s_add_u32 s8, s5, s8
	s_addc_u32 s9, s7, 0
	global_load_ushort v127, v2, s[8:9] offset:2048
	s_or_b32 s5, s4, 60
	s_mul_hi_i32 s7, s5, 0xc00
	s_mulk_i32 s5, 0xc00
	s_add_u32 s5, s2, s5
	s_addc_u32 s7, s3, s7
	s_lshl_b32 s8, s6, 1
	s_add_u32 s8, s5, s8
	s_addc_u32 s9, s7, 0
	global_load_ushort v128, v2, s[8:9] offset:2048
	s_or_b32 s5, s4, 61
	s_mul_hi_i32 s7, s5, 0xc00
	s_mulk_i32 s5, 0xc00
	s_add_u32 s5, s2, s5
	s_addc_u32 s7, s3, s7
	s_lshl_b32 s8, s6, 1
	s_add_u32 s8, s5, s8
	s_addc_u32 s9, s7, 0
	global_load_ushort v129, v2, s[8:9] offset:2048
	s_or_b32 s5, s4, 62
	s_mul_hi_i32 s7, s5, 0xc00
	s_mulk_i32 s5, 0xc00
	s_add_u32 s5, s2, s5
	s_addc_u32 s7, s3, s7
	s_lshl_b32 s8, s6, 1
	s_add_u32 s8, s5, s8
	s_addc_u32 s9, s7, 0
	global_load_ushort v130, v2, s[8:9] offset:2048
	s_or_b32 s4, s4, 63
	s_mul_hi_i32 s5, s4, 0xc00
	s_mulk_i32 s4, 0xc00
	s_add_u32 s4, s2, s4
	s_addc_u32 s5, s3, s5
	s_lshl_b32 s6, s6, 1
	s_add_u32 s4, s4, s6
	s_addc_u32 s5, s5, 0
	global_load_ushort v131, v2, s[4:5] offset:2048
	ds_read_b32 v132, v1 offset:51584
	ds_read_b32 v133, v1 offset:51588
	ds_read_b32 v134, v1 offset:51592
	ds_read_b32 v135, v1 offset:51596
	ds_read_b32 v136, v1 offset:51600
	ds_read_b32 v137, v1 offset:51604
	ds_read_b32 v138, v1 offset:51608
	ds_read_b32 v139, v1 offset:51612
	s_waitcnt lgkmcnt(0)
	ds_read_b32 v140, v1 offset:51616
	ds_read_b32 v141, v1 offset:51620
	ds_read_b32 v142, v1 offset:51624
	ds_read_b32 v143, v1 offset:51628
	ds_read_b32 v144, v1 offset:51632
	ds_read_b32 v145, v1 offset:51636
	ds_read_b32 v146, v1 offset:51640
	ds_read_b32 v147, v1 offset:51644
	s_waitcnt lgkmcnt(0)
	ds_read_b32 v148, v1 offset:51648
	ds_read_b32 v149, v1 offset:51652
	ds_read_b32 v150, v1 offset:51656
	ds_read_b32 v151, v1 offset:51660
	ds_read_b32 v152, v1 offset:51664
	ds_read_b32 v153, v1 offset:51668
	ds_read_b32 v154, v1 offset:51672
	ds_read_b32 v155, v1 offset:51676
	s_waitcnt lgkmcnt(0)
	ds_read_b32 v156, v1 offset:51680
	ds_read_b32 v157, v1 offset:51684
	ds_read_b32 v158, v1 offset:51688
	ds_read_b32 v159, v1 offset:51692
	ds_read_b32 v160, v1 offset:51696
	ds_read_b32 v161, v1 offset:51700
	ds_read_b32 v162, v1 offset:51704
	ds_read_b32 v163, v1 offset:51708
	s_waitcnt lgkmcnt(0)
	s_waitcnt vmcnt(0)
	v_lshlrev_b32_e32 v100, 16, v100
	v_mul_f32_e32 v46, v132, v100
	v_lshlrev_b32_e32 v101, 16, v101
	v_mul_f32_e32 v47, v133, v101
	v_lshlrev_b32_e32 v102, 16, v102
	v_mul_f32_e32 v49, v134, v102
	v_lshlrev_b32_e32 v103, 16, v103
	v_mul_f32_e32 v51, v135, v103
	v_lshlrev_b32_e32 v104, 16, v104
	v_mul_f32_e32 v58, v136, v104
	v_lshlrev_b32_e32 v105, 16, v105
	v_mul_f32_e32 v59, v137, v105
	v_lshlrev_b32_e32 v106, 16, v106
	v_mul_f32_e32 v61, v138, v106
	v_lshlrev_b32_e32 v107, 16, v107
	v_mul_f32_e32 v63, v139, v107
	v_lshlrev_b32_e32 v108, 16, v108
	v_mul_f32_e32 v65, v140, v108
	v_lshlrev_b32_e32 v109, 16, v109
	v_mul_f32_e32 v67, v141, v109
	v_lshlrev_b32_e32 v110, 16, v110
	v_mul_f32_e32 v69, v142, v110
	v_lshlrev_b32_e32 v111, 16, v111
	v_mul_f32_e32 v71, v143, v111
	v_lshlrev_b32_e32 v112, 16, v112
	v_mul_f32_e32 v73, v144, v112
	v_lshlrev_b32_e32 v113, 16, v113
	v_mul_f32_e32 v72, v145, v113
	v_lshlrev_b32_e32 v114, 16, v114
	v_mul_f32_e32 v70, v146, v114
	v_lshlrev_b32_e32 v115, 16, v115
	v_mul_f32_e32 v68, v147, v115
	v_lshlrev_b32_e32 v116, 16, v116
	v_mul_f32_e32 v66, v148, v116
	v_lshlrev_b32_e32 v117, 16, v117
	v_mul_f32_e32 v64, v149, v117
	v_lshlrev_b32_e32 v118, 16, v118
	v_mul_f32_e32 v62, v150, v118
	v_lshlrev_b32_e32 v119, 16, v119
	v_mul_f32_e32 v60, v151, v119
	v_lshlrev_b32_e32 v120, 16, v120
	v_mul_f32_e32 v57, v152, v120
	v_lshlrev_b32_e32 v121, 16, v121
	v_mul_f32_e32 v50, v153, v121
	v_lshlrev_b32_e32 v122, 16, v122
	v_mul_f32_e32 v48, v154, v122
	v_lshlrev_b32_e32 v123, 16, v123
	v_mul_f32_e32 v45, v155, v123
	v_lshlrev_b32_e32 v124, 16, v124
	v_mul_f32_e32 v41, v156, v124
	v_lshlrev_b32_e32 v125, 16, v125
	v_mul_f32_e32 v38, v157, v125
	v_lshlrev_b32_e32 v126, 16, v126
	v_mul_f32_e32 v35, v158, v126
	v_lshlrev_b32_e32 v127, 16, v127
	v_mul_f32_e32 v32, v159, v127
	v_lshlrev_b32_e32 v128, 16, v128
	v_mul_f32_e32 v29, v160, v128
	v_lshlrev_b32_e32 v129, 16, v129
	v_mul_f32_e32 v26, v161, v129
	v_lshlrev_b32_e32 v130, 16, v130
	v_mul_f32_e32 v21, v162, v130
	v_lshlrev_b32_e32 v131, 16, v131
	v_mul_f32_e32 v17, v163, v131
	s_mov_b64 exec, s[0:1]
	s_branch .Lxinit_done
; DI float bf2f(unsigned h) { return __uint_as_float(h << 16); }
; DI void gdnprep_item(const Params& p, int item, unsigned char* ldsb) {
;     ...
; #pragma unroll
;     for (int i = 0; i < 64; ++i) {
;       if (isw) x[i] = bf2f(sK[i * 136 + c]) * sbeta[i] * __expf(sgc[i]);
;       else x[i] = bf2f(CQ[(size_t)(t0 + i) * 1536 + 1024 + h * 128 + c]) * sbeta[i];
;     }
.Lxinit_lds:
	s_mov_b64 exec, s[0:1]
	ds_read2st64_b32 v[4:5], v1 offset0:200 offset1:201
	ds_read_u16 v0, v2
	s_waitcnt lgkmcnt(1)
	v_mul_f32_e32 v4, 0x3fb8aa3b, v4
	v_exp_f32_e32 v4, v4
	s_waitcnt lgkmcnt(0)
	v_lshlrev_b32_e32 v0, 16, v0
	v_mul_f32_e32 v0, v5, v0
	v_mul_f32_e32 v0, v0, v4
	v_add_u32_e64 v4, 4, 0
	ds_read2st64_b32 v[4:5], v4 offset0:200 offset1:201
	ds_read_u16 v6, v2 offset:272
	s_waitcnt lgkmcnt(1)
	v_mul_f32_e32 v4, 0x3fb8aa3b, v4
	v_exp_f32_e32 v4, v4
	s_waitcnt lgkmcnt(0)
	v_lshlrev_b32_e32 v6, 16, v6
	v_mul_f32_e32 v5, v5, v6
	v_mul_f32_e32 v4, v5, v4
	v_add_u32_e64 v5, 8, 0
	ds_read2st64_b32 v[6:7], v5 offset0:200 offset1:201
	ds_read_u16 v5, v2 offset:544
	s_waitcnt lgkmcnt(1)
	v_mul_f32_e32 v6, 0x3fb8aa3b, v6
	v_exp_f32_e32 v6, v6
	s_waitcnt lgkmcnt(0)
	v_lshlrev_b32_e32 v5, 16, v5
	v_mul_f32_e32 v5, v7, v5
	v_mul_f32_e32 v5, v5, v6
	v_add_u32_e64 v6, 12, 0
	ds_read2st64_b32 v[6:7], v6 offset0:200 offset1:201
	ds_read_u16 v8, v2 offset:816
	s_waitcnt lgkmcnt(1)
	v_mul_f32_e32 v6, 0x3fb8aa3b, v6
	v_exp_f32_e32 v6, v6
	s_waitcnt lgkmcnt(0)
	v_lshlrev_b32_e32 v8, 16, v8
	v_mul_f32_e32 v7, v7, v8
	v_mul_f32_e32 v6, v7, v6
	v_add_u32_e64 v7, 16, 0
	ds_read2st64_b32 v[8:9], v7 offset0:200 offset1:201
	ds_read_u16 v7, v2 offset:1088
	s_waitcnt lgkmcnt(1)
	v_mul_f32_e32 v8, 0x3fb8aa3b, v8
	v_exp_f32_e32 v8, v8
	s_waitcnt lgkmcnt(0)
	v_lshlrev_b32_e32 v7, 16, v7
	v_mul_f32_e32 v7, v9, v7
	v_mul_f32_e32 v7, v7, v8
	v_add_u32_e64 v8, 20, 0
	ds_read2st64_b32 v[8:9], v8 offset0:200 offset1:201
	ds_read_u16 v10, v2 offset:1360
	s_waitcnt lgkmcnt(1)
	v_mul_f32_e32 v8, 0x3fb8aa3b, v8
	v_exp_f32_e32 v8, v8
	s_waitcnt lgkmcnt(0)
	v_lshlrev_b32_e32 v10, 16, v10
	v_mul_f32_e32 v9, v9, v10
	v_mul_f32_e32 v8, v9, v8
	v_add_u32_e64 v9, 24, 0
	ds_read2st64_b32 v[10:11], v9 offset0:200 offset1:201
	ds_read_u16 v9, v2 offset:1632
	s_waitcnt lgkmcnt(1)
	v_mul_f32_e32 v10, 0x3fb8aa3b, v10
	v_exp_f32_e32 v10, v10
	s_waitcnt lgkmcnt(0)
	v_lshlrev_b32_e32 v9, 16, v9
	v_mul_f32_e32 v9, v11, v9
	v_mul_f32_e32 v9, v9, v10
	v_add_u32_e64 v10, 28, 0
	ds_read2st64_b32 v[10:11], v10 offset0:200 offset1:201
	ds_read_u16 v12, v2 offset:1904
	s_waitcnt lgkmcnt(1)
	v_mul_f32_e32 v10, 0x3fb8aa3b, v10
	v_exp_f32_e32 v10, v10
	s_waitcnt lgkmcnt(0)
	v_lshlrev_b32_e32 v12, 16, v12
	v_mul_f32_e32 v11, v11, v12
	v_mul_f32_e32 v10, v11, v10
	v_add_u32_e64 v11, 32, 0
	ds_read2st64_b32 v[12:13], v11 offset0:200 offset1:201
	ds_read_u16 v11, v2 offset:2176
	s_waitcnt lgkmcnt(1)
	v_mul_f32_e32 v12, 0x3fb8aa3b, v12
	v_exp_f32_e32 v12, v12
	s_waitcnt lgkmcnt(0)
	v_lshlrev_b32_e32 v11, 16, v11
	v_mul_f32_e32 v11, v13, v11
	v_mul_f32_e32 v11, v11, v12
	v_add_u32_e64 v12, 36, 0
	ds_read2st64_b32 v[12:13], v12 offset0:200 offset1:201
	ds_read_u16 v14, v2 offset:2448
	s_waitcnt lgkmcnt(1)
	v_mul_f32_e32 v12, 0x3fb8aa3b, v12
	v_exp_f32_e32 v12, v12
	s_waitcnt lgkmcnt(0)
	v_lshlrev_b32_e32 v14, 16, v14
	v_mul_f32_e32 v13, v13, v14
	v_mul_f32_e32 v12, v13, v12
	v_add_u32_e64 v13, 40, 0
	ds_read2st64_b32 v[14:15], v13 offset0:200 offset1:201
	ds_read_u16 v13, v2 offset:2720
	s_waitcnt lgkmcnt(1)
	v_mul_f32_e32 v14, 0x3fb8aa3b, v14
	v_exp_f32_e32 v14, v14
	s_waitcnt lgkmcnt(0)
	v_lshlrev_b32_e32 v13, 16, v13
	v_mul_f32_e32 v13, v15, v13
	v_mul_f32_e32 v13, v13, v14
	v_add_u32_e64 v14, 44, 0
	ds_read2st64_b32 v[14:15], v14 offset0:200 offset1:201
	ds_read_u16 v16, v2 offset:2992
	s_waitcnt lgkmcnt(1)
	v_mul_f32_e32 v14, 0x3fb8aa3b, v14
	v_exp_f32_e32 v14, v14
	s_waitcnt lgkmcnt(0)
	v_lshlrev_b32_e32 v16, 16, v16
	v_mul_f32_e32 v15, v15, v16
	v_mul_f32_e32 v14, v15, v14
	v_add_u32_e64 v15, 48, 0
	ds_read2st64_b32 v[16:17], v15 offset0:200 offset1:201
	ds_read_u16 v15, v2 offset:3264
	s_waitcnt lgkmcnt(1)
	v_mul_f32_e32 v16, 0x3fb8aa3b, v16
	v_exp_f32_e32 v16, v16
	s_waitcnt lgkmcnt(0)
	v_lshlrev_b32_e32 v15, 16, v15
	v_mul_f32_e32 v15, v17, v15
	v_mul_f32_e32 v15, v15, v16
	v_add_u32_e64 v16, 52, 0
	ds_read2st64_b32 v[16:17], v16 offset0:200 offset1:201
	ds_read_u16 v18, v2 offset:3536
	s_waitcnt lgkmcnt(1)
	v_mul_f32_e32 v16, 0x3fb8aa3b, v16
	v_exp_f32_e32 v16, v16
	s_waitcnt lgkmcnt(0)
	v_lshlrev_b32_e32 v18, 16, v18
	v_mul_f32_e32 v17, v17, v18
	v_mul_f32_e32 v16, v17, v16
	v_add_u32_e64 v17, 56, 0
	ds_read2st64_b32 v[18:19], v17 offset0:200 offset1:201
	ds_read_u16 v17, v2 offset:3808
	s_waitcnt lgkmcnt(1)
	v_mul_f32_e32 v18, 0x3fb8aa3b, v18
	v_exp_f32_e32 v18, v18
	s_waitcnt lgkmcnt(0)
	v_lshlrev_b32_e32 v17, 16, v17
	v_mul_f32_e32 v17, v19, v17
	v_mul_f32_e32 v18, v17, v18
	v_add_u32_e64 v17, 60, 0
	ds_read2st64_b32 v[20:21], v17 offset0:200 offset1:201
	ds_read_u16 v17, v2 offset:4080
	s_waitcnt lgkmcnt(1)
	v_mul_f32_e32 v19, 0x3fb8aa3b, v20
	v_exp_f32_e32 v19, v19
	s_waitcnt lgkmcnt(0)
	v_lshlrev_b32_e32 v17, 16, v17
	v_mul_f32_e32 v17, v21, v17
	v_mul_f32_e32 v19, v17, v19
	v_add_u32_e64 v17, 64, 0
	ds_read2st64_b32 v[20:21], v17 offset0:200 offset1:201
	ds_read_u16 v17, v2 offset:4352
	s_waitcnt lgkmcnt(1)
	v_mul_f32_e32 v20, 0x3fb8aa3b, v20
	v_exp_f32_e32 v20, v20
	s_waitcnt lgkmcnt(0)
	v_lshlrev_b32_e32 v17, 16, v17
	v_mul_f32_e32 v17, v21, v17
	v_mul_f32_e32 v20, v17, v20
	s_movk_i32 s7, 0x44
	v_add_u32_e64 v17, s7, 0
	ds_read2st64_b32 v[22:23], v17 offset0:200 offset1:201
	ds_read_u16 v17, v2 offset:4624
	s_waitcnt lgkmcnt(1)
	v_mul_f32_e32 v21, 0x3fb8aa3b, v22
	v_exp_f32_e32 v21, v21
	s_waitcnt lgkmcnt(0)
	v_lshlrev_b32_e32 v17, 16, v17
	v_mul_f32_e32 v17, v23, v17
	v_mul_f32_e32 v22, v17, v21
	s_movk_i32 s7, 0x48
	v_add_u32_e64 v17, s7, 0
	ds_read2st64_b32 v[24:25], v17 offset0:200 offset1:201
	ds_read_u16 v17, v2 offset:4896
	s_waitcnt lgkmcnt(1)
; DI float bf2f(unsigned h) { return __uint_as_float(h << 16); }
; DI void gdnprep_item(const Params& p, int item, unsigned char* ldsb) {
;     ...
; #pragma unroll
;     for (int i = 0; i < 64; ++i) {
;       if (isw) x[i] = bf2f(sK[i * 136 + c]) * sbeta[i] * __expf(sgc[i]);
;       else x[i] = bf2f(CQ[(size_t)(t0 + i) * 1536 + 1024 + h * 128 + c]) * sbeta[i];
;     }
	v_mul_f32_e32 v21, 0x3fb8aa3b, v24
	v_exp_f32_e32 v21, v21
	s_waitcnt lgkmcnt(0)
	v_lshlrev_b32_e32 v17, 16, v17
	v_mul_f32_e32 v17, v25, v17
	v_mul_f32_e32 v23, v17, v21
	s_movk_i32 s7, 0x4c
	v_add_u32_e64 v17, s7, 0
	ds_read2st64_b32 v[24:25], v17 offset0:200 offset1:201
	ds_read_u16 v17, v2 offset:5168
	s_waitcnt lgkmcnt(1)
	v_mul_f32_e32 v21, 0x3fb8aa3b, v24
	v_exp_f32_e32 v21, v21
	s_waitcnt lgkmcnt(0)
	v_lshlrev_b32_e32 v17, 16, v17
	v_mul_f32_e32 v17, v25, v17
	v_mul_f32_e32 v24, v17, v21
	s_movk_i32 s7, 0x50
	v_add_u32_e64 v17, s7, 0
	ds_read2st64_b32 v[26:27], v17 offset0:200 offset1:201
	ds_read_u16 v17, v2 offset:5440
	s_waitcnt lgkmcnt(1)
	v_mul_f32_e32 v21, 0x3fb8aa3b, v26
	v_exp_f32_e32 v21, v21
	s_waitcnt lgkmcnt(0)
	v_lshlrev_b32_e32 v17, 16, v17
	v_mul_f32_e32 v17, v27, v17
	v_mul_f32_e32 v25, v17, v21
	s_movk_i32 s7, 0x54
	v_add_u32_e64 v17, s7, 0
	ds_read2st64_b32 v[26:27], v17 offset0:200 offset1:201
	ds_read_u16 v17, v2 offset:5712
	s_waitcnt lgkmcnt(1)
	v_mul_f32_e32 v21, 0x3fb8aa3b, v26
	v_exp_f32_e32 v21, v21
	s_waitcnt lgkmcnt(0)
	v_lshlrev_b32_e32 v17, 16, v17
	v_mul_f32_e32 v17, v27, v17
	v_mul_f32_e32 v27, v17, v21
	s_movk_i32 s7, 0x58
	v_add_u32_e64 v17, s7, 0
	ds_read2st64_b32 v[28:29], v17 offset0:200 offset1:201
	ds_read_u16 v17, v2 offset:5984
	s_waitcnt lgkmcnt(1)
	v_mul_f32_e32 v21, 0x3fb8aa3b, v28
	v_exp_f32_e32 v21, v21
	s_waitcnt lgkmcnt(0)
	v_lshlrev_b32_e32 v17, 16, v17
	v_mul_f32_e32 v17, v29, v17
	v_mul_f32_e32 v28, v17, v21
	s_movk_i32 s7, 0x5c
	v_add_u32_e64 v17, s7, 0
	ds_read2st64_b32 v[30:31], v17 offset0:200 offset1:201
	ds_read_u16 v17, v2 offset:6256
	s_waitcnt lgkmcnt(1)
	v_mul_f32_e32 v21, 0x3fb8aa3b, v30
	v_exp_f32_e32 v21, v21
	s_waitcnt lgkmcnt(0)
	v_lshlrev_b32_e32 v17, 16, v17
	v_mul_f32_e32 v17, v31, v17
	v_mul_f32_e32 v30, v17, v21
	s_movk_i32 s7, 0x60
	v_add_u32_e64 v17, s7, 0
	ds_read2st64_b32 v[32:33], v17 offset0:200 offset1:201
	ds_read_u16 v17, v2 offset:6528
	s_waitcnt lgkmcnt(1)
	v_mul_f32_e32 v21, 0x3fb8aa3b, v32
	v_exp_f32_e32 v21, v21
	s_waitcnt lgkmcnt(0)
	v_lshlrev_b32_e32 v17, 16, v17
	v_mul_f32_e32 v17, v33, v17
	v_mul_f32_e32 v31, v17, v21
	s_movk_i32 s7, 0x64
	v_add_u32_e64 v17, s7, 0
	ds_read2st64_b32 v[32:33], v17 offset0:200 offset1:201
	ds_read_u16 v17, v2 offset:6800
	s_waitcnt lgkmcnt(1)
	v_mul_f32_e32 v21, 0x3fb8aa3b, v32
	v_exp_f32_e32 v21, v21
	s_waitcnt lgkmcnt(0)
	v_lshlrev_b32_e32 v17, 16, v17
	v_mul_f32_e32 v17, v33, v17
	v_mul_f32_e32 v33, v17, v21
	s_movk_i32 s7, 0x68
	v_add_u32_e64 v17, s7, 0
	ds_read2st64_b32 v[34:35], v17 offset0:200 offset1:201
	ds_read_u16 v17, v2 offset:7072
	s_waitcnt lgkmcnt(1)
	v_mul_f32_e32 v21, 0x3fb8aa3b, v34
	v_exp_f32_e32 v21, v21
	s_waitcnt lgkmcnt(0)
	v_lshlrev_b32_e32 v17, 16, v17
	v_mul_f32_e32 v17, v35, v17
	v_mul_f32_e32 v34, v17, v21
	s_movk_i32 s7, 0x6c
	v_add_u32_e64 v17, s7, 0
	ds_read2st64_b32 v[36:37], v17 offset0:200 offset1:201
	ds_read_u16 v17, v2 offset:7344
	s_waitcnt lgkmcnt(1)
	v_mul_f32_e32 v21, 0x3fb8aa3b, v36
	v_exp_f32_e32 v21, v21
	s_waitcnt lgkmcnt(0)
	v_lshlrev_b32_e32 v17, 16, v17
	v_mul_f32_e32 v17, v37, v17
	v_mul_f32_e32 v36, v17, v21
	s_movk_i32 s7, 0x70
	v_add_u32_e64 v17, s7, 0
	ds_read2st64_b32 v[38:39], v17 offset0:200 offset1:201
	ds_read_u16 v17, v2 offset:7616
	s_waitcnt lgkmcnt(1)
	v_mul_f32_e32 v21, 0x3fb8aa3b, v38
	v_exp_f32_e32 v21, v21
	s_waitcnt lgkmcnt(0)
	v_lshlrev_b32_e32 v17, 16, v17
	v_mul_f32_e32 v17, v39, v17
	v_mul_f32_e32 v37, v17, v21
	s_movk_i32 s7, 0x74
	v_add_u32_e64 v17, s7, 0
	ds_read2st64_b32 v[38:39], v17 offset0:200 offset1:201
	ds_read_u16 v17, v2 offset:7888
	s_waitcnt lgkmcnt(1)
	v_mul_f32_e32 v21, 0x3fb8aa3b, v38
	v_exp_f32_e32 v21, v21
	s_waitcnt lgkmcnt(0)
	v_lshlrev_b32_e32 v17, 16, v17
	v_mul_f32_e32 v17, v39, v17
	v_mul_f32_e32 v39, v17, v21
	s_movk_i32 s7, 0x78
	v_add_u32_e64 v17, s7, 0
	ds_read2st64_b32 v[40:41], v17 offset0:200 offset1:201
	ds_read_u16 v17, v2 offset:8160
	s_waitcnt lgkmcnt(1)
	v_mul_f32_e32 v21, 0x3fb8aa3b, v40
	v_exp_f32_e32 v21, v21
	s_waitcnt lgkmcnt(0)
	v_lshlrev_b32_e32 v17, 16, v17
	v_mul_f32_e32 v17, v41, v17
	v_mul_f32_e32 v40, v17, v21
	s_movk_i32 s7, 0x7c
	v_add_u32_e64 v17, s7, 0
	ds_read2st64_b32 v[44:45], v17 offset0:200 offset1:201
	ds_read_u16 v17, v2 offset:8432
	s_waitcnt lgkmcnt(1)
	v_mul_f32_e32 v21, 0x3fb8aa3b, v44
	v_exp_f32_e32 v21, v21
	s_waitcnt lgkmcnt(0)
	v_lshlrev_b32_e32 v17, 16, v17
	v_mul_f32_e32 v17, v45, v17
	v_mul_f32_e32 v44, v17, v21
	s_movk_i32 s7, 0x80
	v_add_u32_e64 v17, s7, 0
	ds_read2st64_b32 v[46:47], v17 offset0:200 offset1:201
	ds_read_u16 v17, v2 offset:8704
	s_waitcnt lgkmcnt(1)
	v_mul_f32_e32 v21, 0x3fb8aa3b, v46
	v_exp_f32_e32 v21, v21
	s_waitcnt lgkmcnt(0)
	v_lshlrev_b32_e32 v17, 16, v17
	v_mul_f32_e32 v17, v47, v17
	v_mul_f32_e32 v46, v17, v21
	s_movk_i32 s7, 0x84
	v_add_u32_e64 v17, s7, 0
	ds_read2st64_b32 v[48:49], v17 offset0:200 offset1:201
	ds_read_u16 v17, v2 offset:8976
	s_waitcnt lgkmcnt(1)
	v_mul_f32_e32 v21, 0x3fb8aa3b, v48
	v_exp_f32_e32 v21, v21
	s_waitcnt lgkmcnt(0)
	v_lshlrev_b32_e32 v17, 16, v17
	v_mul_f32_e32 v17, v49, v17
	v_mul_f32_e32 v47, v17, v21
	s_movk_i32 s7, 0x88
	v_add_u32_e64 v17, s7, 0
	ds_read2st64_b32 v[48:49], v17 offset0:200 offset1:201
	ds_read_u16 v17, v2 offset:9248
	s_waitcnt lgkmcnt(1)
	v_mul_f32_e32 v21, 0x3fb8aa3b, v48
	v_exp_f32_e32 v21, v21
	s_waitcnt lgkmcnt(0)
	v_lshlrev_b32_e32 v17, 16, v17
	v_mul_f32_e32 v17, v49, v17
	v_mul_f32_e32 v49, v17, v21
	s_movk_i32 s7, 0x8c
	v_add_u32_e64 v17, s7, 0
	ds_read2st64_b32 v[50:51], v17 offset0:200 offset1:201
	ds_read_u16 v17, v2 offset:9520
	s_waitcnt lgkmcnt(1)
; DI float bf2f(unsigned h) { return __uint_as_float(h << 16); }
; DI void gdnprep_item(const Params& p, int item, unsigned char* ldsb) {
;     ...
; #pragma unroll
;     for (int i = 0; i < 64; ++i) {
;       if (isw) x[i] = bf2f(sK[i * 136 + c]) * sbeta[i] * __expf(sgc[i]);
;       else x[i] = bf2f(CQ[(size_t)(t0 + i) * 1536 + 1024 + h * 128 + c]) * sbeta[i];
;     }
	v_mul_f32_e32 v21, 0x3fb8aa3b, v50
	v_exp_f32_e32 v21, v21
	s_waitcnt lgkmcnt(0)
	v_lshlrev_b32_e32 v17, 16, v17
	v_mul_f32_e32 v17, v51, v17
	v_mul_f32_e32 v51, v17, v21
	v_add_u32_e64 v17, s87, 0
	ds_read2st64_b32 v[58:59], v17 offset0:200 offset1:201
	ds_read_u16 v17, v2 offset:9792
	s_waitcnt lgkmcnt(1)
	v_mul_f32_e32 v21, 0x3fb8aa3b, v58
	v_exp_f32_e32 v21, v21
	s_waitcnt lgkmcnt(0)
	v_lshlrev_b32_e32 v17, 16, v17
	v_mul_f32_e32 v17, v59, v17
	v_mul_f32_e32 v58, v17, v21
	s_movk_i32 s7, 0x94
	v_add_u32_e64 v17, s7, 0
	ds_read2st64_b32 v[60:61], v17 offset0:200 offset1:201
	ds_read_u16 v17, v2 offset:10064
	s_waitcnt lgkmcnt(1)
	v_mul_f32_e32 v21, 0x3fb8aa3b, v60
	v_exp_f32_e32 v21, v21
	s_waitcnt lgkmcnt(0)
	v_lshlrev_b32_e32 v17, 16, v17
	v_mul_f32_e32 v17, v61, v17
	v_mul_f32_e32 v59, v17, v21
	s_movk_i32 s7, 0x98
	v_add_u32_e64 v17, s7, 0
	ds_read2st64_b32 v[60:61], v17 offset0:200 offset1:201
	ds_read_u16 v17, v2 offset:10336
	s_waitcnt lgkmcnt(1)
	v_mul_f32_e32 v21, 0x3fb8aa3b, v60
	v_exp_f32_e32 v21, v21
	s_waitcnt lgkmcnt(0)
	v_lshlrev_b32_e32 v17, 16, v17
	v_mul_f32_e32 v17, v61, v17
	v_mul_f32_e32 v61, v17, v21
	s_movk_i32 s7, 0x9c
	v_add_u32_e64 v17, s7, 0
	ds_read2st64_b32 v[62:63], v17 offset0:200 offset1:201
	ds_read_u16 v17, v2 offset:10608
	s_waitcnt lgkmcnt(1)
	v_mul_f32_e32 v21, 0x3fb8aa3b, v62
	v_exp_f32_e32 v21, v21
	s_waitcnt lgkmcnt(0)
	v_lshlrev_b32_e32 v17, 16, v17
	v_mul_f32_e32 v17, v63, v17
	v_mul_f32_e32 v63, v17, v21
	s_movk_i32 s7, 0xa0
	v_add_u32_e64 v17, s7, 0
	ds_read2st64_b32 v[64:65], v17 offset0:200 offset1:201
	ds_read_u16 v17, v2 offset:10880
	s_waitcnt lgkmcnt(1)
	v_mul_f32_e32 v21, 0x3fb8aa3b, v64
	v_exp_f32_e32 v21, v21
	s_waitcnt lgkmcnt(0)
	v_lshlrev_b32_e32 v17, 16, v17
	v_mul_f32_e32 v17, v65, v17
	v_mul_f32_e32 v65, v17, v21
	s_movk_i32 s7, 0xa4
	v_add_u32_e64 v17, s7, 0
	ds_read2st64_b32 v[66:67], v17 offset0:200 offset1:201
	ds_read_u16 v17, v2 offset:11152
	s_waitcnt lgkmcnt(1)
	v_mul_f32_e32 v21, 0x3fb8aa3b, v66
	v_exp_f32_e32 v21, v21
	s_waitcnt lgkmcnt(0)
	v_lshlrev_b32_e32 v17, 16, v17
	v_mul_f32_e32 v17, v67, v17
	v_mul_f32_e32 v67, v17, v21
	s_movk_i32 s7, 0xa8
	v_add_u32_e64 v17, s7, 0
	ds_read2st64_b32 v[68:69], v17 offset0:200 offset1:201
	ds_read_u16 v17, v2 offset:11424
	s_waitcnt lgkmcnt(1)
	v_mul_f32_e32 v21, 0x3fb8aa3b, v68
	v_exp_f32_e32 v21, v21
	s_waitcnt lgkmcnt(0)
	v_lshlrev_b32_e32 v17, 16, v17
	v_mul_f32_e32 v17, v69, v17
	v_mul_f32_e32 v69, v17, v21
	s_movk_i32 s7, 0xac
	v_add_u32_e64 v17, s7, 0
	ds_read2st64_b32 v[70:71], v17 offset0:200 offset1:201
	ds_read_u16 v17, v2 offset:11696
	s_waitcnt lgkmcnt(1)
	v_mul_f32_e32 v21, 0x3fb8aa3b, v70
	v_exp_f32_e32 v21, v21
	s_waitcnt lgkmcnt(0)
	v_lshlrev_b32_e32 v17, 16, v17
	v_mul_f32_e32 v17, v71, v17
	v_mul_f32_e32 v71, v17, v21
	s_movk_i32 s7, 0xb0
	v_add_u32_e64 v17, s7, 0
	ds_read2st64_b32 v[72:73], v17 offset0:200 offset1:201
	ds_read_u16 v17, v2 offset:11968
	s_waitcnt lgkmcnt(1)
	v_mul_f32_e32 v21, 0x3fb8aa3b, v72
	v_exp_f32_e32 v21, v21
	s_waitcnt lgkmcnt(0)
	v_lshlrev_b32_e32 v17, 16, v17
	v_mul_f32_e32 v17, v73, v17
	v_mul_f32_e32 v73, v17, v21
	s_movk_i32 s7, 0xb4
	v_add_u32_e64 v17, s7, 0
	ds_read2st64_b32 v[74:75], v17 offset0:200 offset1:201
	ds_read_u16 v17, v2 offset:12240
	s_waitcnt lgkmcnt(1)
	v_mul_f32_e32 v21, 0x3fb8aa3b, v74
	v_exp_f32_e32 v21, v21
	s_waitcnt lgkmcnt(0)
	v_lshlrev_b32_e32 v17, 16, v17
	v_mul_f32_e32 v17, v75, v17
	v_mul_f32_e32 v72, v17, v21
	s_movk_i32 s7, 0xb8
	v_add_u32_e64 v17, s7, 0
	ds_read2st64_b32 v[74:75], v17 offset0:200 offset1:201
	ds_read_u16 v17, v2 offset:12512
	s_waitcnt lgkmcnt(1)
	v_mul_f32_e32 v21, 0x3fb8aa3b, v74
	v_exp_f32_e32 v21, v21
	s_waitcnt lgkmcnt(0)
	v_lshlrev_b32_e32 v17, 16, v17
	v_mul_f32_e32 v17, v75, v17
	v_mul_f32_e32 v70, v17, v21
	s_movk_i32 s5, 0xbc
	v_add_u32_e64 v17, s5, 0
	ds_read2st64_b32 v[74:75], v17 offset0:200 offset1:201
	ds_read_u16 v17, v2 offset:12784
	s_waitcnt lgkmcnt(1)
	v_mul_f32_e32 v21, 0x3fb8aa3b, v74
	v_exp_f32_e32 v21, v21
	s_waitcnt lgkmcnt(0)
	v_lshlrev_b32_e32 v17, 16, v17
	v_mul_f32_e32 v17, v75, v17
	v_mul_f32_e32 v68, v17, v21
	s_movk_i32 s5, 0xc0
	v_add_u32_e64 v17, s5, 0
	ds_read2st64_b32 v[74:75], v17 offset0:200 offset1:201
	ds_read_u16 v17, v2 offset:13056
	s_waitcnt lgkmcnt(1)
	v_mul_f32_e32 v21, 0x3fb8aa3b, v74
	v_exp_f32_e32 v21, v21
	s_waitcnt lgkmcnt(0)
	v_lshlrev_b32_e32 v17, 16, v17
	v_mul_f32_e32 v17, v75, v17
	v_mul_f32_e32 v66, v17, v21
	s_movk_i32 s5, 0xc4
	v_add_u32_e64 v17, s5, 0
	ds_read2st64_b32 v[74:75], v17 offset0:200 offset1:201
	ds_read_u16 v17, v2 offset:13328
	s_waitcnt lgkmcnt(1)
	v_mul_f32_e32 v21, 0x3fb8aa3b, v74
	v_exp_f32_e32 v21, v21
	s_waitcnt lgkmcnt(0)
	v_lshlrev_b32_e32 v17, 16, v17
	v_mul_f32_e32 v17, v75, v17
	v_mul_f32_e32 v64, v17, v21
	s_movk_i32 s5, 0xc8
	v_add_u32_e64 v17, s5, 0
	ds_read2st64_b32 v[74:75], v17 offset0:200 offset1:201
	ds_read_u16 v17, v2 offset:13600
	s_waitcnt lgkmcnt(1)
	v_mul_f32_e32 v21, 0x3fb8aa3b, v74
	v_exp_f32_e32 v21, v21
	s_waitcnt lgkmcnt(0)
	v_lshlrev_b32_e32 v17, 16, v17
	v_mul_f32_e32 v17, v75, v17
	v_mul_f32_e32 v62, v17, v21
	s_movk_i32 s5, 0xcc
	v_add_u32_e64 v17, s5, 0
	ds_read2st64_b32 v[74:75], v17 offset0:200 offset1:201
	ds_read_u16 v17, v2 offset:13872
	s_waitcnt lgkmcnt(1)
	v_mul_f32_e32 v21, 0x3fb8aa3b, v74
	v_exp_f32_e32 v21, v21
	s_waitcnt lgkmcnt(0)
	v_lshlrev_b32_e32 v17, 16, v17
	v_mul_f32_e32 v17, v75, v17
	v_mul_f32_e32 v60, v17, v21
	s_movk_i32 s5, 0xd0
	v_add_u32_e64 v17, s5, 0
	ds_read2st64_b32 v[74:75], v17 offset0:200 offset1:201
	ds_read_u16 v17, v2 offset:14144
	s_waitcnt lgkmcnt(1)
; DI float bf2f(unsigned h) { return __uint_as_float(h << 16); }
; DI void gdnprep_item(const Params& p, int item, unsigned char* ldsb) {
;     ...
; #pragma unroll
;     for (int i = 0; i < 64; ++i) {
;       if (isw) x[i] = bf2f(sK[i * 136 + c]) * sbeta[i] * __expf(sgc[i]);
;       else x[i] = bf2f(CQ[(size_t)(t0 + i) * 1536 + 1024 + h * 128 + c]) * sbeta[i];
;     }
; #pragma unroll
;     for (int i = 1; i < 64; ++i) {
;       float a = x[i];
; #pragma unroll
;       for (int j4 = 0; j4 < (i + 3) / 4; ++j4) {
;         f32x4 Lv = *(const f32x4*)(Lm + i * 64 + j4 * 4);
; #pragma unroll
;         for (int e = 0; e < 4; ++e) if (j4 * 4 + e < i) a -= Lv[e] * x[j4 * 4 + e];
;       }
;       x[i] = a;
;       if ((i & 3) == 3) __builtin_amdgcn_sched_barrier(0);
	v_mul_f32_e32 v21, 0x3fb8aa3b, v74
	v_exp_f32_e32 v21, v21
	s_waitcnt lgkmcnt(0)
	v_lshlrev_b32_e32 v17, 16, v17
	v_mul_f32_e32 v17, v75, v17
	v_mul_f32_e32 v57, v17, v21
	s_movk_i32 s5, 0xd4
	v_add_u32_e64 v17, s5, 0
	ds_read2st64_b32 v[74:75], v17 offset0:200 offset1:201
	ds_read_u16 v17, v2 offset:14416
	s_waitcnt lgkmcnt(1)
	v_mul_f32_e32 v21, 0x3fb8aa3b, v74
	v_exp_f32_e32 v21, v21
	s_waitcnt lgkmcnt(0)
	v_lshlrev_b32_e32 v17, 16, v17
	v_mul_f32_e32 v17, v75, v17
	v_mul_f32_e32 v50, v17, v21
	s_movk_i32 s5, 0xd8
	v_add_u32_e64 v17, s5, 0
	ds_read2st64_b32 v[74:75], v17 offset0:200 offset1:201
	ds_read_u16 v17, v2 offset:14688
	s_waitcnt lgkmcnt(1)
	v_mul_f32_e32 v21, 0x3fb8aa3b, v74
	v_exp_f32_e32 v21, v21
	s_waitcnt lgkmcnt(0)
	v_lshlrev_b32_e32 v17, 16, v17
	v_mul_f32_e32 v17, v75, v17
	v_mul_f32_e32 v48, v17, v21
	s_movk_i32 s5, 0xdc
	v_add_u32_e64 v17, s5, 0
	ds_read2st64_b32 v[74:75], v17 offset0:200 offset1:201
	ds_read_u16 v17, v2 offset:14960
	s_waitcnt lgkmcnt(1)
	v_mul_f32_e32 v21, 0x3fb8aa3b, v74
	v_exp_f32_e32 v21, v21
	s_waitcnt lgkmcnt(0)
	v_lshlrev_b32_e32 v17, 16, v17
	v_mul_f32_e32 v17, v75, v17
	v_mul_f32_e32 v45, v17, v21
	s_movk_i32 s5, 0xe0
	v_add_u32_e64 v17, s5, 0
	ds_read2st64_b32 v[74:75], v17 offset0:200 offset1:201
	ds_read_u16 v17, v2 offset:15232
	s_waitcnt lgkmcnt(1)
	v_mul_f32_e32 v21, 0x3fb8aa3b, v74
	v_exp_f32_e32 v21, v21
	s_waitcnt lgkmcnt(0)
	v_lshlrev_b32_e32 v17, 16, v17
	v_mul_f32_e32 v17, v75, v17
	v_mul_f32_e32 v41, v17, v21
	s_movk_i32 s5, 0xe4
	v_add_u32_e64 v17, s5, 0
	ds_read2st64_b32 v[74:75], v17 offset0:200 offset1:201
	ds_read_u16 v17, v2 offset:15504
	s_waitcnt lgkmcnt(1)
	v_mul_f32_e32 v21, 0x3fb8aa3b, v74
	v_exp_f32_e32 v21, v21
	s_waitcnt lgkmcnt(0)
	v_lshlrev_b32_e32 v17, 16, v17
	v_mul_f32_e32 v17, v75, v17
	v_mul_f32_e32 v38, v17, v21
	s_movk_i32 s5, 0xe8
	v_add_u32_e64 v17, s5, 0
	ds_read2st64_b32 v[74:75], v17 offset0:200 offset1:201
	ds_read_u16 v17, v2 offset:15776
	s_waitcnt lgkmcnt(1)
	v_mul_f32_e32 v21, 0x3fb8aa3b, v74
	v_exp_f32_e32 v21, v21
	s_waitcnt lgkmcnt(0)
	v_lshlrev_b32_e32 v17, 16, v17
	v_mul_f32_e32 v17, v75, v17
	v_mul_f32_e32 v35, v17, v21
	s_movk_i32 s5, 0xec
	v_add_u32_e64 v17, s5, 0
	ds_read2st64_b32 v[74:75], v17 offset0:200 offset1:201
	ds_read_u16 v17, v2 offset:16048
	s_waitcnt lgkmcnt(1)
	v_mul_f32_e32 v21, 0x3fb8aa3b, v74
	v_exp_f32_e32 v21, v21
	s_waitcnt lgkmcnt(0)
	v_lshlrev_b32_e32 v17, 16, v17
	v_mul_f32_e32 v17, v75, v17
	v_mul_f32_e32 v32, v17, v21
	s_movk_i32 s5, 0xf0
	v_add_u32_e64 v17, s5, 0
	ds_read2st64_b32 v[74:75], v17 offset0:200 offset1:201
	ds_read_u16 v17, v2 offset:16320
	s_waitcnt lgkmcnt(1)
	v_mul_f32_e32 v21, 0x3fb8aa3b, v74
	v_exp_f32_e32 v21, v21
	s_waitcnt lgkmcnt(0)
	v_lshlrev_b32_e32 v17, 16, v17
	v_mul_f32_e32 v17, v75, v17
	v_mul_f32_e32 v29, v17, v21
	s_movk_i32 s5, 0xf4
	v_add_u32_e64 v17, s5, 0
	ds_read2st64_b32 v[74:75], v17 offset0:200 offset1:201
	ds_read_u16 v17, v2 offset:16592
	s_waitcnt lgkmcnt(1)
	v_mul_f32_e32 v21, 0x3fb8aa3b, v74
	v_exp_f32_e32 v21, v21
	s_waitcnt lgkmcnt(0)
	v_lshlrev_b32_e32 v17, 16, v17
	v_mul_f32_e32 v17, v75, v17
	v_mul_f32_e32 v26, v17, v21
	s_movk_i32 s5, 0xf8
	v_add_u32_e64 v17, s5, 0
	ds_read2st64_b32 v[74:75], v17 offset0:200 offset1:201
	ds_read_u16 v17, v2 offset:16864
	s_waitcnt lgkmcnt(1)
	v_mul_f32_e32 v21, 0x3fb8aa3b, v74
	v_exp_f32_e32 v21, v21
	s_waitcnt lgkmcnt(0)
	v_lshlrev_b32_e32 v17, 16, v17
	v_mul_f32_e32 v17, v75, v17
	v_mul_f32_e32 v21, v17, v21
	s_movk_i32 s4, 0xfc
	v_add_u32_e64 v17, s4, 0
	ds_read2st64_b32 v[74:75], v17 offset0:200 offset1:201
	ds_read_u16 v17, v2 offset:17136
	s_waitcnt lgkmcnt(1)
	v_mul_f32_e32 v74, 0x3fb8aa3b, v74
	v_exp_f32_e32 v74, v74
	s_waitcnt lgkmcnt(0)
	v_lshlrev_b32_e32 v17, 16, v17
	v_mul_f32_e32 v17, v75, v17
	v_mul_f32_e32 v17, v17, v74
.Lxinit_done:
.LBB0_833:
	s_or_b64 exec, exec, s[0:1]
	ds_read_b128 v[100:103], v1 offset:35072
	ds_read_b128 v[104:107], v1 offset:35328
	ds_read_b128 v[108:111], v1 offset:35584
	ds_read_b128 v[112:115], v1 offset:35840
	ds_read_b128 v[116:119], v1 offset:36096
	ds_read_b128 v[120:123], v1 offset:36112
	ds_read_b128 v[124:127], v1 offset:36352
	ds_read_b128 v[128:131], v1 offset:36368
	ds_read_b128 v[132:135], v1 offset:36608
	ds_read_b128 v[136:139], v1 offset:36624
	ds_read_b128 v[140:143], v1 offset:36864
	ds_read_b128 v[144:147], v1 offset:36880
	ds_read_b128 v[148:151], v1 offset:37120
	ds_read_b128 v[152:155], v1 offset:37136
	s_waitcnt lgkmcnt(13)
	v_fma_f32 v4, -v0, v100, v4
	ds_read_b128 v[100:103], v1 offset:37152
	s_waitcnt lgkmcnt(13)
	v_fma_f32 v5, -v0, v104, v5
	v_fma_f32 v5, -v105, v4, v5
	ds_read_b128 v[104:107], v1 offset:37376
	s_waitcnt lgkmcnt(13)
	v_fma_f32 v6, -v0, v108, v6
	v_fma_f32 v6, -v109, v4, v6
	v_fma_f32 v6, -v110, v5, v6
	ds_read_b128 v[108:111], v1 offset:37392
	s_waitcnt lgkmcnt(13)
	v_fma_f32 v7, -v0, v112, v7
	v_fma_f32 v7, -v4, v113, v7
	v_fma_f32 v7, -v114, v5, v7
	v_fma_f32 v7, -v115, v6, v7
	ds_read_b128 v[112:115], v1 offset:37408
	s_waitcnt lgkmcnt(13)
	v_fma_f32 v8, -v0, v116, v8
	v_fma_f32 v8, -v4, v117, v8
	v_fma_f32 v8, -v5, v118, v8
	v_fma_f32 v8, -v119, v6, v8
	ds_read_b128 v[116:119], v1 offset:37632
	s_waitcnt lgkmcnt(13)
	v_fma_f32 v8, -v120, v7, v8
	ds_read_b128 v[120:123], v1 offset:37648
	s_waitcnt lgkmcnt(13)
	v_fma_f32 v9, -v0, v124, v9
	v_fma_f32 v9, -v4, v125, v9
	v_fma_f32 v9, -v5, v126, v9
	v_fma_f32 v9, -v6, v127, v9
	ds_read_b128 v[124:127], v1 offset:37664
	s_waitcnt lgkmcnt(13)
	v_fma_f32 v9, -v128, v7, v9
	v_fma_f32 v9, -v129, v8, v9
	ds_read_b128 v[128:131], v1 offset:37888
	s_waitcnt lgkmcnt(13)
; DI void gdnprep_item(const Params& p, int item, unsigned char* ldsb) {
;     ...
;     for (int i = 1; i < 64; ++i) {
;       float a = x[i];
; #pragma unroll
;       for (int j4 = 0; j4 < (i + 3) / 4; ++j4) {
;         f32x4 Lv = *(const f32x4*)(Lm + i * 64 + j4 * 4);
; #pragma unroll
;         for (int e = 0; e < 4; ++e) if (j4 * 4 + e < i) a -= Lv[e] * x[j4 * 4 + e];
;       }
;       x[i] = a;
;       if ((i & 3) == 3) __builtin_amdgcn_sched_barrier(0);
;     }
	v_fma_f32 v10, -v0, v132, v10
	v_fma_f32 v10, -v4, v133, v10
	v_fma_f32 v10, -v5, v134, v10
	v_fma_f32 v10, -v6, v135, v10
	ds_read_b128 v[132:135], v1 offset:37904
	s_waitcnt lgkmcnt(13)
	v_fma_f32 v10, -v7, v136, v10
	v_fma_f32 v10, -v137, v8, v10
	v_fma_f32 v10, -v138, v9, v10
	ds_read_b128 v[136:139], v1 offset:37920
	s_waitcnt lgkmcnt(13)
	v_fma_f32 v11, -v0, v140, v11
	v_fma_f32 v11, -v4, v141, v11
	v_fma_f32 v11, -v5, v142, v11
	v_fma_f32 v11, -v6, v143, v11
	ds_read_b128 v[140:143], v1 offset:38144
	s_waitcnt lgkmcnt(13)
	v_fma_f32 v11, -v7, v144, v11
	v_fma_f32 v11, -v8, v145, v11
	v_fma_f32 v11, -v146, v9, v11
	v_fma_f32 v11, -v147, v10, v11
	ds_read_b128 v[144:147], v1 offset:38160
	s_waitcnt lgkmcnt(13)
	v_fma_f32 v12, -v0, v148, v12
	v_fma_f32 v12, -v4, v149, v12
	v_fma_f32 v12, -v5, v150, v12
	v_fma_f32 v12, -v6, v151, v12
	ds_read_b128 v[148:151], v1 offset:38176
	s_waitcnt lgkmcnt(13)
	v_fma_f32 v12, -v7, v152, v12
	v_fma_f32 v12, -v8, v153, v12
	v_fma_f32 v12, -v9, v154, v12
	v_fma_f32 v12, -v155, v10, v12
	ds_read_b128 v[152:155], v1 offset:38192
	s_waitcnt lgkmcnt(13)
	v_fma_f32 v12, -v100, v11, v12
	ds_read_b128 v[100:103], v1 offset:38400
	s_waitcnt lgkmcnt(13)
	v_fma_f32 v13, -v0, v104, v13
	v_fma_f32 v13, -v4, v105, v13
	v_fma_f32 v13, -v5, v106, v13
	v_fma_f32 v13, -v6, v107, v13
	ds_read_b128 v[104:107], v1 offset:38416
	s_waitcnt lgkmcnt(13)
	v_fma_f32 v13, -v7, v108, v13
	v_fma_f32 v13, -v8, v109, v13
	v_fma_f32 v13, -v9, v110, v13
	v_fma_f32 v13, -v10, v111, v13
	ds_read_b128 v[108:111], v1 offset:38432
	s_waitcnt lgkmcnt(13)
	v_fma_f32 v13, -v112, v11, v13
	v_fma_f32 v13, -v113, v12, v13
	ds_read_b128 v[112:115], v1 offset:38448
	s_waitcnt lgkmcnt(13)
	v_fma_f32 v14, -v0, v116, v14
	v_fma_f32 v14, -v4, v117, v14
	v_fma_f32 v14, -v5, v118, v14
	v_fma_f32 v14, -v6, v119, v14
	ds_read_b128 v[116:119], v1 offset:38656
	s_waitcnt lgkmcnt(13)
	v_fma_f32 v14, -v7, v120, v14
	v_fma_f32 v14, -v8, v121, v14
	v_fma_f32 v14, -v9, v122, v14
	v_fma_f32 v14, -v10, v123, v14
	ds_read_b128 v[120:123], v1 offset:38672
	s_waitcnt lgkmcnt(13)
	v_fma_f32 v14, -v11, v124, v14
	v_fma_f32 v14, -v125, v12, v14
	v_fma_f32 v14, -v126, v13, v14
	ds_read_b128 v[124:127], v1 offset:38688
	s_waitcnt lgkmcnt(13)
	v_fma_f32 v15, -v0, v128, v15
	v_fma_f32 v15, -v4, v129, v15
	v_fma_f32 v15, -v5, v130, v15
	v_fma_f32 v15, -v6, v131, v15
	ds_read_b128 v[128:131], v1 offset:38704
	s_waitcnt lgkmcnt(13)
	v_fma_f32 v15, -v7, v132, v15
	v_fma_f32 v15, -v8, v133, v15
	v_fma_f32 v15, -v9, v134, v15
	v_fma_f32 v15, -v10, v135, v15
	ds_read_b128 v[132:135], v1 offset:38912
	s_waitcnt lgkmcnt(12)
	v_fma_f32 v16, -v0, v140, v16
	v_fma_f32 v16, -v4, v141, v16
	v_fma_f32 v16, -v5, v142, v16
	v_fma_f32 v16, -v6, v143, v16
	v_fma_f32 v15, -v11, v136, v15
	v_fma_f32 v15, -v12, v137, v15
	v_fma_f32 v15, -v138, v13, v15
	v_fma_f32 v15, -v139, v14, v15
	ds_read_b128 v[136:139], v1 offset:38928
	ds_read_b128 v[140:143], v1 offset:38944
	s_waitcnt lgkmcnt(13)
	v_fma_f32 v16, -v7, v144, v16
	v_fma_f32 v16, -v8, v145, v16
	v_fma_f32 v16, -v9, v146, v16
	v_fma_f32 v16, -v10, v147, v16
	ds_read_b128 v[144:147], v1 offset:38960
	s_waitcnt lgkmcnt(13)
	v_fma_f32 v16, -v11, v148, v16
	v_fma_f32 v16, -v12, v149, v16
	v_fma_f32 v16, -v13, v150, v16
	v_fma_f32 v16, -v151, v14, v16
	ds_read_b128 v[148:151], v1 offset:39168
	s_waitcnt lgkmcnt(13)
	v_fma_f32 v16, -v152, v15, v16
	ds_read_b128 v[152:155], v1 offset:39184
	s_waitcnt lgkmcnt(13)
	v_fma_f32 v18, -v0, v100, v18
	v_fma_f32 v18, -v4, v101, v18
	v_fma_f32 v18, -v5, v102, v18
	v_fma_f32 v18, -v6, v103, v18
	ds_read_b128 v[100:103], v1 offset:39200
	s_waitcnt lgkmcnt(13)
	v_fma_f32 v18, -v7, v104, v18
	v_fma_f32 v18, -v8, v105, v18
	v_fma_f32 v18, -v9, v106, v18
	v_fma_f32 v18, -v10, v107, v18
	ds_read_b128 v[104:107], v1 offset:39216
	s_waitcnt lgkmcnt(13)
	v_fma_f32 v18, -v11, v108, v18
	v_fma_f32 v18, -v12, v109, v18
	v_fma_f32 v18, -v13, v110, v18
	v_fma_f32 v18, -v14, v111, v18
	ds_read_b128 v[108:111], v1 offset:39232
	s_waitcnt lgkmcnt(13)
	v_fma_f32 v18, -v112, v15, v18
	v_fma_f32 v18, -v113, v16, v18
	ds_read_b128 v[112:115], v1 offset:39424
	s_waitcnt lgkmcnt(13)
	v_fma_f32 v19, -v0, v116, v19
	v_fma_f32 v19, -v4, v117, v19
	v_fma_f32 v19, -v5, v118, v19
	v_fma_f32 v19, -v6, v119, v19
	ds_read_b128 v[116:119], v1 offset:39440
	s_waitcnt lgkmcnt(13)
	v_fma_f32 v19, -v7, v120, v19
	v_fma_f32 v19, -v8, v121, v19
	v_fma_f32 v19, -v9, v122, v19
	v_fma_f32 v19, -v10, v123, v19
	ds_read_b128 v[120:123], v1 offset:39456
	s_waitcnt lgkmcnt(13)
	v_fma_f32 v19, -v11, v124, v19
	v_fma_f32 v19, -v12, v125, v19
	v_fma_f32 v19, -v13, v126, v19
	v_fma_f32 v19, -v14, v127, v19
	ds_read_b128 v[124:127], v1 offset:39472
	s_waitcnt lgkmcnt(13)
	v_fma_f32 v19, -v15, v128, v19
	v_fma_f32 v19, -v129, v16, v19
	v_fma_f32 v19, -v130, v18, v19
	ds_read_b128 v[128:131], v1 offset:39488
	s_waitcnt lgkmcnt(13)
	v_fma_f32 v20, -v0, v132, v20
	v_fma_f32 v20, -v4, v133, v20
	v_fma_f32 v20, -v5, v134, v20
	v_fma_f32 v20, -v6, v135, v20
	ds_read_b128 v[132:135], v1 offset:39680
	s_waitcnt lgkmcnt(13)
	v_fma_f32 v20, -v7, v136, v20
	v_fma_f32 v20, -v8, v137, v20
	v_fma_f32 v20, -v9, v138, v20
	v_fma_f32 v20, -v10, v139, v20
	ds_read_b128 v[136:139], v1 offset:39696
	s_waitcnt lgkmcnt(11)
	v_fma_f32 v22, -v0, v148, v22
	v_fma_f32 v22, -v4, v149, v22
	v_fma_f32 v22, -v5, v150, v22
	v_fma_f32 v22, -v6, v151, v22
	v_fma_f32 v20, -v11, v140, v20
	v_fma_f32 v20, -v12, v141, v20
	v_fma_f32 v20, -v13, v142, v20
	v_fma_f32 v20, -v14, v143, v20
	ds_read_b128 v[140:143], v1 offset:39712
	s_waitcnt lgkmcnt(11)
; DI void gdnprep_item(const Params& p, int item, unsigned char* ldsb) {
;     ...
;     for (int i = 1; i < 64; ++i) {
;       float a = x[i];
; #pragma unroll
;       for (int j4 = 0; j4 < (i + 3) / 4; ++j4) {
;         f32x4 Lv = *(const f32x4*)(Lm + i * 64 + j4 * 4);
; #pragma unroll
;         for (int e = 0; e < 4; ++e) if (j4 * 4 + e < i) a -= Lv[e] * x[j4 * 4 + e];
;       }
;       x[i] = a;
;       if ((i & 3) == 3) __builtin_amdgcn_sched_barrier(0);
;     }
	v_fma_f32 v22, -v7, v152, v22
	v_fma_f32 v22, -v8, v153, v22
	v_fma_f32 v22, -v9, v154, v22
	v_fma_f32 v22, -v10, v155, v22
	v_fma_f32 v20, -v15, v144, v20
	v_fma_f32 v20, -v16, v145, v20
	v_fma_f32 v20, -v146, v18, v20
	v_fma_f32 v20, -v147, v19, v20
	ds_read_b128 v[144:147], v1 offset:39728
	ds_read_b128 v[148:151], v1 offset:39744
	ds_read_b128 v[152:155], v1 offset:39936
	s_waitcnt lgkmcnt(13)
	v_fma_f32 v22, -v11, v100, v22
	v_fma_f32 v22, -v12, v101, v22
	v_fma_f32 v22, -v13, v102, v22
	v_fma_f32 v22, -v14, v103, v22
	ds_read_b128 v[100:103], v1 offset:39952
	s_waitcnt lgkmcnt(13)
	v_fma_f32 v22, -v15, v104, v22
	v_fma_f32 v22, -v16, v105, v22
	v_fma_f32 v22, -v18, v106, v22
	v_fma_f32 v22, -v107, v19, v22
	ds_read_b128 v[104:107], v1 offset:39968
	s_waitcnt lgkmcnt(13)
	v_fma_f32 v22, -v108, v20, v22
	ds_read_b128 v[108:111], v1 offset:39984
	s_waitcnt lgkmcnt(13)
	v_fma_f32 v23, -v0, v112, v23
	v_fma_f32 v23, -v4, v113, v23
	v_fma_f32 v23, -v5, v114, v23
	v_fma_f32 v23, -v6, v115, v23
	ds_read_b128 v[112:115], v1 offset:40000
	s_waitcnt lgkmcnt(13)
	v_fma_f32 v23, -v7, v116, v23
	v_fma_f32 v23, -v8, v117, v23
	v_fma_f32 v23, -v9, v118, v23
	v_fma_f32 v23, -v10, v119, v23
	ds_read_b128 v[116:119], v1 offset:40192
	s_waitcnt lgkmcnt(13)
	v_fma_f32 v23, -v11, v120, v23
	v_fma_f32 v23, -v12, v121, v23
	v_fma_f32 v23, -v13, v122, v23
	v_fma_f32 v23, -v14, v123, v23
	ds_read_b128 v[120:123], v1 offset:40208
	s_waitcnt lgkmcnt(13)
	v_fma_f32 v23, -v15, v124, v23
	v_fma_f32 v23, -v16, v125, v23
	v_fma_f32 v23, -v18, v126, v23
	v_fma_f32 v23, -v19, v127, v23
	ds_read_b128 v[124:127], v1 offset:40224
	s_waitcnt lgkmcnt(13)
	v_fma_f32 v23, -v128, v20, v23
	v_fma_f32 v23, -v129, v22, v23
	ds_read_b128 v[128:131], v1 offset:40240
	s_waitcnt lgkmcnt(13)
	v_fma_f32 v24, -v0, v132, v24
	v_fma_f32 v24, -v4, v133, v24
	v_fma_f32 v24, -v5, v134, v24
	v_fma_f32 v24, -v6, v135, v24
	ds_read_b128 v[132:135], v1 offset:40256
	s_waitcnt lgkmcnt(13)
	v_fma_f32 v24, -v7, v136, v24
	v_fma_f32 v24, -v8, v137, v24
	v_fma_f32 v24, -v9, v138, v24
	v_fma_f32 v24, -v10, v139, v24
	ds_read_b128 v[136:139], v1 offset:40272
	s_waitcnt lgkmcnt(13)
	v_fma_f32 v24, -v11, v140, v24
	v_fma_f32 v24, -v12, v141, v24
	v_fma_f32 v24, -v13, v142, v24
	v_fma_f32 v24, -v14, v143, v24
	ds_read_b128 v[140:143], v1 offset:40448
	s_waitcnt lgkmcnt(13)
	v_fma_f32 v24, -v15, v144, v24
	v_fma_f32 v24, -v16, v145, v24
	v_fma_f32 v24, -v18, v146, v24
	v_fma_f32 v24, -v19, v147, v24
	ds_read_b128 v[144:147], v1 offset:40464
	s_waitcnt lgkmcnt(13)
	v_fma_f32 v24, -v20, v148, v24
	v_fma_f32 v24, -v149, v22, v24
	v_fma_f32 v24, -v150, v23, v24
	ds_read_b128 v[148:151], v1 offset:40480
	s_waitcnt lgkmcnt(13)
	v_fma_f32 v25, -v0, v152, v25
	v_fma_f32 v25, -v4, v153, v25
	v_fma_f32 v25, -v5, v154, v25
	v_fma_f32 v25, -v6, v155, v25
	ds_read_b128 v[152:155], v1 offset:40496
	s_waitcnt lgkmcnt(13)
	v_fma_f32 v25, -v7, v100, v25
	v_fma_f32 v25, -v8, v101, v25
	v_fma_f32 v25, -v9, v102, v25
	v_fma_f32 v25, -v10, v103, v25
	ds_read_b128 v[100:103], v1 offset:40512
	s_waitcnt lgkmcnt(13)
	v_fma_f32 v25, -v11, v104, v25
	v_fma_f32 v25, -v12, v105, v25
	v_fma_f32 v25, -v13, v106, v25
	v_fma_f32 v25, -v14, v107, v25
	ds_read_b128 v[104:107], v1 offset:40528
	s_waitcnt lgkmcnt(13)
	v_fma_f32 v25, -v15, v108, v25
	v_fma_f32 v25, -v16, v109, v25
	v_fma_f32 v25, -v18, v110, v25
	v_fma_f32 v25, -v19, v111, v25
	ds_read_b128 v[108:111], v1 offset:40704
	s_waitcnt lgkmcnt(13)
	v_fma_f32 v25, -v20, v112, v25
	v_fma_f32 v25, -v22, v113, v25
	v_fma_f32 v25, -v114, v23, v25
	v_fma_f32 v25, -v115, v24, v25
	ds_read_b128 v[112:115], v1 offset:40720
	s_waitcnt lgkmcnt(13)
	v_fma_f32 v27, -v0, v116, v27
	v_fma_f32 v27, -v4, v117, v27
	v_fma_f32 v27, -v5, v118, v27
	v_fma_f32 v27, -v6, v119, v27
	ds_read_b128 v[116:119], v1 offset:40736
	s_waitcnt lgkmcnt(13)
	v_fma_f32 v27, -v7, v120, v27
	v_fma_f32 v27, -v8, v121, v27
	v_fma_f32 v27, -v9, v122, v27
	v_fma_f32 v27, -v10, v123, v27
	ds_read_b128 v[120:123], v1 offset:40752
	s_waitcnt lgkmcnt(13)
	v_fma_f32 v27, -v11, v124, v27
	v_fma_f32 v27, -v12, v125, v27
	v_fma_f32 v27, -v13, v126, v27
	v_fma_f32 v27, -v14, v127, v27
	ds_read_b128 v[124:127], v1 offset:40768
	s_waitcnt lgkmcnt(13)
	v_fma_f32 v27, -v15, v128, v27
	v_fma_f32 v27, -v16, v129, v27
	v_fma_f32 v27, -v18, v130, v27
	v_fma_f32 v27, -v19, v131, v27
	ds_read_b128 v[128:131], v1 offset:40784
	s_waitcnt lgkmcnt(13)
	v_fma_f32 v27, -v20, v132, v27
	v_fma_f32 v27, -v22, v133, v27
	v_fma_f32 v27, -v23, v134, v27
	v_fma_f32 v27, -v135, v24, v27
	ds_read_b128 v[132:135], v1 offset:40960
	s_waitcnt lgkmcnt(13)
	v_fma_f32 v27, -v136, v25, v27
	ds_read_b128 v[136:139], v1 offset:40976
	s_waitcnt lgkmcnt(13)
	v_fma_f32 v28, -v0, v140, v28
	v_fma_f32 v28, -v4, v141, v28
	v_fma_f32 v28, -v5, v142, v28
	v_fma_f32 v28, -v6, v143, v28
	ds_read_b128 v[140:143], v1 offset:40992
	s_waitcnt lgkmcnt(13)
	v_fma_f32 v28, -v7, v144, v28
	v_fma_f32 v28, -v8, v145, v28
	v_fma_f32 v28, -v9, v146, v28
	v_fma_f32 v28, -v10, v147, v28
	ds_read_b128 v[144:147], v1 offset:41008
	s_waitcnt lgkmcnt(13)
	v_fma_f32 v28, -v11, v148, v28
	v_fma_f32 v28, -v12, v149, v28
	v_fma_f32 v28, -v13, v150, v28
	v_fma_f32 v28, -v14, v151, v28
	ds_read_b128 v[148:151], v1 offset:41024
	s_waitcnt lgkmcnt(13)
	v_fma_f32 v28, -v15, v152, v28
	v_fma_f32 v28, -v16, v153, v28
	v_fma_f32 v28, -v18, v154, v28
	v_fma_f32 v28, -v19, v155, v28
	ds_read_b128 v[152:155], v1 offset:41040
	s_waitcnt lgkmcnt(13)
	v_fma_f32 v28, -v20, v100, v28
	v_fma_f32 v28, -v22, v101, v28
	v_fma_f32 v28, -v23, v102, v28
	v_fma_f32 v28, -v24, v103, v28
	ds_read_b128 v[100:103], v1 offset:41216
	s_waitcnt lgkmcnt(13)
; DI void gdnprep_item(const Params& p, int item, unsigned char* ldsb) {
;     ...
;     for (int i = 1; i < 64; ++i) {
;       float a = x[i];
; #pragma unroll
;       for (int j4 = 0; j4 < (i + 3) / 4; ++j4) {
;         f32x4 Lv = *(const f32x4*)(Lm + i * 64 + j4 * 4);
; #pragma unroll
;         for (int e = 0; e < 4; ++e) if (j4 * 4 + e < i) a -= Lv[e] * x[j4 * 4 + e];
;       }
;       x[i] = a;
;       if ((i & 3) == 3) __builtin_amdgcn_sched_barrier(0);
;     }
	v_fma_f32 v28, -v104, v25, v28
	v_fma_f32 v28, -v105, v27, v28
	ds_read_b128 v[104:107], v1 offset:41232
	s_waitcnt lgkmcnt(13)
	v_fma_f32 v30, -v0, v108, v30
	v_fma_f32 v30, -v4, v109, v30
	v_fma_f32 v30, -v5, v110, v30
	v_fma_f32 v30, -v6, v111, v30
	ds_read_b128 v[108:111], v1 offset:41248
	s_waitcnt lgkmcnt(13)
	v_fma_f32 v30, -v7, v112, v30
	v_fma_f32 v30, -v8, v113, v30
	v_fma_f32 v30, -v9, v114, v30
	v_fma_f32 v30, -v10, v115, v30
	ds_read_b128 v[112:115], v1 offset:41264
	s_waitcnt lgkmcnt(13)
	v_fma_f32 v30, -v11, v116, v30
	v_fma_f32 v30, -v12, v117, v30
	v_fma_f32 v30, -v13, v118, v30
	v_fma_f32 v30, -v14, v119, v30
	ds_read_b128 v[116:119], v1 offset:41280
	s_waitcnt lgkmcnt(13)
	v_fma_f32 v30, -v15, v120, v30
	v_fma_f32 v30, -v16, v121, v30
	v_fma_f32 v30, -v18, v122, v30
	v_fma_f32 v30, -v19, v123, v30
	ds_read_b128 v[120:123], v1 offset:41296
	s_waitcnt lgkmcnt(13)
	v_fma_f32 v30, -v20, v124, v30
	v_fma_f32 v30, -v22, v125, v30
	v_fma_f32 v30, -v23, v126, v30
	v_fma_f32 v30, -v24, v127, v30
	ds_read_b128 v[124:127], v1 offset:41312
	s_waitcnt lgkmcnt(13)
	v_fma_f32 v30, -v25, v128, v30
	v_fma_f32 v30, -v129, v27, v30
	v_fma_f32 v30, -v130, v28, v30
	ds_read_b128 v[128:131], v1 offset:41472
	s_waitcnt lgkmcnt(13)
	v_fma_f32 v31, -v0, v132, v31
	v_fma_f32 v31, -v4, v133, v31
	v_fma_f32 v31, -v5, v134, v31
	v_fma_f32 v31, -v6, v135, v31
	ds_read_b128 v[132:135], v1 offset:41488
	s_waitcnt lgkmcnt(13)
	v_fma_f32 v31, -v7, v136, v31
	v_fma_f32 v31, -v8, v137, v31
	v_fma_f32 v31, -v9, v138, v31
	v_fma_f32 v31, -v10, v139, v31
	ds_read_b128 v[136:139], v1 offset:41504
	s_waitcnt lgkmcnt(13)
	v_fma_f32 v31, -v11, v140, v31
	v_fma_f32 v31, -v12, v141, v31
	v_fma_f32 v31, -v13, v142, v31
	v_fma_f32 v31, -v14, v143, v31
	ds_read_b128 v[140:143], v1 offset:41520
	s_waitcnt lgkmcnt(13)
	v_fma_f32 v31, -v15, v144, v31
	v_fma_f32 v31, -v16, v145, v31
	v_fma_f32 v31, -v18, v146, v31
	v_fma_f32 v31, -v19, v147, v31
	ds_read_b128 v[144:147], v1 offset:41536
	s_waitcnt lgkmcnt(13)
	v_fma_f32 v31, -v20, v148, v31
	v_fma_f32 v31, -v22, v149, v31
	v_fma_f32 v31, -v23, v150, v31
	v_fma_f32 v31, -v24, v151, v31
	ds_read_b128 v[148:151], v1 offset:41552
	s_waitcnt lgkmcnt(13)
	v_fma_f32 v31, -v25, v152, v31
	v_fma_f32 v31, -v27, v153, v31
	v_fma_f32 v31, -v154, v28, v31
	v_fma_f32 v31, -v155, v30, v31
	ds_read_b128 v[152:155], v1 offset:41568
	s_waitcnt lgkmcnt(13)
	v_fma_f32 v33, -v0, v100, v33
	v_fma_f32 v33, -v4, v101, v33
	v_fma_f32 v33, -v5, v102, v33
	v_fma_f32 v33, -v6, v103, v33
	ds_read_b128 v[100:103], v1 offset:41728
	s_waitcnt lgkmcnt(13)
	v_fma_f32 v33, -v7, v104, v33
	v_fma_f32 v33, -v8, v105, v33
	v_fma_f32 v33, -v9, v106, v33
	v_fma_f32 v33, -v10, v107, v33
	ds_read_b128 v[104:107], v1 offset:41744
	s_waitcnt lgkmcnt(13)
	v_fma_f32 v33, -v11, v108, v33
	v_fma_f32 v33, -v12, v109, v33
	v_fma_f32 v33, -v13, v110, v33
	v_fma_f32 v33, -v14, v111, v33
	ds_read_b128 v[108:111], v1 offset:41760
	s_waitcnt lgkmcnt(13)
	v_fma_f32 v33, -v15, v112, v33
	v_fma_f32 v33, -v16, v113, v33
	v_fma_f32 v33, -v18, v114, v33
	v_fma_f32 v33, -v19, v115, v33
	ds_read_b128 v[112:115], v1 offset:41776
	s_waitcnt lgkmcnt(13)
	v_fma_f32 v33, -v20, v116, v33
	v_fma_f32 v33, -v22, v117, v33
	v_fma_f32 v33, -v23, v118, v33
	v_fma_f32 v33, -v24, v119, v33
	ds_read_b128 v[116:119], v1 offset:41792
	s_waitcnt lgkmcnt(13)
	v_fma_f32 v33, -v25, v120, v33
	v_fma_f32 v33, -v27, v121, v33
	v_fma_f32 v33, -v28, v122, v33
	v_fma_f32 v33, -v123, v30, v33
	ds_read_b128 v[120:123], v1 offset:41808
	s_waitcnt lgkmcnt(13)
	v_fma_f32 v33, -v124, v31, v33
	ds_read_b128 v[124:127], v1 offset:41824
	s_waitcnt lgkmcnt(13)
	v_fma_f32 v34, -v0, v128, v34
	v_fma_f32 v34, -v4, v129, v34
	v_fma_f32 v34, -v5, v130, v34
	v_fma_f32 v34, -v6, v131, v34
	ds_read_b128 v[128:131], v1 offset:41984
	s_waitcnt lgkmcnt(13)
	v_fma_f32 v34, -v7, v132, v34
	v_fma_f32 v34, -v8, v133, v34
	v_fma_f32 v34, -v9, v134, v34
	v_fma_f32 v34, -v10, v135, v34
	ds_read_b128 v[132:135], v1 offset:42000
	s_waitcnt lgkmcnt(13)
	v_fma_f32 v34, -v11, v136, v34
	v_fma_f32 v34, -v12, v137, v34
	v_fma_f32 v34, -v13, v138, v34
	v_fma_f32 v34, -v14, v139, v34
	ds_read_b128 v[136:139], v1 offset:42016
	s_waitcnt lgkmcnt(13)
	v_fma_f32 v34, -v15, v140, v34
	v_fma_f32 v34, -v16, v141, v34
	v_fma_f32 v34, -v18, v142, v34
	v_fma_f32 v34, -v19, v143, v34
	ds_read_b128 v[140:143], v1 offset:42032
	s_waitcnt lgkmcnt(13)
	v_fma_f32 v34, -v20, v144, v34
	v_fma_f32 v34, -v22, v145, v34
	v_fma_f32 v34, -v23, v146, v34
	v_fma_f32 v34, -v24, v147, v34
	ds_read_b128 v[144:147], v1 offset:42048
	s_waitcnt lgkmcnt(13)
	v_fma_f32 v34, -v25, v148, v34
	v_fma_f32 v34, -v27, v149, v34
	v_fma_f32 v34, -v28, v150, v34
	v_fma_f32 v34, -v30, v151, v34
	ds_read_b128 v[148:151], v1 offset:42064
	s_waitcnt lgkmcnt(13)
	v_fma_f32 v34, -v152, v31, v34
	v_fma_f32 v34, -v153, v33, v34
	ds_read_b128 v[152:155], v1 offset:42080
	s_waitcnt lgkmcnt(13)
	v_fma_f32 v36, -v0, v100, v36
	v_fma_f32 v36, -v4, v101, v36
	v_fma_f32 v36, -v5, v102, v36
	v_fma_f32 v36, -v6, v103, v36
	ds_read_b128 v[100:103], v1 offset:42240
	s_waitcnt lgkmcnt(13)
	v_fma_f32 v36, -v7, v104, v36
	v_fma_f32 v36, -v8, v105, v36
	v_fma_f32 v36, -v9, v106, v36
	v_fma_f32 v36, -v10, v107, v36
	ds_read_b128 v[104:107], v1 offset:42256
	s_waitcnt lgkmcnt(13)
	v_fma_f32 v36, -v11, v108, v36
	v_fma_f32 v36, -v12, v109, v36
	v_fma_f32 v36, -v13, v110, v36
	v_fma_f32 v36, -v14, v111, v36
	ds_read_b128 v[108:111], v1 offset:42272
	s_waitcnt lgkmcnt(13)
	v_fma_f32 v36, -v15, v112, v36
	v_fma_f32 v36, -v16, v113, v36
	v_fma_f32 v36, -v18, v114, v36
	v_fma_f32 v36, -v19, v115, v36
	ds_read_b128 v[112:115], v1 offset:42288
	s_waitcnt lgkmcnt(13)
; DI void gdnprep_item(const Params& p, int item, unsigned char* ldsb) {
;     ...
;     for (int i = 1; i < 64; ++i) {
;       float a = x[i];
; #pragma unroll
;       for (int j4 = 0; j4 < (i + 3) / 4; ++j4) {
;         f32x4 Lv = *(const f32x4*)(Lm + i * 64 + j4 * 4);
; #pragma unroll
;         for (int e = 0; e < 4; ++e) if (j4 * 4 + e < i) a -= Lv[e] * x[j4 * 4 + e];
;       }
;       x[i] = a;
;       if ((i & 3) == 3) __builtin_amdgcn_sched_barrier(0);
;     }
	v_fma_f32 v36, -v20, v116, v36
	v_fma_f32 v36, -v22, v117, v36
	v_fma_f32 v36, -v23, v118, v36
	v_fma_f32 v36, -v24, v119, v36
	ds_read_b128 v[116:119], v1 offset:42304
	s_waitcnt lgkmcnt(13)
	v_fma_f32 v36, -v25, v120, v36
	v_fma_f32 v36, -v27, v121, v36
	v_fma_f32 v36, -v28, v122, v36
	v_fma_f32 v36, -v30, v123, v36
	ds_read_b128 v[120:123], v1 offset:42320
	s_waitcnt lgkmcnt(13)
	v_fma_f32 v36, -v31, v124, v36
	v_fma_f32 v36, -v125, v33, v36
	v_fma_f32 v36, -v126, v34, v36
	ds_read_b128 v[124:127], v1 offset:42336
	s_waitcnt lgkmcnt(13)
	v_fma_f32 v37, -v0, v128, v37
	v_fma_f32 v37, -v4, v129, v37
	v_fma_f32 v37, -v5, v130, v37
	v_fma_f32 v37, -v6, v131, v37
	ds_read_b128 v[128:131], v1 offset:42352
	s_waitcnt lgkmcnt(13)
	v_fma_f32 v37, -v7, v132, v37
	v_fma_f32 v37, -v8, v133, v37
	v_fma_f32 v37, -v9, v134, v37
	v_fma_f32 v37, -v10, v135, v37
	ds_read_b128 v[132:135], v1 offset:42496
	s_waitcnt lgkmcnt(13)
	v_fma_f32 v37, -v11, v136, v37
	v_fma_f32 v37, -v12, v137, v37
	v_fma_f32 v37, -v13, v138, v37
	v_fma_f32 v37, -v14, v139, v37
	ds_read_b128 v[136:139], v1 offset:42512
	s_waitcnt lgkmcnt(13)
	v_fma_f32 v37, -v15, v140, v37
	v_fma_f32 v37, -v16, v141, v37
	v_fma_f32 v37, -v18, v142, v37
	v_fma_f32 v37, -v19, v143, v37
	ds_read_b128 v[140:143], v1 offset:42528
	s_waitcnt lgkmcnt(13)
	v_fma_f32 v37, -v20, v144, v37
	v_fma_f32 v37, -v22, v145, v37
	v_fma_f32 v37, -v23, v146, v37
	v_fma_f32 v37, -v24, v147, v37
	ds_read_b128 v[144:147], v1 offset:42544
	s_waitcnt lgkmcnt(13)
	v_fma_f32 v37, -v25, v148, v37
	v_fma_f32 v37, -v27, v149, v37
	v_fma_f32 v37, -v28, v150, v37
	v_fma_f32 v37, -v30, v151, v37
	ds_read_b128 v[148:151], v1 offset:42560
	s_waitcnt lgkmcnt(13)
	v_fma_f32 v37, -v31, v152, v37
	v_fma_f32 v37, -v33, v153, v37
	v_fma_f32 v37, -v154, v34, v37
	v_fma_f32 v37, -v155, v36, v37
	ds_read_b128 v[152:155], v1 offset:42576
	s_waitcnt lgkmcnt(13)
	v_fma_f32 v39, -v0, v100, v39
	v_fma_f32 v39, -v4, v101, v39
	v_fma_f32 v39, -v5, v102, v39
	v_fma_f32 v39, -v6, v103, v39
	ds_read_b128 v[100:103], v1 offset:42592
	s_waitcnt lgkmcnt(13)
	v_fma_f32 v39, -v7, v104, v39
	v_fma_f32 v39, -v8, v105, v39
	v_fma_f32 v39, -v9, v106, v39
	v_fma_f32 v39, -v10, v107, v39
	ds_read_b128 v[104:107], v1 offset:42608
	s_waitcnt lgkmcnt(13)
	v_fma_f32 v39, -v11, v108, v39
	v_fma_f32 v39, -v12, v109, v39
	v_fma_f32 v39, -v13, v110, v39
	v_fma_f32 v39, -v14, v111, v39
	ds_read_b128 v[108:111], v1 offset:42752
	s_waitcnt lgkmcnt(13)
	v_fma_f32 v39, -v15, v112, v39
	v_fma_f32 v39, -v16, v113, v39
	v_fma_f32 v39, -v18, v114, v39
	v_fma_f32 v39, -v19, v115, v39
	ds_read_b128 v[112:115], v1 offset:42768
	s_waitcnt lgkmcnt(13)
	v_fma_f32 v39, -v20, v116, v39
	v_fma_f32 v39, -v22, v117, v39
	v_fma_f32 v39, -v23, v118, v39
	v_fma_f32 v39, -v24, v119, v39
	ds_read_b128 v[116:119], v1 offset:42784
	s_waitcnt lgkmcnt(13)
	v_fma_f32 v39, -v25, v120, v39
	v_fma_f32 v39, -v27, v121, v39
	v_fma_f32 v39, -v28, v122, v39
	v_fma_f32 v39, -v30, v123, v39
	ds_read_b128 v[120:123], v1 offset:42800
	s_waitcnt lgkmcnt(13)
	v_fma_f32 v39, -v31, v124, v39
	v_fma_f32 v39, -v33, v125, v39
	v_fma_f32 v39, -v34, v126, v39
	v_fma_f32 v39, -v127, v36, v39
	ds_read_b128 v[124:127], v1 offset:42816
	s_waitcnt lgkmcnt(13)
	v_fma_f32 v39, -v128, v37, v39
	ds_read_b128 v[128:131], v1 offset:42832
	s_waitcnt lgkmcnt(13)
	v_fma_f32 v40, -v0, v132, v40
	v_fma_f32 v40, -v4, v133, v40
	v_fma_f32 v40, -v5, v134, v40
	v_fma_f32 v40, -v6, v135, v40
	ds_read_b128 v[132:135], v1 offset:42848
	s_waitcnt lgkmcnt(13)
	v_fma_f32 v40, -v7, v136, v40
	v_fma_f32 v40, -v8, v137, v40
	v_fma_f32 v40, -v9, v138, v40
	v_fma_f32 v40, -v10, v139, v40
	ds_read_b128 v[136:139], v1 offset:42864
	s_waitcnt lgkmcnt(13)
	v_fma_f32 v40, -v11, v140, v40
	v_fma_f32 v40, -v12, v141, v40
	v_fma_f32 v40, -v13, v142, v40
	v_fma_f32 v40, -v14, v143, v40
	ds_read_b128 v[140:143], v1 offset:43008
	s_waitcnt lgkmcnt(13)
	v_fma_f32 v40, -v15, v144, v40
	v_fma_f32 v40, -v16, v145, v40
	v_fma_f32 v40, -v18, v146, v40
	v_fma_f32 v40, -v19, v147, v40
	ds_read_b128 v[144:147], v1 offset:43024
	s_waitcnt lgkmcnt(13)
	v_fma_f32 v40, -v20, v148, v40
	v_fma_f32 v40, -v22, v149, v40
	v_fma_f32 v40, -v23, v150, v40
	v_fma_f32 v40, -v24, v151, v40
	ds_read_b128 v[148:151], v1 offset:43040
	s_waitcnt lgkmcnt(13)
	v_fma_f32 v40, -v25, v152, v40
	v_fma_f32 v40, -v27, v153, v40
	v_fma_f32 v40, -v28, v154, v40
	v_fma_f32 v40, -v30, v155, v40
	ds_read_b128 v[152:155], v1 offset:43056
	s_waitcnt lgkmcnt(13)
	v_fma_f32 v40, -v31, v100, v40
	v_fma_f32 v40, -v33, v101, v40
	v_fma_f32 v40, -v34, v102, v40
	v_fma_f32 v40, -v36, v103, v40
	ds_read_b128 v[100:103], v1 offset:43072
	s_waitcnt lgkmcnt(13)
	v_fma_f32 v40, -v104, v37, v40
	v_fma_f32 v40, -v105, v39, v40
	ds_read_b128 v[104:107], v1 offset:43088
	s_waitcnt lgkmcnt(13)
	v_fma_f32 v44, -v0, v108, v44
	v_fma_f32 v44, -v4, v109, v44
	v_fma_f32 v44, -v5, v110, v44
	v_fma_f32 v44, -v6, v111, v44
	ds_read_b128 v[108:111], v1 offset:43104
	s_waitcnt lgkmcnt(13)
	v_fma_f32 v44, -v7, v112, v44
	v_fma_f32 v44, -v8, v113, v44
	v_fma_f32 v44, -v9, v114, v44
	v_fma_f32 v44, -v10, v115, v44
	ds_read_b128 v[112:115], v1 offset:43120
	s_waitcnt lgkmcnt(13)
	v_fma_f32 v44, -v11, v116, v44
	v_fma_f32 v44, -v12, v117, v44
	v_fma_f32 v44, -v13, v118, v44
	v_fma_f32 v44, -v14, v119, v44
	ds_read_b128 v[116:119], v1 offset:43264
	s_waitcnt lgkmcnt(13)
	v_fma_f32 v44, -v15, v120, v44
	v_fma_f32 v44, -v16, v121, v44
	v_fma_f32 v44, -v18, v122, v44
	v_fma_f32 v44, -v19, v123, v44
	ds_read_b128 v[120:123], v1 offset:43280
	s_waitcnt lgkmcnt(13)
; DI void gdnprep_item(const Params& p, int item, unsigned char* ldsb) {
;     ...
;     for (int i = 1; i < 64; ++i) {
;       float a = x[i];
; #pragma unroll
;       for (int j4 = 0; j4 < (i + 3) / 4; ++j4) {
;         f32x4 Lv = *(const f32x4*)(Lm + i * 64 + j4 * 4);
; #pragma unroll
;         for (int e = 0; e < 4; ++e) if (j4 * 4 + e < i) a -= Lv[e] * x[j4 * 4 + e];
;       }
;       x[i] = a;
;       if ((i & 3) == 3) __builtin_amdgcn_sched_barrier(0);
;     }
	v_fma_f32 v44, -v20, v124, v44
	v_fma_f32 v44, -v22, v125, v44
	v_fma_f32 v44, -v23, v126, v44
	v_fma_f32 v44, -v24, v127, v44
	ds_read_b128 v[124:127], v1 offset:43296
	s_waitcnt lgkmcnt(13)
	v_fma_f32 v44, -v25, v128, v44
	v_fma_f32 v44, -v27, v129, v44
	v_fma_f32 v44, -v28, v130, v44
	v_fma_f32 v44, -v30, v131, v44
	ds_read_b128 v[128:131], v1 offset:43312
	s_waitcnt lgkmcnt(13)
	v_fma_f32 v44, -v31, v132, v44
	v_fma_f32 v44, -v33, v133, v44
	v_fma_f32 v44, -v34, v134, v44
	v_fma_f32 v44, -v36, v135, v44
	ds_read_b128 v[132:135], v1 offset:43328
	s_waitcnt lgkmcnt(13)
	v_fma_f32 v44, -v37, v136, v44
	v_fma_f32 v44, -v137, v39, v44
	v_fma_f32 v44, -v138, v40, v44
	ds_read_b128 v[136:139], v1 offset:43344
	s_waitcnt lgkmcnt(13)
	v_fma_f32 v46, -v0, v140, v46
	v_fma_f32 v46, -v4, v141, v46
	v_fma_f32 v46, -v5, v142, v46
	v_fma_f32 v46, -v6, v143, v46
	ds_read_b128 v[140:143], v1 offset:43360
	s_waitcnt lgkmcnt(13)
	v_fma_f32 v46, -v7, v144, v46
	v_fma_f32 v46, -v8, v145, v46
	v_fma_f32 v46, -v9, v146, v46
	v_fma_f32 v46, -v10, v147, v46
	ds_read_b128 v[144:147], v1 offset:43376
	s_waitcnt lgkmcnt(13)
	v_fma_f32 v46, -v11, v148, v46
	v_fma_f32 v46, -v12, v149, v46
	v_fma_f32 v46, -v13, v150, v46
	v_fma_f32 v46, -v14, v151, v46
	ds_read_b128 v[148:151], v1 offset:43392
	s_waitcnt lgkmcnt(13)
	v_fma_f32 v46, -v15, v152, v46
	v_fma_f32 v46, -v16, v153, v46
	v_fma_f32 v46, -v18, v154, v46
	v_fma_f32 v46, -v19, v155, v46
	ds_read_b128 v[152:155], v1 offset:43520
	s_waitcnt lgkmcnt(13)
	v_fma_f32 v46, -v20, v100, v46
	v_fma_f32 v46, -v22, v101, v46
	v_fma_f32 v46, -v23, v102, v46
	v_fma_f32 v46, -v24, v103, v46
	ds_read_b128 v[100:103], v1 offset:43536
	s_waitcnt lgkmcnt(13)
	v_fma_f32 v46, -v25, v104, v46
	v_fma_f32 v46, -v27, v105, v46
	v_fma_f32 v46, -v28, v106, v46
	v_fma_f32 v46, -v30, v107, v46
	ds_read_b128 v[104:107], v1 offset:43552
	s_waitcnt lgkmcnt(13)
	v_fma_f32 v46, -v31, v108, v46
	v_fma_f32 v46, -v33, v109, v46
	v_fma_f32 v46, -v34, v110, v46
	v_fma_f32 v46, -v36, v111, v46
	ds_read_b128 v[108:111], v1 offset:43568
	s_waitcnt lgkmcnt(13)
	v_fma_f32 v46, -v37, v112, v46
	v_fma_f32 v46, -v39, v113, v46
	v_fma_f32 v46, -v114, v40, v46
	v_fma_f32 v46, -v115, v44, v46
	ds_read_b128 v[112:115], v1 offset:43584
	s_waitcnt lgkmcnt(13)
	v_fma_f32 v47, -v0, v116, v47
	v_fma_f32 v47, -v4, v117, v47
	v_fma_f32 v47, -v5, v118, v47
	v_fma_f32 v47, -v6, v119, v47
	ds_read_b128 v[116:119], v1 offset:43600
	s_waitcnt lgkmcnt(13)
	v_fma_f32 v47, -v7, v120, v47
	v_fma_f32 v47, -v8, v121, v47
	v_fma_f32 v47, -v9, v122, v47
	v_fma_f32 v47, -v10, v123, v47
	ds_read_b128 v[120:123], v1 offset:43616
	s_waitcnt lgkmcnt(13)
	v_fma_f32 v47, -v11, v124, v47
	v_fma_f32 v47, -v12, v125, v47
	v_fma_f32 v47, -v13, v126, v47
	v_fma_f32 v47, -v14, v127, v47
	ds_read_b128 v[124:127], v1 offset:43632
	s_waitcnt lgkmcnt(13)
	v_fma_f32 v47, -v15, v128, v47
	v_fma_f32 v47, -v16, v129, v47
	v_fma_f32 v47, -v18, v130, v47
	v_fma_f32 v47, -v19, v131, v47
	ds_read_b128 v[128:131], v1 offset:43648
	s_waitcnt lgkmcnt(13)
	v_fma_f32 v47, -v20, v132, v47
	v_fma_f32 v47, -v22, v133, v47
	v_fma_f32 v47, -v23, v134, v47
	v_fma_f32 v47, -v24, v135, v47
	ds_read_b128 v[132:135], v1 offset:43776
	s_waitcnt lgkmcnt(13)
	v_fma_f32 v47, -v25, v136, v47
	v_fma_f32 v47, -v27, v137, v47
	v_fma_f32 v47, -v28, v138, v47
	v_fma_f32 v47, -v30, v139, v47
	ds_read_b128 v[136:139], v1 offset:43792
	s_waitcnt lgkmcnt(13)
	v_fma_f32 v47, -v31, v140, v47
	v_fma_f32 v47, -v33, v141, v47
	v_fma_f32 v47, -v34, v142, v47
	v_fma_f32 v47, -v36, v143, v47
	ds_read_b128 v[140:143], v1 offset:43808
	s_waitcnt lgkmcnt(13)
	v_fma_f32 v47, -v37, v144, v47
	v_fma_f32 v47, -v39, v145, v47
	v_fma_f32 v47, -v40, v146, v47
	v_fma_f32 v47, -v147, v44, v47
	ds_read_b128 v[144:147], v1 offset:43824
	s_waitcnt lgkmcnt(13)
	v_fma_f32 v47, -v148, v46, v47
	ds_read_b128 v[148:151], v1 offset:43840
	s_waitcnt lgkmcnt(13)
	v_fma_f32 v49, -v0, v152, v49
	v_fma_f32 v49, -v4, v153, v49
	v_fma_f32 v49, -v5, v154, v49
	v_fma_f32 v49, -v6, v155, v49
	ds_read_b128 v[152:155], v1 offset:43856
	s_waitcnt lgkmcnt(13)
	v_fma_f32 v49, -v7, v100, v49
	v_fma_f32 v49, -v8, v101, v49
	v_fma_f32 v49, -v9, v102, v49
	v_fma_f32 v49, -v10, v103, v49
	ds_read_b128 v[100:103], v1 offset:43872
	s_waitcnt lgkmcnt(13)
	v_fma_f32 v49, -v11, v104, v49
	v_fma_f32 v49, -v12, v105, v49
	v_fma_f32 v49, -v13, v106, v49
	v_fma_f32 v49, -v14, v107, v49
	ds_read_b128 v[104:107], v1 offset:43888
	s_waitcnt lgkmcnt(13)
	v_fma_f32 v49, -v15, v108, v49
	v_fma_f32 v49, -v16, v109, v49
	v_fma_f32 v49, -v18, v110, v49
	v_fma_f32 v49, -v19, v111, v49
	ds_read_b128 v[108:111], v1 offset:43904
	s_waitcnt lgkmcnt(13)
	v_fma_f32 v49, -v20, v112, v49
	v_fma_f32 v49, -v22, v113, v49
	v_fma_f32 v49, -v23, v114, v49
	v_fma_f32 v49, -v24, v115, v49
	ds_read_b128 v[112:115], v1 offset:44032
	s_waitcnt lgkmcnt(13)
	v_fma_f32 v49, -v25, v116, v49
	v_fma_f32 v49, -v27, v117, v49
	v_fma_f32 v49, -v28, v118, v49
	v_fma_f32 v49, -v30, v119, v49
	ds_read_b128 v[116:119], v1 offset:44048
	s_waitcnt lgkmcnt(13)
	v_fma_f32 v49, -v31, v120, v49
	v_fma_f32 v49, -v33, v121, v49
	v_fma_f32 v49, -v34, v122, v49
	v_fma_f32 v49, -v36, v123, v49
	ds_read_b128 v[120:123], v1 offset:44064
	s_waitcnt lgkmcnt(13)
	v_fma_f32 v49, -v37, v124, v49
	v_fma_f32 v49, -v39, v125, v49
	v_fma_f32 v49, -v40, v126, v49
	v_fma_f32 v49, -v44, v127, v49
	ds_read_b128 v[124:127], v1 offset:44080
	s_waitcnt lgkmcnt(13)
	v_fma_f32 v49, -v128, v46, v49
	v_fma_f32 v49, -v129, v47, v49
	ds_read_b128 v[128:131], v1 offset:44096
	s_waitcnt lgkmcnt(13)
; DI void gdnprep_item(const Params& p, int item, unsigned char* ldsb) {
;     ...
;     for (int i = 1; i < 64; ++i) {
;       float a = x[i];
; #pragma unroll
;       for (int j4 = 0; j4 < (i + 3) / 4; ++j4) {
;         f32x4 Lv = *(const f32x4*)(Lm + i * 64 + j4 * 4);
; #pragma unroll
;         for (int e = 0; e < 4; ++e) if (j4 * 4 + e < i) a -= Lv[e] * x[j4 * 4 + e];
;       }
;       x[i] = a;
;       if ((i & 3) == 3) __builtin_amdgcn_sched_barrier(0);
;     }
	v_fma_f32 v51, -v0, v132, v51
	v_fma_f32 v51, -v4, v133, v51
	v_fma_f32 v51, -v5, v134, v51
	v_fma_f32 v51, -v6, v135, v51
	ds_read_b128 v[132:135], v1 offset:44112
	s_waitcnt lgkmcnt(13)
	v_fma_f32 v51, -v7, v136, v51
	v_fma_f32 v51, -v8, v137, v51
	v_fma_f32 v51, -v9, v138, v51
	v_fma_f32 v51, -v10, v139, v51
	ds_read_b128 v[136:139], v1 offset:44128
	s_waitcnt lgkmcnt(13)
	v_fma_f32 v51, -v11, v140, v51
	v_fma_f32 v51, -v12, v141, v51
	v_fma_f32 v51, -v13, v142, v51
	v_fma_f32 v51, -v14, v143, v51
	ds_read_b128 v[140:143], v1 offset:44144
	s_waitcnt lgkmcnt(13)
	v_fma_f32 v51, -v15, v144, v51
	v_fma_f32 v51, -v16, v145, v51
	v_fma_f32 v51, -v18, v146, v51
	v_fma_f32 v51, -v19, v147, v51
	ds_read_b128 v[144:147], v1 offset:44160
	s_waitcnt lgkmcnt(13)
	v_fma_f32 v51, -v20, v148, v51
	v_fma_f32 v51, -v22, v149, v51
	v_fma_f32 v51, -v23, v150, v51
	v_fma_f32 v51, -v24, v151, v51
	ds_read_b128 v[148:151], v1 offset:44288
	s_waitcnt lgkmcnt(13)
	v_fma_f32 v51, -v25, v152, v51
	v_fma_f32 v51, -v27, v153, v51
	v_fma_f32 v51, -v28, v154, v51
	v_fma_f32 v51, -v30, v155, v51
	ds_read_b128 v[152:155], v1 offset:44304
	s_waitcnt lgkmcnt(13)
	v_fma_f32 v51, -v31, v100, v51
	v_fma_f32 v51, -v33, v101, v51
	v_fma_f32 v51, -v34, v102, v51
	v_fma_f32 v51, -v36, v103, v51
	ds_read_b128 v[100:103], v1 offset:44320
	s_waitcnt lgkmcnt(13)
	v_fma_f32 v51, -v37, v104, v51
	v_fma_f32 v51, -v39, v105, v51
	v_fma_f32 v51, -v40, v106, v51
	v_fma_f32 v51, -v44, v107, v51
	ds_read_b128 v[104:107], v1 offset:44336
	s_waitcnt lgkmcnt(13)
	v_fma_f32 v51, -v46, v108, v51
	v_fma_f32 v51, -v109, v47, v51
	v_fma_f32 v51, -v110, v49, v51
	ds_read_b128 v[108:111], v1 offset:44352
	s_waitcnt lgkmcnt(13)
	v_fma_f32 v58, -v0, v112, v58
	v_fma_f32 v58, -v4, v113, v58
	v_fma_f32 v58, -v5, v114, v58
	v_fma_f32 v58, -v6, v115, v58
	ds_read_b128 v[112:115], v1 offset:44368
	s_waitcnt lgkmcnt(13)
	v_fma_f32 v58, -v7, v116, v58
	v_fma_f32 v58, -v8, v117, v58
	v_fma_f32 v58, -v9, v118, v58
	v_fma_f32 v58, -v10, v119, v58
	ds_read_b128 v[116:119], v1 offset:44384
	s_waitcnt lgkmcnt(13)
	v_fma_f32 v58, -v11, v120, v58
	v_fma_f32 v58, -v12, v121, v58
	v_fma_f32 v58, -v13, v122, v58
	v_fma_f32 v58, -v14, v123, v58
	ds_read_b128 v[120:123], v1 offset:44400
	s_waitcnt lgkmcnt(13)
	v_fma_f32 v58, -v15, v124, v58
	v_fma_f32 v58, -v16, v125, v58
	v_fma_f32 v58, -v18, v126, v58
	v_fma_f32 v58, -v19, v127, v58
	ds_read_b128 v[124:127], v1 offset:44416
	s_waitcnt lgkmcnt(13)
	v_fma_f32 v58, -v20, v128, v58
	v_fma_f32 v58, -v22, v129, v58
	v_fma_f32 v58, -v23, v130, v58
	v_fma_f32 v58, -v24, v131, v58
	ds_read_b128 v[128:131], v1 offset:44432
	s_waitcnt lgkmcnt(13)
	v_fma_f32 v58, -v25, v132, v58
	v_fma_f32 v58, -v27, v133, v58
	v_fma_f32 v58, -v28, v134, v58
	v_fma_f32 v58, -v30, v135, v58
	ds_read_b128 v[132:135], v1 offset:44544
	s_waitcnt lgkmcnt(13)
	v_fma_f32 v58, -v31, v136, v58
	v_fma_f32 v58, -v33, v137, v58
	v_fma_f32 v58, -v34, v138, v58
	v_fma_f32 v58, -v36, v139, v58
	ds_read_b128 v[136:139], v1 offset:44560
	s_waitcnt lgkmcnt(13)
	v_fma_f32 v58, -v37, v140, v58
	v_fma_f32 v58, -v39, v141, v58
	v_fma_f32 v58, -v40, v142, v58
	v_fma_f32 v58, -v44, v143, v58
	ds_read_b128 v[140:143], v1 offset:44576
	s_waitcnt lgkmcnt(13)
	v_fma_f32 v58, -v46, v144, v58
	v_fma_f32 v58, -v47, v145, v58
	v_fma_f32 v58, -v146, v49, v58
	v_fma_f32 v58, -v147, v51, v58
	ds_read_b128 v[144:147], v1 offset:44592
	s_waitcnt lgkmcnt(13)
	v_fma_f32 v59, -v0, v148, v59
	v_fma_f32 v59, -v4, v149, v59
	v_fma_f32 v59, -v5, v150, v59
	v_fma_f32 v59, -v6, v151, v59
	ds_read_b128 v[148:151], v1 offset:44608
	s_waitcnt lgkmcnt(13)
	v_fma_f32 v59, -v7, v152, v59
	v_fma_f32 v59, -v8, v153, v59
	v_fma_f32 v59, -v9, v154, v59
	v_fma_f32 v59, -v10, v155, v59
	ds_read_b128 v[152:155], v1 offset:44624
	s_waitcnt lgkmcnt(13)
	v_fma_f32 v59, -v11, v100, v59
	v_fma_f32 v59, -v12, v101, v59
	v_fma_f32 v59, -v13, v102, v59
	v_fma_f32 v59, -v14, v103, v59
	ds_read_b128 v[100:103], v1 offset:44640
	s_waitcnt lgkmcnt(13)
	v_fma_f32 v59, -v15, v104, v59
	v_fma_f32 v59, -v16, v105, v59
	v_fma_f32 v59, -v18, v106, v59
	v_fma_f32 v59, -v19, v107, v59
	ds_read_b128 v[104:107], v1 offset:44656
	s_waitcnt lgkmcnt(13)
	v_fma_f32 v59, -v20, v108, v59
	v_fma_f32 v59, -v22, v109, v59
	v_fma_f32 v59, -v23, v110, v59
	v_fma_f32 v59, -v24, v111, v59
	ds_read_b128 v[108:111], v1 offset:44672
	s_waitcnt lgkmcnt(13)
	v_fma_f32 v59, -v25, v112, v59
	v_fma_f32 v59, -v27, v113, v59
	v_fma_f32 v59, -v28, v114, v59
	v_fma_f32 v59, -v30, v115, v59
	ds_read_b128 v[112:115], v1 offset:44688
	s_waitcnt lgkmcnt(13)
	v_fma_f32 v59, -v31, v116, v59
	v_fma_f32 v59, -v33, v117, v59
	v_fma_f32 v59, -v34, v118, v59
	v_fma_f32 v59, -v36, v119, v59
	ds_read_b128 v[116:119], v1 offset:44800
	s_waitcnt lgkmcnt(13)
	v_fma_f32 v59, -v37, v120, v59
	v_fma_f32 v59, -v39, v121, v59
	v_fma_f32 v59, -v40, v122, v59
	v_fma_f32 v59, -v44, v123, v59
	ds_read_b128 v[120:123], v1 offset:44816
	s_waitcnt lgkmcnt(13)
	v_fma_f32 v59, -v46, v124, v59
	v_fma_f32 v59, -v47, v125, v59
	v_fma_f32 v59, -v49, v126, v59
	v_fma_f32 v59, -v127, v51, v59
	ds_read_b128 v[124:127], v1 offset:44832
	s_waitcnt lgkmcnt(13)
	v_fma_f32 v59, -v128, v58, v59
	ds_read_b128 v[128:131], v1 offset:44848
	s_waitcnt lgkmcnt(13)
	v_fma_f32 v61, -v0, v132, v61
	v_fma_f32 v61, -v4, v133, v61
	v_fma_f32 v61, -v5, v134, v61
	v_fma_f32 v61, -v6, v135, v61
	ds_read_b128 v[132:135], v1 offset:44864
	s_waitcnt lgkmcnt(13)
	v_fma_f32 v61, -v7, v136, v61
	v_fma_f32 v61, -v8, v137, v61
	v_fma_f32 v61, -v9, v138, v61
	v_fma_f32 v61, -v10, v139, v61
	ds_read_b128 v[136:139], v1 offset:44880
	s_waitcnt lgkmcnt(13)
; DI void gdnprep_item(const Params& p, int item, unsigned char* ldsb) {
;     ...
;     for (int i = 1; i < 64; ++i) {
;       float a = x[i];
; #pragma unroll
;       for (int j4 = 0; j4 < (i + 3) / 4; ++j4) {
;         f32x4 Lv = *(const f32x4*)(Lm + i * 64 + j4 * 4);
; #pragma unroll
;         for (int e = 0; e < 4; ++e) if (j4 * 4 + e < i) a -= Lv[e] * x[j4 * 4 + e];
;       }
;       x[i] = a;
;       if ((i & 3) == 3) __builtin_amdgcn_sched_barrier(0);
;     }
	v_fma_f32 v61, -v11, v140, v61
	v_fma_f32 v61, -v12, v141, v61
	v_fma_f32 v61, -v13, v142, v61
	v_fma_f32 v61, -v14, v143, v61
	ds_read_b128 v[140:143], v1 offset:44896
	s_waitcnt lgkmcnt(13)
	v_fma_f32 v61, -v15, v144, v61
	v_fma_f32 v61, -v16, v145, v61
	v_fma_f32 v61, -v18, v146, v61
	v_fma_f32 v61, -v19, v147, v61
	ds_read_b128 v[144:147], v1 offset:44912
	s_waitcnt lgkmcnt(13)
	v_fma_f32 v61, -v20, v148, v61
	v_fma_f32 v61, -v22, v149, v61
	v_fma_f32 v61, -v23, v150, v61
	v_fma_f32 v61, -v24, v151, v61
	ds_read_b128 v[148:151], v1 offset:44928
	s_waitcnt lgkmcnt(13)
	v_fma_f32 v61, -v25, v152, v61
	v_fma_f32 v61, -v27, v153, v61
	v_fma_f32 v61, -v28, v154, v61
	v_fma_f32 v61, -v30, v155, v61
	ds_read_b128 v[152:155], v1 offset:44944
	s_waitcnt lgkmcnt(13)
	v_fma_f32 v61, -v31, v100, v61
	v_fma_f32 v61, -v33, v101, v61
	v_fma_f32 v61, -v34, v102, v61
	v_fma_f32 v61, -v36, v103, v61
	ds_read_b128 v[100:103], v1 offset:45056
	s_waitcnt lgkmcnt(13)
	v_fma_f32 v61, -v37, v104, v61
	v_fma_f32 v61, -v39, v105, v61
	v_fma_f32 v61, -v40, v106, v61
	v_fma_f32 v61, -v44, v107, v61
	ds_read_b128 v[104:107], v1 offset:45072
	s_waitcnt lgkmcnt(13)
	v_fma_f32 v61, -v46, v108, v61
	v_fma_f32 v61, -v47, v109, v61
	v_fma_f32 v61, -v49, v110, v61
	v_fma_f32 v61, -v51, v111, v61
	ds_read_b128 v[108:111], v1 offset:45088
	s_waitcnt lgkmcnt(13)
	v_fma_f32 v61, -v112, v58, v61
	v_fma_f32 v61, -v113, v59, v61
	ds_read_b128 v[112:115], v1 offset:45104
	s_waitcnt lgkmcnt(13)
	v_fma_f32 v63, -v0, v116, v63
	v_fma_f32 v63, -v4, v117, v63
	v_fma_f32 v63, -v5, v118, v63
	v_fma_f32 v63, -v6, v119, v63
	ds_read_b128 v[116:119], v1 offset:45120
	s_waitcnt lgkmcnt(13)
	v_fma_f32 v63, -v7, v120, v63
	v_fma_f32 v63, -v8, v121, v63
	v_fma_f32 v63, -v9, v122, v63
	v_fma_f32 v63, -v10, v123, v63
	ds_read_b128 v[120:123], v1 offset:45136
	s_waitcnt lgkmcnt(13)
	v_fma_f32 v63, -v11, v124, v63
	v_fma_f32 v63, -v12, v125, v63
	v_fma_f32 v63, -v13, v126, v63
	v_fma_f32 v63, -v14, v127, v63
	ds_read_b128 v[124:127], v1 offset:45152
	s_waitcnt lgkmcnt(13)
	v_fma_f32 v63, -v15, v128, v63
	v_fma_f32 v63, -v16, v129, v63
	v_fma_f32 v63, -v18, v130, v63
	v_fma_f32 v63, -v19, v131, v63
	ds_read_b128 v[128:131], v1 offset:45168
	s_waitcnt lgkmcnt(13)
	v_fma_f32 v63, -v20, v132, v63
	v_fma_f32 v63, -v22, v133, v63
	v_fma_f32 v63, -v23, v134, v63
	v_fma_f32 v63, -v24, v135, v63
	ds_read_b128 v[132:135], v1 offset:45184
	s_waitcnt lgkmcnt(13)
	v_fma_f32 v63, -v25, v136, v63
	v_fma_f32 v63, -v27, v137, v63
	v_fma_f32 v63, -v28, v138, v63
	v_fma_f32 v63, -v30, v139, v63
	ds_read_b128 v[136:139], v1 offset:45200
	s_waitcnt lgkmcnt(13)
	v_fma_f32 v63, -v31, v140, v63
	v_fma_f32 v63, -v33, v141, v63
	v_fma_f32 v63, -v34, v142, v63
	v_fma_f32 v63, -v36, v143, v63
	ds_read_b128 v[140:143], v1 offset:45312
	s_waitcnt lgkmcnt(13)
	v_fma_f32 v63, -v37, v144, v63
	v_fma_f32 v63, -v39, v145, v63
	v_fma_f32 v63, -v40, v146, v63
	v_fma_f32 v63, -v44, v147, v63
	ds_read_b128 v[144:147], v1 offset:45328
	s_waitcnt lgkmcnt(13)
	v_fma_f32 v63, -v46, v148, v63
	v_fma_f32 v63, -v47, v149, v63
	v_fma_f32 v63, -v49, v150, v63
	v_fma_f32 v63, -v51, v151, v63
	ds_read_b128 v[148:151], v1 offset:45344
	s_waitcnt lgkmcnt(13)
	v_fma_f32 v63, -v58, v152, v63
	v_fma_f32 v63, -v153, v59, v63
	v_fma_f32 v63, -v154, v61, v63
	ds_read_b128 v[152:155], v1 offset:45360
	s_waitcnt lgkmcnt(13)
	v_fma_f32 v65, -v0, v100, v65
	v_fma_f32 v65, -v4, v101, v65
	v_fma_f32 v65, -v5, v102, v65
	v_fma_f32 v65, -v6, v103, v65
	ds_read_b128 v[100:103], v1 offset:45376
	s_waitcnt lgkmcnt(13)
	v_fma_f32 v65, -v7, v104, v65
	v_fma_f32 v65, -v8, v105, v65
	v_fma_f32 v65, -v9, v106, v65
	v_fma_f32 v65, -v10, v107, v65
	ds_read_b128 v[104:107], v1 offset:45392
	s_waitcnt lgkmcnt(13)
	v_fma_f32 v65, -v11, v108, v65
	v_fma_f32 v65, -v12, v109, v65
	v_fma_f32 v65, -v13, v110, v65
	v_fma_f32 v65, -v14, v111, v65
	ds_read_b128 v[108:111], v1 offset:45408
	s_waitcnt lgkmcnt(13)
	v_fma_f32 v65, -v15, v112, v65
	v_fma_f32 v65, -v16, v113, v65
	v_fma_f32 v65, -v18, v114, v65
	v_fma_f32 v65, -v19, v115, v65
	ds_read_b128 v[112:115], v1 offset:45424
	s_waitcnt lgkmcnt(13)
	v_fma_f32 v65, -v20, v116, v65
	v_fma_f32 v65, -v22, v117, v65
	v_fma_f32 v65, -v23, v118, v65
	v_fma_f32 v65, -v24, v119, v65
	ds_read_b128 v[116:119], v1 offset:45440
	s_waitcnt lgkmcnt(13)
	v_fma_f32 v65, -v25, v120, v65
	v_fma_f32 v65, -v27, v121, v65
	v_fma_f32 v65, -v28, v122, v65
	v_fma_f32 v65, -v30, v123, v65
	ds_read_b128 v[120:123], v1 offset:45456
	s_waitcnt lgkmcnt(13)
	v_fma_f32 v65, -v31, v124, v65
	v_fma_f32 v65, -v33, v125, v65
	v_fma_f32 v65, -v34, v126, v65
	v_fma_f32 v65, -v36, v127, v65
	ds_read_b128 v[124:127], v1 offset:45472
	s_waitcnt lgkmcnt(13)
	v_fma_f32 v65, -v37, v128, v65
	v_fma_f32 v65, -v39, v129, v65
	v_fma_f32 v65, -v40, v130, v65
	v_fma_f32 v65, -v44, v131, v65
	ds_read_b128 v[128:131], v1 offset:45568
	s_waitcnt lgkmcnt(13)
	v_fma_f32 v65, -v46, v132, v65
	v_fma_f32 v65, -v47, v133, v65
	v_fma_f32 v65, -v49, v134, v65
	v_fma_f32 v65, -v51, v135, v65
	ds_read_b128 v[132:135], v1 offset:45584
	s_waitcnt lgkmcnt(13)
	v_fma_f32 v65, -v58, v136, v65
	v_fma_f32 v65, -v59, v137, v65
	v_fma_f32 v65, -v138, v61, v65
	v_fma_f32 v65, -v139, v63, v65
	ds_read_b128 v[136:139], v1 offset:45600
	s_waitcnt lgkmcnt(13)
	v_fma_f32 v67, -v0, v140, v67
	v_fma_f32 v67, -v4, v141, v67
	v_fma_f32 v67, -v5, v142, v67
	v_fma_f32 v67, -v6, v143, v67
	ds_read_b128 v[140:143], v1 offset:45616
	s_waitcnt lgkmcnt(13)
	v_fma_f32 v67, -v7, v144, v67
	v_fma_f32 v67, -v8, v145, v67
	v_fma_f32 v67, -v9, v146, v67
	v_fma_f32 v67, -v10, v147, v67
	ds_read_b128 v[144:147], v1 offset:45632
	s_waitcnt lgkmcnt(13)
; DI void gdnprep_item(const Params& p, int item, unsigned char* ldsb) {
;     ...
;     for (int i = 1; i < 64; ++i) {
;       float a = x[i];
; #pragma unroll
;       for (int j4 = 0; j4 < (i + 3) / 4; ++j4) {
;         f32x4 Lv = *(const f32x4*)(Lm + i * 64 + j4 * 4);
; #pragma unroll
;         for (int e = 0; e < 4; ++e) if (j4 * 4 + e < i) a -= Lv[e] * x[j4 * 4 + e];
;       }
;       x[i] = a;
;       if ((i & 3) == 3) __builtin_amdgcn_sched_barrier(0);
;     }
	v_fma_f32 v67, -v11, v148, v67
	v_fma_f32 v67, -v12, v149, v67
	v_fma_f32 v67, -v13, v150, v67
	v_fma_f32 v67, -v14, v151, v67
	ds_read_b128 v[148:151], v1 offset:45648
	s_waitcnt lgkmcnt(13)
	v_fma_f32 v67, -v15, v152, v67
	v_fma_f32 v67, -v16, v153, v67
	v_fma_f32 v67, -v18, v154, v67
	v_fma_f32 v67, -v19, v155, v67
	ds_read_b128 v[152:155], v1 offset:45664
	s_waitcnt lgkmcnt(13)
	v_fma_f32 v67, -v20, v100, v67
	v_fma_f32 v67, -v22, v101, v67
	v_fma_f32 v67, -v23, v102, v67
	v_fma_f32 v67, -v24, v103, v67
	ds_read_b128 v[100:103], v1 offset:45680
	s_waitcnt lgkmcnt(13)
	v_fma_f32 v67, -v25, v104, v67
	v_fma_f32 v67, -v27, v105, v67
	v_fma_f32 v67, -v28, v106, v67
	v_fma_f32 v67, -v30, v107, v67
	ds_read_b128 v[104:107], v1 offset:45696
	s_waitcnt lgkmcnt(13)
	v_fma_f32 v67, -v31, v108, v67
	v_fma_f32 v67, -v33, v109, v67
	v_fma_f32 v67, -v34, v110, v67
	v_fma_f32 v67, -v36, v111, v67
	ds_read_b128 v[108:111], v1 offset:45712
	s_waitcnt lgkmcnt(13)
	v_fma_f32 v67, -v37, v112, v67
	v_fma_f32 v67, -v39, v113, v67
	v_fma_f32 v67, -v40, v114, v67
	v_fma_f32 v67, -v44, v115, v67
	ds_read_b128 v[112:115], v1 offset:45728
	s_waitcnt lgkmcnt(13)
	v_fma_f32 v67, -v46, v116, v67
	v_fma_f32 v67, -v47, v117, v67
	v_fma_f32 v67, -v49, v118, v67
	v_fma_f32 v67, -v51, v119, v67
	ds_read_b128 v[116:119], v1 offset:45824
	s_waitcnt lgkmcnt(13)
	v_fma_f32 v67, -v58, v120, v67
	v_fma_f32 v67, -v59, v121, v67
	v_fma_f32 v67, -v61, v122, v67
	v_fma_f32 v67, -v123, v63, v67
	ds_read_b128 v[120:123], v1 offset:45840
	s_waitcnt lgkmcnt(13)
	v_fma_f32 v67, -v124, v65, v67
	ds_read_b128 v[124:127], v1 offset:45856
	s_waitcnt lgkmcnt(13)
	v_fma_f32 v69, -v0, v128, v69
	v_fma_f32 v69, -v4, v129, v69
	v_fma_f32 v69, -v5, v130, v69
	v_fma_f32 v69, -v6, v131, v69
	ds_read_b128 v[128:131], v1 offset:45872
	s_waitcnt lgkmcnt(13)
	v_fma_f32 v69, -v7, v132, v69
	v_fma_f32 v69, -v8, v133, v69
	v_fma_f32 v69, -v9, v134, v69
	v_fma_f32 v69, -v10, v135, v69
	ds_read_b128 v[132:135], v1 offset:45888
	s_waitcnt lgkmcnt(13)
	v_fma_f32 v69, -v11, v136, v69
	v_fma_f32 v69, -v12, v137, v69
	v_fma_f32 v69, -v13, v138, v69
	v_fma_f32 v69, -v14, v139, v69
	ds_read_b128 v[136:139], v1 offset:45904
	s_waitcnt lgkmcnt(13)
	v_fma_f32 v69, -v15, v140, v69
	v_fma_f32 v69, -v16, v141, v69
	v_fma_f32 v69, -v18, v142, v69
	v_fma_f32 v69, -v19, v143, v69
	ds_read_b128 v[140:143], v1 offset:45920
	s_waitcnt lgkmcnt(13)
	v_fma_f32 v69, -v20, v144, v69
	v_fma_f32 v69, -v22, v145, v69
	v_fma_f32 v69, -v23, v146, v69
	v_fma_f32 v69, -v24, v147, v69
	ds_read_b128 v[144:147], v1 offset:45936
	s_waitcnt lgkmcnt(13)
	v_fma_f32 v69, -v25, v148, v69
	v_fma_f32 v69, -v27, v149, v69
	v_fma_f32 v69, -v28, v150, v69
	v_fma_f32 v69, -v30, v151, v69
	ds_read_b128 v[148:151], v1 offset:45952
	s_waitcnt lgkmcnt(13)
	v_fma_f32 v69, -v31, v152, v69
	v_fma_f32 v69, -v33, v153, v69
	v_fma_f32 v69, -v34, v154, v69
	v_fma_f32 v69, -v36, v155, v69
	ds_read_b128 v[152:155], v1 offset:45968
	s_waitcnt lgkmcnt(13)
	v_fma_f32 v69, -v37, v100, v69
	v_fma_f32 v69, -v39, v101, v69
	v_fma_f32 v69, -v40, v102, v69
	v_fma_f32 v69, -v44, v103, v69
	ds_read_b128 v[100:103], v1 offset:45984
	s_waitcnt lgkmcnt(13)
	v_fma_f32 v69, -v46, v104, v69
	v_fma_f32 v69, -v47, v105, v69
	v_fma_f32 v69, -v49, v106, v69
	v_fma_f32 v69, -v51, v107, v69
	ds_read_b128 v[104:107], v1 offset:46080
	s_waitcnt lgkmcnt(13)
	v_fma_f32 v69, -v58, v108, v69
	v_fma_f32 v69, -v59, v109, v69
	v_fma_f32 v69, -v61, v110, v69
	v_fma_f32 v69, -v63, v111, v69
	ds_read_b128 v[108:111], v1 offset:46096
	s_waitcnt lgkmcnt(13)
	v_fma_f32 v69, -v112, v65, v69
	v_fma_f32 v69, -v113, v67, v69
	ds_read_b128 v[112:115], v1 offset:46112
	s_waitcnt lgkmcnt(13)
	v_fma_f32 v71, -v0, v116, v71
	v_fma_f32 v71, -v4, v117, v71
	v_fma_f32 v71, -v5, v118, v71
	v_fma_f32 v71, -v6, v119, v71
	ds_read_b128 v[116:119], v1 offset:46128
	s_waitcnt lgkmcnt(13)
	v_fma_f32 v71, -v7, v120, v71
	v_fma_f32 v71, -v8, v121, v71
	v_fma_f32 v71, -v9, v122, v71
	v_fma_f32 v71, -v10, v123, v71
	ds_read_b128 v[120:123], v1 offset:46144
	s_waitcnt lgkmcnt(13)
	v_fma_f32 v71, -v11, v124, v71
	v_fma_f32 v71, -v12, v125, v71
	v_fma_f32 v71, -v13, v126, v71
	v_fma_f32 v71, -v14, v127, v71
	ds_read_b128 v[124:127], v1 offset:46160
	s_waitcnt lgkmcnt(13)
	v_fma_f32 v71, -v15, v128, v71
	v_fma_f32 v71, -v16, v129, v71
	v_fma_f32 v71, -v18, v130, v71
	v_fma_f32 v71, -v19, v131, v71
	ds_read_b128 v[128:131], v1 offset:46176
	s_waitcnt lgkmcnt(13)
	v_fma_f32 v71, -v20, v132, v71
	v_fma_f32 v71, -v22, v133, v71
	v_fma_f32 v71, -v23, v134, v71
	v_fma_f32 v71, -v24, v135, v71
	ds_read_b128 v[132:135], v1 offset:46192
	s_waitcnt lgkmcnt(13)
	v_fma_f32 v71, -v25, v136, v71
	v_fma_f32 v71, -v27, v137, v71
	v_fma_f32 v71, -v28, v138, v71
	v_fma_f32 v71, -v30, v139, v71
	ds_read_b128 v[136:139], v1 offset:46208
	s_waitcnt lgkmcnt(13)
	v_fma_f32 v71, -v31, v140, v71
	v_fma_f32 v71, -v33, v141, v71
	v_fma_f32 v71, -v34, v142, v71
	v_fma_f32 v71, -v36, v143, v71
	ds_read_b128 v[140:143], v1 offset:46224
	s_waitcnt lgkmcnt(13)
	v_fma_f32 v71, -v37, v144, v71
	v_fma_f32 v71, -v39, v145, v71
	v_fma_f32 v71, -v40, v146, v71
	v_fma_f32 v71, -v44, v147, v71
	ds_read_b128 v[144:147], v1 offset:46240
	s_waitcnt lgkmcnt(13)
	v_fma_f32 v71, -v46, v148, v71
	v_fma_f32 v71, -v47, v149, v71
	v_fma_f32 v71, -v49, v150, v71
	v_fma_f32 v71, -v51, v151, v71
	ds_read_b128 v[148:151], v1 offset:46336
	s_waitcnt lgkmcnt(13)
	v_fma_f32 v71, -v58, v152, v71
	v_fma_f32 v71, -v59, v153, v71
	v_fma_f32 v71, -v61, v154, v71
	v_fma_f32 v71, -v63, v155, v71
	ds_read_b128 v[152:155], v1 offset:46352
	s_waitcnt lgkmcnt(13)
; DI void gdnprep_item(const Params& p, int item, unsigned char* ldsb) {
;     ...
;     for (int i = 1; i < 64; ++i) {
;       float a = x[i];
; #pragma unroll
;       for (int j4 = 0; j4 < (i + 3) / 4; ++j4) {
;         f32x4 Lv = *(const f32x4*)(Lm + i * 64 + j4 * 4);
; #pragma unroll
;         for (int e = 0; e < 4; ++e) if (j4 * 4 + e < i) a -= Lv[e] * x[j4 * 4 + e];
;       }
;       x[i] = a;
;       if ((i & 3) == 3) __builtin_amdgcn_sched_barrier(0);
;     }
	v_fma_f32 v71, -v65, v100, v71
	v_fma_f32 v71, -v101, v67, v71
	v_fma_f32 v71, -v102, v69, v71
	ds_read_b128 v[100:103], v1 offset:46368
	s_waitcnt lgkmcnt(13)
	v_fma_f32 v73, -v0, v104, v73
	v_fma_f32 v73, -v4, v105, v73
	v_fma_f32 v73, -v5, v106, v73
	v_fma_f32 v73, -v6, v107, v73
	ds_read_b128 v[104:107], v1 offset:46384
	s_waitcnt lgkmcnt(13)
	v_fma_f32 v73, -v7, v108, v73
	v_fma_f32 v73, -v8, v109, v73
	v_fma_f32 v73, -v9, v110, v73
	v_fma_f32 v73, -v10, v111, v73
	ds_read_b128 v[108:111], v1 offset:46400
	s_waitcnt lgkmcnt(13)
	v_fma_f32 v73, -v11, v112, v73
	v_fma_f32 v73, -v12, v113, v73
	v_fma_f32 v73, -v13, v114, v73
	v_fma_f32 v73, -v14, v115, v73
	ds_read_b128 v[112:115], v1 offset:46416
	s_waitcnt lgkmcnt(13)
	v_fma_f32 v73, -v15, v116, v73
	v_fma_f32 v73, -v16, v117, v73
	v_fma_f32 v73, -v18, v118, v73
	v_fma_f32 v73, -v19, v119, v73
	ds_read_b128 v[116:119], v1 offset:46432
	s_waitcnt lgkmcnt(13)
	v_fma_f32 v73, -v20, v120, v73
	v_fma_f32 v73, -v22, v121, v73
	v_fma_f32 v73, -v23, v122, v73
	v_fma_f32 v73, -v24, v123, v73
	ds_read_b128 v[120:123], v1 offset:46448
	s_waitcnt lgkmcnt(13)
	v_fma_f32 v73, -v25, v124, v73
	v_fma_f32 v73, -v27, v125, v73
	v_fma_f32 v73, -v28, v126, v73
	v_fma_f32 v73, -v30, v127, v73
	ds_read_b128 v[124:127], v1 offset:46464
	s_waitcnt lgkmcnt(13)
	v_fma_f32 v73, -v31, v128, v73
	v_fma_f32 v73, -v33, v129, v73
	v_fma_f32 v73, -v34, v130, v73
	v_fma_f32 v73, -v36, v131, v73
	ds_read_b128 v[128:131], v1 offset:46480
	s_waitcnt lgkmcnt(13)
	v_fma_f32 v73, -v37, v132, v73
	v_fma_f32 v73, -v39, v133, v73
	v_fma_f32 v73, -v40, v134, v73
	v_fma_f32 v73, -v44, v135, v73
	ds_read_b128 v[132:135], v1 offset:46496
	s_waitcnt lgkmcnt(13)
	v_fma_f32 v73, -v46, v136, v73
	v_fma_f32 v73, -v47, v137, v73
	v_fma_f32 v73, -v49, v138, v73
	v_fma_f32 v73, -v51, v139, v73
	ds_read_b128 v[136:139], v1 offset:46512
	s_waitcnt lgkmcnt(13)
	v_fma_f32 v73, -v58, v140, v73
	v_fma_f32 v73, -v59, v141, v73
	v_fma_f32 v73, -v61, v142, v73
	v_fma_f32 v73, -v63, v143, v73
	ds_read_b128 v[140:143], v1 offset:46592
	s_waitcnt lgkmcnt(13)
	v_fma_f32 v73, -v65, v144, v73
	v_fma_f32 v73, -v67, v145, v73
	v_fma_f32 v73, -v146, v69, v73
	v_fma_f32 v73, -v147, v71, v73
	ds_read_b128 v[144:147], v1 offset:46608
	s_waitcnt lgkmcnt(13)
	v_fma_f32 v72, -v0, v148, v72
	v_fma_f32 v72, -v4, v149, v72
	v_fma_f32 v72, -v5, v150, v72
	v_fma_f32 v72, -v6, v151, v72
	ds_read_b128 v[148:151], v1 offset:46624
	s_waitcnt lgkmcnt(13)
	v_fma_f32 v72, -v7, v152, v72
	v_fma_f32 v72, -v8, v153, v72
	v_fma_f32 v72, -v9, v154, v72
	v_fma_f32 v72, -v10, v155, v72
	ds_read_b128 v[152:155], v1 offset:46640
	s_waitcnt lgkmcnt(13)
	v_fma_f32 v72, -v11, v100, v72
	v_fma_f32 v72, -v12, v101, v72
	v_fma_f32 v72, -v13, v102, v72
	v_fma_f32 v72, -v14, v103, v72
	ds_read_b128 v[100:103], v1 offset:46656
	s_waitcnt lgkmcnt(13)
	v_fma_f32 v72, -v15, v104, v72
	v_fma_f32 v72, -v16, v105, v72
	v_fma_f32 v72, -v18, v106, v72
	v_fma_f32 v72, -v19, v107, v72
	ds_read_b128 v[104:107], v1 offset:46672
	s_waitcnt lgkmcnt(13)
	v_fma_f32 v72, -v20, v108, v72
	v_fma_f32 v72, -v22, v109, v72
	v_fma_f32 v72, -v23, v110, v72
	v_fma_f32 v72, -v24, v111, v72
	ds_read_b128 v[108:111], v1 offset:46688
	s_waitcnt lgkmcnt(13)
	v_fma_f32 v72, -v25, v112, v72
	v_fma_f32 v72, -v27, v113, v72
	v_fma_f32 v72, -v28, v114, v72
	v_fma_f32 v72, -v30, v115, v72
	ds_read_b128 v[112:115], v1 offset:46704
	s_waitcnt lgkmcnt(13)
	v_fma_f32 v72, -v31, v116, v72
	v_fma_f32 v72, -v33, v117, v72
	v_fma_f32 v72, -v34, v118, v72
	v_fma_f32 v72, -v36, v119, v72
	ds_read_b128 v[116:119], v1 offset:46720
	s_waitcnt lgkmcnt(13)
	v_fma_f32 v72, -v37, v120, v72
	v_fma_f32 v72, -v39, v121, v72
	v_fma_f32 v72, -v40, v122, v72
	v_fma_f32 v72, -v44, v123, v72
	ds_read_b128 v[120:123], v1 offset:46736
	s_waitcnt lgkmcnt(13)
	v_fma_f32 v72, -v46, v124, v72
	v_fma_f32 v72, -v47, v125, v72
	v_fma_f32 v72, -v49, v126, v72
	v_fma_f32 v72, -v51, v127, v72
	ds_read_b128 v[124:127], v1 offset:46752
	s_waitcnt lgkmcnt(13)
	v_fma_f32 v72, -v58, v128, v72
	v_fma_f32 v72, -v59, v129, v72
	v_fma_f32 v72, -v61, v130, v72
	v_fma_f32 v72, -v63, v131, v72
	ds_read_b128 v[128:131], v1 offset:46768
	s_waitcnt lgkmcnt(13)
	v_fma_f32 v72, -v65, v132, v72
	v_fma_f32 v72, -v67, v133, v72
	v_fma_f32 v72, -v69, v134, v72
	v_fma_f32 v72, -v135, v71, v72
	ds_read_b128 v[132:135], v1 offset:46848
	s_waitcnt lgkmcnt(13)
	v_fma_f32 v72, -v136, v73, v72
	ds_read_b128 v[136:139], v1 offset:46864
	s_waitcnt lgkmcnt(13)
	v_fma_f32 v70, -v0, v140, v70
	v_fma_f32 v70, -v4, v141, v70
	v_fma_f32 v70, -v5, v142, v70
	v_fma_f32 v70, -v6, v143, v70
	ds_read_b128 v[140:143], v1 offset:46880
	s_waitcnt lgkmcnt(13)
	v_fma_f32 v70, -v7, v144, v70
	v_fma_f32 v70, -v8, v145, v70
	v_fma_f32 v70, -v9, v146, v70
	v_fma_f32 v70, -v10, v147, v70
	ds_read_b128 v[144:147], v1 offset:46896
	s_waitcnt lgkmcnt(13)
	v_fma_f32 v70, -v11, v148, v70
	v_fma_f32 v70, -v12, v149, v70
	v_fma_f32 v70, -v13, v150, v70
	v_fma_f32 v70, -v14, v151, v70
	ds_read_b128 v[148:151], v1 offset:46912
	s_waitcnt lgkmcnt(13)
	v_fma_f32 v70, -v15, v152, v70
	v_fma_f32 v70, -v16, v153, v70
	v_fma_f32 v70, -v18, v154, v70
	v_fma_f32 v70, -v19, v155, v70
	ds_read_b128 v[152:155], v1 offset:46928
	s_waitcnt lgkmcnt(13)
	v_fma_f32 v70, -v20, v100, v70
	v_fma_f32 v70, -v22, v101, v70
	v_fma_f32 v70, -v23, v102, v70
	v_fma_f32 v70, -v24, v103, v70
	ds_read_b128 v[100:103], v1 offset:46944
	s_waitcnt lgkmcnt(13)
	v_fma_f32 v70, -v25, v104, v70
	v_fma_f32 v70, -v27, v105, v70
	v_fma_f32 v70, -v28, v106, v70
	v_fma_f32 v70, -v30, v107, v70
	ds_read_b128 v[104:107], v1 offset:46960
	s_waitcnt lgkmcnt(13)
; DI void gdnprep_item(const Params& p, int item, unsigned char* ldsb) {
;     ...
;     for (int i = 1; i < 64; ++i) {
;       float a = x[i];
; #pragma unroll
;       for (int j4 = 0; j4 < (i + 3) / 4; ++j4) {
;         f32x4 Lv = *(const f32x4*)(Lm + i * 64 + j4 * 4);
; #pragma unroll
;         for (int e = 0; e < 4; ++e) if (j4 * 4 + e < i) a -= Lv[e] * x[j4 * 4 + e];
;       }
;       x[i] = a;
;       if ((i & 3) == 3) __builtin_amdgcn_sched_barrier(0);
;     }
	v_fma_f32 v70, -v31, v108, v70
	v_fma_f32 v70, -v33, v109, v70
	v_fma_f32 v70, -v34, v110, v70
	v_fma_f32 v70, -v36, v111, v70
	ds_read_b128 v[108:111], v1 offset:46976
	s_waitcnt lgkmcnt(13)
	v_fma_f32 v70, -v37, v112, v70
	v_fma_f32 v70, -v39, v113, v70
	v_fma_f32 v70, -v40, v114, v70
	v_fma_f32 v70, -v44, v115, v70
	ds_read_b128 v[112:115], v1 offset:46992
	s_waitcnt lgkmcnt(13)
	v_fma_f32 v70, -v46, v116, v70
	v_fma_f32 v70, -v47, v117, v70
	v_fma_f32 v70, -v49, v118, v70
	v_fma_f32 v70, -v51, v119, v70
	ds_read_b128 v[116:119], v1 offset:47008
	s_waitcnt lgkmcnt(13)
	v_fma_f32 v70, -v58, v120, v70
	v_fma_f32 v70, -v59, v121, v70
	v_fma_f32 v70, -v61, v122, v70
	v_fma_f32 v70, -v63, v123, v70
	ds_read_b128 v[120:123], v1 offset:47024
	s_waitcnt lgkmcnt(13)
	v_fma_f32 v70, -v65, v124, v70
	v_fma_f32 v70, -v67, v125, v70
	v_fma_f32 v70, -v69, v126, v70
	v_fma_f32 v70, -v71, v127, v70
	ds_read_b128 v[124:127], v1 offset:47104
	s_waitcnt lgkmcnt(13)
	v_fma_f32 v70, -v128, v73, v70
	v_fma_f32 v70, -v129, v72, v70
	ds_read_b128 v[128:131], v1 offset:47120
	s_waitcnt lgkmcnt(13)
	v_fma_f32 v68, -v0, v132, v68
	v_fma_f32 v68, -v4, v133, v68
	v_fma_f32 v68, -v5, v134, v68
	v_fma_f32 v68, -v6, v135, v68
	ds_read_b128 v[132:135], v1 offset:47136
	s_waitcnt lgkmcnt(13)
	v_fma_f32 v68, -v7, v136, v68
	v_fma_f32 v68, -v8, v137, v68
	v_fma_f32 v68, -v9, v138, v68
	v_fma_f32 v68, -v10, v139, v68
	ds_read_b128 v[136:139], v1 offset:47152
	s_waitcnt lgkmcnt(13)
	v_fma_f32 v68, -v11, v140, v68
	v_fma_f32 v68, -v12, v141, v68
	v_fma_f32 v68, -v13, v142, v68
	v_fma_f32 v68, -v14, v143, v68
	ds_read_b128 v[140:143], v1 offset:47168
	s_waitcnt lgkmcnt(13)
	v_fma_f32 v68, -v15, v144, v68
	v_fma_f32 v68, -v16, v145, v68
	v_fma_f32 v68, -v18, v146, v68
	v_fma_f32 v68, -v19, v147, v68
	ds_read_b128 v[144:147], v1 offset:47184
	s_waitcnt lgkmcnt(13)
	v_fma_f32 v68, -v20, v148, v68
	v_fma_f32 v68, -v22, v149, v68
	v_fma_f32 v68, -v23, v150, v68
	v_fma_f32 v68, -v24, v151, v68
	ds_read_b128 v[148:151], v1 offset:47200
	s_waitcnt lgkmcnt(13)
	v_fma_f32 v68, -v25, v152, v68
	v_fma_f32 v68, -v27, v153, v68
	v_fma_f32 v68, -v28, v154, v68
	v_fma_f32 v68, -v30, v155, v68
	ds_read_b128 v[152:155], v1 offset:47216
	s_waitcnt lgkmcnt(13)
	v_fma_f32 v68, -v31, v100, v68
	v_fma_f32 v68, -v33, v101, v68
	v_fma_f32 v68, -v34, v102, v68
	v_fma_f32 v68, -v36, v103, v68
	ds_read_b128 v[100:103], v1 offset:47232
	s_waitcnt lgkmcnt(13)
	v_fma_f32 v68, -v37, v104, v68
	v_fma_f32 v68, -v39, v105, v68
	v_fma_f32 v68, -v40, v106, v68
	v_fma_f32 v68, -v44, v107, v68
	ds_read_b128 v[104:107], v1 offset:47248
	s_waitcnt lgkmcnt(13)
	v_fma_f32 v68, -v46, v108, v68
	v_fma_f32 v68, -v47, v109, v68
	v_fma_f32 v68, -v49, v110, v68
	v_fma_f32 v68, -v51, v111, v68
	ds_read_b128 v[108:111], v1 offset:47264
	s_waitcnt lgkmcnt(13)
	v_fma_f32 v68, -v58, v112, v68
	v_fma_f32 v68, -v59, v113, v68
	v_fma_f32 v68, -v61, v114, v68
	v_fma_f32 v68, -v63, v115, v68
	ds_read_b128 v[112:115], v1 offset:47280
	s_waitcnt lgkmcnt(13)
	v_fma_f32 v68, -v65, v116, v68
	v_fma_f32 v68, -v67, v117, v68
	v_fma_f32 v68, -v69, v118, v68
	v_fma_f32 v68, -v71, v119, v68
	ds_read_b128 v[116:119], v1 offset:47360
	s_waitcnt lgkmcnt(13)
	v_fma_f32 v68, -v73, v120, v68
	v_fma_f32 v68, -v121, v72, v68
	v_fma_f32 v68, -v122, v70, v68
	ds_read_b128 v[120:123], v1 offset:47376
	s_waitcnt lgkmcnt(13)
	v_fma_f32 v66, -v0, v124, v66
	v_fma_f32 v66, -v4, v125, v66
	v_fma_f32 v66, -v5, v126, v66
	v_fma_f32 v66, -v6, v127, v66
	ds_read_b128 v[124:127], v1 offset:47392
	s_waitcnt lgkmcnt(13)
	v_fma_f32 v66, -v7, v128, v66
	v_fma_f32 v66, -v8, v129, v66
	v_fma_f32 v66, -v9, v130, v66
	v_fma_f32 v66, -v10, v131, v66
	ds_read_b128 v[128:131], v1 offset:47408
	s_waitcnt lgkmcnt(13)
	v_fma_f32 v66, -v11, v132, v66
	v_fma_f32 v66, -v12, v133, v66
	v_fma_f32 v66, -v13, v134, v66
	v_fma_f32 v66, -v14, v135, v66
	ds_read_b128 v[132:135], v1 offset:47424
	s_waitcnt lgkmcnt(13)
	v_fma_f32 v66, -v15, v136, v66
	v_fma_f32 v66, -v16, v137, v66
	v_fma_f32 v66, -v18, v138, v66
	v_fma_f32 v66, -v19, v139, v66
	ds_read_b128 v[136:139], v1 offset:47440
	s_waitcnt lgkmcnt(13)
	v_fma_f32 v66, -v20, v140, v66
	v_fma_f32 v66, -v22, v141, v66
	v_fma_f32 v66, -v23, v142, v66
	v_fma_f32 v66, -v24, v143, v66
	ds_read_b128 v[140:143], v1 offset:47456
	s_waitcnt lgkmcnt(13)
	v_fma_f32 v66, -v25, v144, v66
	v_fma_f32 v66, -v27, v145, v66
	v_fma_f32 v66, -v28, v146, v66
	v_fma_f32 v66, -v30, v147, v66
	ds_read_b128 v[144:147], v1 offset:47472
	s_waitcnt lgkmcnt(13)
	v_fma_f32 v66, -v31, v148, v66
	v_fma_f32 v66, -v33, v149, v66
	v_fma_f32 v66, -v34, v150, v66
	v_fma_f32 v66, -v36, v151, v66
	ds_read_b128 v[148:151], v1 offset:47488
	s_waitcnt lgkmcnt(13)
	v_fma_f32 v66, -v37, v152, v66
	v_fma_f32 v66, -v39, v153, v66
	v_fma_f32 v66, -v40, v154, v66
	v_fma_f32 v66, -v44, v155, v66
	ds_read_b128 v[152:155], v1 offset:47504
	s_waitcnt lgkmcnt(13)
	v_fma_f32 v66, -v46, v100, v66
	v_fma_f32 v66, -v47, v101, v66
	v_fma_f32 v66, -v49, v102, v66
	v_fma_f32 v66, -v51, v103, v66
	ds_read_b128 v[100:103], v1 offset:47520
	s_waitcnt lgkmcnt(13)
	v_fma_f32 v66, -v58, v104, v66
	v_fma_f32 v66, -v59, v105, v66
	v_fma_f32 v66, -v61, v106, v66
	v_fma_f32 v66, -v63, v107, v66
	ds_read_b128 v[104:107], v1 offset:47536
	s_waitcnt lgkmcnt(13)
	v_fma_f32 v66, -v65, v108, v66
	v_fma_f32 v66, -v67, v109, v66
	v_fma_f32 v66, -v69, v110, v66
	v_fma_f32 v66, -v71, v111, v66
	ds_read_b128 v[108:111], v1 offset:47552
	s_waitcnt lgkmcnt(13)
	v_fma_f32 v66, -v73, v112, v66
	v_fma_f32 v66, -v72, v113, v66
	v_fma_f32 v66, -v114, v70, v66
	v_fma_f32 v66, -v115, v68, v66
	ds_read_b128 v[112:115], v1 offset:47616
	s_waitcnt lgkmcnt(13)
; DI void gdnprep_item(const Params& p, int item, unsigned char* ldsb) {
;     ...
;     for (int i = 1; i < 64; ++i) {
;       float a = x[i];
; #pragma unroll
;       for (int j4 = 0; j4 < (i + 3) / 4; ++j4) {
;         f32x4 Lv = *(const f32x4*)(Lm + i * 64 + j4 * 4);
; #pragma unroll
;         for (int e = 0; e < 4; ++e) if (j4 * 4 + e < i) a -= Lv[e] * x[j4 * 4 + e];
;       }
;       x[i] = a;
;       if ((i & 3) == 3) __builtin_amdgcn_sched_barrier(0);
;     }
	v_fma_f32 v64, -v0, v116, v64
	v_fma_f32 v64, -v4, v117, v64
	v_fma_f32 v64, -v5, v118, v64
	v_fma_f32 v64, -v6, v119, v64
	ds_read_b128 v[116:119], v1 offset:47632
	s_waitcnt lgkmcnt(13)
	v_fma_f32 v64, -v7, v120, v64
	v_fma_f32 v64, -v8, v121, v64
	v_fma_f32 v64, -v9, v122, v64
	v_fma_f32 v64, -v10, v123, v64
	ds_read_b128 v[120:123], v1 offset:47648
	s_waitcnt lgkmcnt(13)
	v_fma_f32 v64, -v11, v124, v64
	v_fma_f32 v64, -v12, v125, v64
	v_fma_f32 v64, -v13, v126, v64
	v_fma_f32 v64, -v14, v127, v64
	ds_read_b128 v[124:127], v1 offset:47664
	s_waitcnt lgkmcnt(13)
	v_fma_f32 v64, -v15, v128, v64
	v_fma_f32 v64, -v16, v129, v64
	v_fma_f32 v64, -v18, v130, v64
	v_fma_f32 v64, -v19, v131, v64
	ds_read_b128 v[128:131], v1 offset:47680
	s_waitcnt lgkmcnt(13)
	v_fma_f32 v64, -v20, v132, v64
	v_fma_f32 v64, -v22, v133, v64
	v_fma_f32 v64, -v23, v134, v64
	v_fma_f32 v64, -v24, v135, v64
	ds_read_b128 v[132:135], v1 offset:47696
	s_waitcnt lgkmcnt(13)
	v_fma_f32 v64, -v25, v136, v64
	v_fma_f32 v64, -v27, v137, v64
	v_fma_f32 v64, -v28, v138, v64
	v_fma_f32 v64, -v30, v139, v64
	ds_read_b128 v[136:139], v1 offset:47712
	s_waitcnt lgkmcnt(13)
	v_fma_f32 v64, -v31, v140, v64
	v_fma_f32 v64, -v33, v141, v64
	v_fma_f32 v64, -v34, v142, v64
	v_fma_f32 v64, -v36, v143, v64
	ds_read_b128 v[140:143], v1 offset:47728
	s_waitcnt lgkmcnt(13)
	v_fma_f32 v64, -v37, v144, v64
	v_fma_f32 v64, -v39, v145, v64
	v_fma_f32 v64, -v40, v146, v64
	v_fma_f32 v64, -v44, v147, v64
	ds_read_b128 v[144:147], v1 offset:47744
	s_waitcnt lgkmcnt(13)
	v_fma_f32 v64, -v46, v148, v64
	v_fma_f32 v64, -v47, v149, v64
	v_fma_f32 v64, -v49, v150, v64
	v_fma_f32 v64, -v51, v151, v64
	ds_read_b128 v[148:151], v1 offset:47760
	s_waitcnt lgkmcnt(13)
	v_fma_f32 v64, -v58, v152, v64
	v_fma_f32 v64, -v59, v153, v64
	v_fma_f32 v64, -v61, v154, v64
	v_fma_f32 v64, -v63, v155, v64
	ds_read_b128 v[152:155], v1 offset:47776
	s_waitcnt lgkmcnt(13)
	v_fma_f32 v64, -v65, v100, v64
	v_fma_f32 v64, -v67, v101, v64
	v_fma_f32 v64, -v69, v102, v64
	v_fma_f32 v64, -v71, v103, v64
	ds_read_b128 v[100:103], v1 offset:47792
	s_waitcnt lgkmcnt(13)
	v_fma_f32 v64, -v73, v104, v64
	v_fma_f32 v64, -v72, v105, v64
	v_fma_f32 v64, -v70, v106, v64
	v_fma_f32 v64, -v107, v68, v64
	ds_read_b128 v[104:107], v1 offset:47808
	s_waitcnt lgkmcnt(13)
	v_fma_f32 v64, -v108, v66, v64
	ds_read_b128 v[108:111], v1 offset:47872
	s_waitcnt lgkmcnt(13)
	v_fma_f32 v62, -v0, v112, v62
	v_fma_f32 v62, -v4, v113, v62
	v_fma_f32 v62, -v5, v114, v62
	v_fma_f32 v62, -v6, v115, v62
	ds_read_b128 v[112:115], v1 offset:47888
	s_waitcnt lgkmcnt(13)
	v_fma_f32 v62, -v7, v116, v62
	v_fma_f32 v62, -v8, v117, v62
	v_fma_f32 v62, -v9, v118, v62
	v_fma_f32 v62, -v10, v119, v62
	ds_read_b128 v[116:119], v1 offset:47904
	s_waitcnt lgkmcnt(13)
	v_fma_f32 v62, -v11, v120, v62
	v_fma_f32 v62, -v12, v121, v62
	v_fma_f32 v62, -v13, v122, v62
	v_fma_f32 v62, -v14, v123, v62
	ds_read_b128 v[120:123], v1 offset:47920
	s_waitcnt lgkmcnt(13)
	v_fma_f32 v62, -v15, v124, v62
	v_fma_f32 v62, -v16, v125, v62
	v_fma_f32 v62, -v18, v126, v62
	v_fma_f32 v62, -v19, v127, v62
	ds_read_b128 v[124:127], v1 offset:47936
	s_waitcnt lgkmcnt(13)
	v_fma_f32 v62, -v20, v128, v62
	v_fma_f32 v62, -v22, v129, v62
	v_fma_f32 v62, -v23, v130, v62
	v_fma_f32 v62, -v24, v131, v62
	ds_read_b128 v[128:131], v1 offset:47952
	s_waitcnt lgkmcnt(13)
	v_fma_f32 v62, -v25, v132, v62
	v_fma_f32 v62, -v27, v133, v62
	v_fma_f32 v62, -v28, v134, v62
	v_fma_f32 v62, -v30, v135, v62
	ds_read_b128 v[132:135], v1 offset:47968
	s_waitcnt lgkmcnt(13)
	v_fma_f32 v62, -v31, v136, v62
	v_fma_f32 v62, -v33, v137, v62
	v_fma_f32 v62, -v34, v138, v62
	v_fma_f32 v62, -v36, v139, v62
	ds_read_b128 v[136:139], v1 offset:47984
	s_waitcnt lgkmcnt(13)
	v_fma_f32 v62, -v37, v140, v62
	v_fma_f32 v62, -v39, v141, v62
	v_fma_f32 v62, -v40, v142, v62
	v_fma_f32 v62, -v44, v143, v62
	ds_read_b128 v[140:143], v1 offset:48000
	s_waitcnt lgkmcnt(13)
	v_fma_f32 v62, -v46, v144, v62
	v_fma_f32 v62, -v47, v145, v62
	v_fma_f32 v62, -v49, v146, v62
	v_fma_f32 v62, -v51, v147, v62
	ds_read_b128 v[144:147], v1 offset:48016
	s_waitcnt lgkmcnt(13)
	v_fma_f32 v62, -v58, v148, v62
	v_fma_f32 v62, -v59, v149, v62
	v_fma_f32 v62, -v61, v150, v62
	v_fma_f32 v62, -v63, v151, v62
	ds_read_b128 v[148:151], v1 offset:48032
	s_waitcnt lgkmcnt(13)
	v_fma_f32 v62, -v65, v152, v62
	v_fma_f32 v62, -v67, v153, v62
	v_fma_f32 v62, -v69, v154, v62
	v_fma_f32 v62, -v71, v155, v62
	ds_read_b128 v[152:155], v1 offset:48048
	s_waitcnt lgkmcnt(13)
	v_fma_f32 v62, -v73, v100, v62
	v_fma_f32 v62, -v72, v101, v62
	v_fma_f32 v62, -v70, v102, v62
	v_fma_f32 v62, -v68, v103, v62
	ds_read_b128 v[100:103], v1 offset:48064
	s_waitcnt lgkmcnt(13)
	v_fma_f32 v62, -v104, v66, v62
	v_fma_f32 v62, -v105, v64, v62
	ds_read_b128 v[104:107], v1 offset:48128
	s_waitcnt lgkmcnt(13)
	v_fma_f32 v60, -v0, v108, v60
	v_fma_f32 v60, -v4, v109, v60
	v_fma_f32 v60, -v5, v110, v60
	v_fma_f32 v60, -v6, v111, v60
	ds_read_b128 v[108:111], v1 offset:48144
	s_waitcnt lgkmcnt(13)
	v_fma_f32 v60, -v7, v112, v60
	v_fma_f32 v60, -v8, v113, v60
	v_fma_f32 v60, -v9, v114, v60
	v_fma_f32 v60, -v10, v115, v60
	ds_read_b128 v[112:115], v1 offset:48160
	s_waitcnt lgkmcnt(13)
	v_fma_f32 v60, -v11, v116, v60
	v_fma_f32 v60, -v12, v117, v60
	v_fma_f32 v60, -v13, v118, v60
	v_fma_f32 v60, -v14, v119, v60
	ds_read_b128 v[116:119], v1 offset:48176
	s_waitcnt lgkmcnt(13)
	v_fma_f32 v60, -v15, v120, v60
	v_fma_f32 v60, -v16, v121, v60
	v_fma_f32 v60, -v18, v122, v60
	v_fma_f32 v60, -v19, v123, v60
	ds_read_b128 v[120:123], v1 offset:48192
	s_waitcnt lgkmcnt(13)
; DI void gdnprep_item(const Params& p, int item, unsigned char* ldsb) {
;     ...
;     for (int i = 1; i < 64; ++i) {
;       float a = x[i];
; #pragma unroll
;       for (int j4 = 0; j4 < (i + 3) / 4; ++j4) {
;         f32x4 Lv = *(const f32x4*)(Lm + i * 64 + j4 * 4);
; #pragma unroll
;         for (int e = 0; e < 4; ++e) if (j4 * 4 + e < i) a -= Lv[e] * x[j4 * 4 + e];
;       }
;       x[i] = a;
;       if ((i & 3) == 3) __builtin_amdgcn_sched_barrier(0);
;     }
	v_fma_f32 v60, -v20, v124, v60
	v_fma_f32 v60, -v22, v125, v60
	v_fma_f32 v60, -v23, v126, v60
	v_fma_f32 v60, -v24, v127, v60
	ds_read_b128 v[124:127], v1 offset:48208
	s_waitcnt lgkmcnt(13)
	v_fma_f32 v60, -v25, v128, v60
	v_fma_f32 v60, -v27, v129, v60
	v_fma_f32 v60, -v28, v130, v60
	v_fma_f32 v60, -v30, v131, v60
	ds_read_b128 v[128:131], v1 offset:48224
	s_waitcnt lgkmcnt(13)
	v_fma_f32 v60, -v31, v132, v60
	v_fma_f32 v60, -v33, v133, v60
	v_fma_f32 v60, -v34, v134, v60
	v_fma_f32 v60, -v36, v135, v60
	ds_read_b128 v[132:135], v1 offset:48240
	s_waitcnt lgkmcnt(13)
	v_fma_f32 v60, -v37, v136, v60
	v_fma_f32 v60, -v39, v137, v60
	v_fma_f32 v60, -v40, v138, v60
	v_fma_f32 v60, -v44, v139, v60
	ds_read_b128 v[136:139], v1 offset:48256
	s_waitcnt lgkmcnt(13)
	v_fma_f32 v60, -v46, v140, v60
	v_fma_f32 v60, -v47, v141, v60
	v_fma_f32 v60, -v49, v142, v60
	v_fma_f32 v60, -v51, v143, v60
	ds_read_b128 v[140:143], v1 offset:48272
	s_waitcnt lgkmcnt(13)
	v_fma_f32 v60, -v58, v144, v60
	v_fma_f32 v60, -v59, v145, v60
	v_fma_f32 v60, -v61, v146, v60
	v_fma_f32 v60, -v63, v147, v60
	ds_read_b128 v[144:147], v1 offset:48288
	s_waitcnt lgkmcnt(13)
	v_fma_f32 v60, -v65, v148, v60
	v_fma_f32 v60, -v67, v149, v60
	v_fma_f32 v60, -v69, v150, v60
	v_fma_f32 v60, -v71, v151, v60
	ds_read_b128 v[148:151], v1 offset:48304
	s_waitcnt lgkmcnt(13)
	v_fma_f32 v60, -v73, v152, v60
	v_fma_f32 v60, -v72, v153, v60
	v_fma_f32 v60, -v70, v154, v60
	v_fma_f32 v60, -v68, v155, v60
	ds_read_b128 v[152:155], v1 offset:48320
	s_waitcnt lgkmcnt(13)
	v_fma_f32 v60, -v66, v100, v60
	v_fma_f32 v60, -v101, v64, v60
	v_fma_f32 v60, -v102, v62, v60
	ds_read_b128 v[100:103], v1 offset:48384
	s_waitcnt lgkmcnt(13)
	v_fma_f32 v57, -v0, v104, v57
	v_fma_f32 v57, -v4, v105, v57
	v_fma_f32 v57, -v5, v106, v57
	v_fma_f32 v57, -v6, v107, v57
	ds_read_b128 v[104:107], v1 offset:48400
	s_waitcnt lgkmcnt(13)
	v_fma_f32 v57, -v7, v108, v57
	v_fma_f32 v57, -v8, v109, v57
	v_fma_f32 v57, -v9, v110, v57
	v_fma_f32 v57, -v10, v111, v57
	ds_read_b128 v[108:111], v1 offset:48416
	s_waitcnt lgkmcnt(13)
	v_fma_f32 v57, -v11, v112, v57
	v_fma_f32 v57, -v12, v113, v57
	v_fma_f32 v57, -v13, v114, v57
	v_fma_f32 v57, -v14, v115, v57
	ds_read_b128 v[112:115], v1 offset:48432
	s_waitcnt lgkmcnt(13)
	v_fma_f32 v57, -v15, v116, v57
	v_fma_f32 v57, -v16, v117, v57
	v_fma_f32 v57, -v18, v118, v57
	v_fma_f32 v57, -v19, v119, v57
	ds_read_b128 v[116:119], v1 offset:48448
	s_waitcnt lgkmcnt(13)
	v_fma_f32 v57, -v20, v120, v57
	v_fma_f32 v57, -v22, v121, v57
	v_fma_f32 v57, -v23, v122, v57
	v_fma_f32 v57, -v24, v123, v57
	ds_read_b128 v[120:123], v1 offset:48464
	s_waitcnt lgkmcnt(13)
	v_fma_f32 v57, -v25, v124, v57
	v_fma_f32 v57, -v27, v125, v57
	v_fma_f32 v57, -v28, v126, v57
	v_fma_f32 v57, -v30, v127, v57
	ds_read_b128 v[124:127], v1 offset:48480
	s_waitcnt lgkmcnt(13)
	v_fma_f32 v57, -v31, v128, v57
	v_fma_f32 v57, -v33, v129, v57
	v_fma_f32 v57, -v34, v130, v57
	v_fma_f32 v57, -v36, v131, v57
	ds_read_b128 v[128:131], v1 offset:48496
	s_waitcnt lgkmcnt(13)
	v_fma_f32 v57, -v37, v132, v57
	v_fma_f32 v57, -v39, v133, v57
	v_fma_f32 v57, -v40, v134, v57
	v_fma_f32 v57, -v44, v135, v57
	ds_read_b128 v[132:135], v1 offset:48512
	s_waitcnt lgkmcnt(13)
	v_fma_f32 v57, -v46, v136, v57
	v_fma_f32 v57, -v47, v137, v57
	v_fma_f32 v57, -v49, v138, v57
	v_fma_f32 v57, -v51, v139, v57
	ds_read_b128 v[136:139], v1 offset:48528
	s_waitcnt lgkmcnt(13)
	v_fma_f32 v57, -v58, v140, v57
	v_fma_f32 v57, -v59, v141, v57
	v_fma_f32 v57, -v61, v142, v57
	v_fma_f32 v57, -v63, v143, v57
	ds_read_b128 v[140:143], v1 offset:48544
	s_waitcnt lgkmcnt(13)
	v_fma_f32 v57, -v65, v144, v57
	v_fma_f32 v57, -v67, v145, v57
	v_fma_f32 v57, -v69, v146, v57
	v_fma_f32 v57, -v71, v147, v57
	ds_read_b128 v[144:147], v1 offset:48560
	s_waitcnt lgkmcnt(13)
	v_fma_f32 v57, -v73, v148, v57
	v_fma_f32 v57, -v72, v149, v57
	v_fma_f32 v57, -v70, v150, v57
	v_fma_f32 v57, -v68, v151, v57
	ds_read_b128 v[148:151], v1 offset:48576
	s_waitcnt lgkmcnt(13)
	v_fma_f32 v57, -v66, v152, v57
	v_fma_f32 v57, -v64, v153, v57
	v_fma_f32 v57, -v154, v62, v57
	v_fma_f32 v57, -v155, v60, v57
	ds_read_b128 v[152:155], v1 offset:48592
	s_waitcnt lgkmcnt(13)
	v_fma_f32 v50, -v0, v100, v50
	v_fma_f32 v50, -v4, v101, v50
	v_fma_f32 v50, -v5, v102, v50
	v_fma_f32 v50, -v6, v103, v50
	ds_read_b128 v[100:103], v1 offset:48640
	s_waitcnt lgkmcnt(13)
	v_fma_f32 v50, -v7, v104, v50
	v_fma_f32 v50, -v8, v105, v50
	v_fma_f32 v50, -v9, v106, v50
	v_fma_f32 v50, -v10, v107, v50
	ds_read_b128 v[104:107], v1 offset:48656
	s_waitcnt lgkmcnt(13)
	v_fma_f32 v50, -v11, v108, v50
	v_fma_f32 v50, -v12, v109, v50
	v_fma_f32 v50, -v13, v110, v50
	v_fma_f32 v50, -v14, v111, v50
	ds_read_b128 v[108:111], v1 offset:48672
	s_waitcnt lgkmcnt(13)
	v_fma_f32 v50, -v15, v112, v50
	v_fma_f32 v50, -v16, v113, v50
	v_fma_f32 v50, -v18, v114, v50
	v_fma_f32 v50, -v19, v115, v50
	ds_read_b128 v[112:115], v1 offset:48688
	s_waitcnt lgkmcnt(13)
	v_fma_f32 v50, -v20, v116, v50
	v_fma_f32 v50, -v22, v117, v50
	v_fma_f32 v50, -v23, v118, v50
	v_fma_f32 v50, -v24, v119, v50
	ds_read_b128 v[116:119], v1 offset:48704
	s_waitcnt lgkmcnt(13)
	v_fma_f32 v50, -v25, v120, v50
	v_fma_f32 v50, -v27, v121, v50
	v_fma_f32 v50, -v28, v122, v50
	v_fma_f32 v50, -v30, v123, v50
	ds_read_b128 v[120:123], v1 offset:48720
	s_waitcnt lgkmcnt(13)
	v_fma_f32 v50, -v31, v124, v50
	v_fma_f32 v50, -v33, v125, v50
	v_fma_f32 v50, -v34, v126, v50
	v_fma_f32 v50, -v36, v127, v50
	ds_read_b128 v[124:127], v1 offset:48736
	s_waitcnt lgkmcnt(13)
; DI void gdnprep_item(const Params& p, int item, unsigned char* ldsb) {
;     ...
;     for (int i = 1; i < 64; ++i) {
;       float a = x[i];
; #pragma unroll
;       for (int j4 = 0; j4 < (i + 3) / 4; ++j4) {
;         f32x4 Lv = *(const f32x4*)(Lm + i * 64 + j4 * 4);
; #pragma unroll
;         for (int e = 0; e < 4; ++e) if (j4 * 4 + e < i) a -= Lv[e] * x[j4 * 4 + e];
;       }
;       x[i] = a;
;       if ((i & 3) == 3) __builtin_amdgcn_sched_barrier(0);
;     }
	v_fma_f32 v50, -v37, v128, v50
	v_fma_f32 v50, -v39, v129, v50
	v_fma_f32 v50, -v40, v130, v50
	v_fma_f32 v50, -v44, v131, v50
	ds_read_b128 v[128:131], v1 offset:48752
	s_waitcnt lgkmcnt(13)
	v_fma_f32 v50, -v46, v132, v50
	v_fma_f32 v50, -v47, v133, v50
	v_fma_f32 v50, -v49, v134, v50
	v_fma_f32 v50, -v51, v135, v50
	ds_read_b128 v[132:135], v1 offset:48768
	s_waitcnt lgkmcnt(13)
	v_fma_f32 v50, -v58, v136, v50
	v_fma_f32 v50, -v59, v137, v50
	v_fma_f32 v50, -v61, v138, v50
	v_fma_f32 v50, -v63, v139, v50
	ds_read_b128 v[136:139], v1 offset:48784
	s_waitcnt lgkmcnt(13)
	v_fma_f32 v50, -v65, v140, v50
	v_fma_f32 v50, -v67, v141, v50
	v_fma_f32 v50, -v69, v142, v50
	v_fma_f32 v50, -v71, v143, v50
	ds_read_b128 v[140:143], v1 offset:48800
	s_waitcnt lgkmcnt(13)
	v_fma_f32 v50, -v73, v144, v50
	v_fma_f32 v50, -v72, v145, v50
	v_fma_f32 v50, -v70, v146, v50
	v_fma_f32 v50, -v68, v147, v50
	ds_read_b128 v[144:147], v1 offset:48816
	s_waitcnt lgkmcnt(13)
	v_fma_f32 v50, -v66, v148, v50
	v_fma_f32 v50, -v64, v149, v50
	v_fma_f32 v50, -v62, v150, v50
	v_fma_f32 v50, -v151, v60, v50
	ds_read_b128 v[148:151], v1 offset:48832
	s_waitcnt lgkmcnt(13)
	v_fma_f32 v50, -v152, v57, v50
	ds_read_b128 v[152:155], v1 offset:48848
	s_waitcnt lgkmcnt(13)
	v_fma_f32 v48, -v0, v100, v48
	v_fma_f32 v48, -v4, v101, v48
	v_fma_f32 v48, -v5, v102, v48
	v_fma_f32 v48, -v6, v103, v48
	ds_read_b128 v[100:103], v1 offset:48896
	s_waitcnt lgkmcnt(13)
	v_fma_f32 v48, -v7, v104, v48
	v_fma_f32 v48, -v8, v105, v48
	v_fma_f32 v48, -v9, v106, v48
	v_fma_f32 v48, -v10, v107, v48
	ds_read_b128 v[104:107], v1 offset:48912
	s_waitcnt lgkmcnt(13)
	v_fma_f32 v48, -v11, v108, v48
	v_fma_f32 v48, -v12, v109, v48
	v_fma_f32 v48, -v13, v110, v48
	v_fma_f32 v48, -v14, v111, v48
	ds_read_b128 v[108:111], v1 offset:48928
	s_waitcnt lgkmcnt(13)
	v_fma_f32 v48, -v15, v112, v48
	v_fma_f32 v48, -v16, v113, v48
	v_fma_f32 v48, -v18, v114, v48
	v_fma_f32 v48, -v19, v115, v48
	ds_read_b128 v[112:115], v1 offset:48944
	s_waitcnt lgkmcnt(13)
	v_fma_f32 v48, -v20, v116, v48
	v_fma_f32 v48, -v22, v117, v48
	v_fma_f32 v48, -v23, v118, v48
	v_fma_f32 v48, -v24, v119, v48
	ds_read_b128 v[116:119], v1 offset:48960
	s_waitcnt lgkmcnt(13)
	v_fma_f32 v48, -v25, v120, v48
	v_fma_f32 v48, -v27, v121, v48
	v_fma_f32 v48, -v28, v122, v48
	v_fma_f32 v48, -v30, v123, v48
	ds_read_b128 v[120:123], v1 offset:48976
	s_waitcnt lgkmcnt(13)
	v_fma_f32 v48, -v31, v124, v48
	v_fma_f32 v48, -v33, v125, v48
	v_fma_f32 v48, -v34, v126, v48
	v_fma_f32 v48, -v36, v127, v48
	ds_read_b128 v[124:127], v1 offset:48992
	s_waitcnt lgkmcnt(13)
	v_fma_f32 v48, -v37, v128, v48
	v_fma_f32 v48, -v39, v129, v48
	v_fma_f32 v48, -v40, v130, v48
	v_fma_f32 v48, -v44, v131, v48
	ds_read_b128 v[128:131], v1 offset:49008
	s_waitcnt lgkmcnt(13)
	v_fma_f32 v48, -v46, v132, v48
	v_fma_f32 v48, -v47, v133, v48
	v_fma_f32 v48, -v49, v134, v48
	v_fma_f32 v48, -v51, v135, v48
	ds_read_b128 v[132:135], v1 offset:49024
	s_waitcnt lgkmcnt(13)
	v_fma_f32 v48, -v58, v136, v48
	v_fma_f32 v48, -v59, v137, v48
	v_fma_f32 v48, -v61, v138, v48
	v_fma_f32 v48, -v63, v139, v48
	ds_read_b128 v[136:139], v1 offset:49040
	s_waitcnt lgkmcnt(13)
	v_fma_f32 v48, -v65, v140, v48
	v_fma_f32 v48, -v67, v141, v48
	v_fma_f32 v48, -v69, v142, v48
	v_fma_f32 v48, -v71, v143, v48
	ds_read_b128 v[140:143], v1 offset:49056
	s_waitcnt lgkmcnt(13)
	v_fma_f32 v48, -v73, v144, v48
	v_fma_f32 v48, -v72, v145, v48
	v_fma_f32 v48, -v70, v146, v48
	v_fma_f32 v48, -v68, v147, v48
	ds_read_b128 v[144:147], v1 offset:49072
	s_waitcnt lgkmcnt(13)
	v_fma_f32 v48, -v66, v148, v48
	v_fma_f32 v48, -v64, v149, v48
	v_fma_f32 v48, -v62, v150, v48
	v_fma_f32 v48, -v60, v151, v48
	ds_read_b128 v[148:151], v1 offset:49088
	s_waitcnt lgkmcnt(13)
	v_fma_f32 v48, -v152, v57, v48
	v_fma_f32 v48, -v153, v50, v48
	ds_read_b128 v[152:155], v1 offset:49104
	s_waitcnt lgkmcnt(13)
	v_fma_f32 v45, -v0, v100, v45
	v_fma_f32 v45, -v4, v101, v45
	v_fma_f32 v45, -v5, v102, v45
	v_fma_f32 v45, -v6, v103, v45
	ds_read_b128 v[100:103], v1 offset:49152
	s_waitcnt lgkmcnt(13)
	v_fma_f32 v45, -v7, v104, v45
	v_fma_f32 v45, -v8, v105, v45
	v_fma_f32 v45, -v9, v106, v45
	v_fma_f32 v45, -v10, v107, v45
	ds_read_b128 v[104:107], v1 offset:49168
	s_waitcnt lgkmcnt(13)
	v_fma_f32 v45, -v11, v108, v45
	v_fma_f32 v45, -v12, v109, v45
	v_fma_f32 v45, -v13, v110, v45
	v_fma_f32 v45, -v14, v111, v45
	ds_read_b128 v[108:111], v1 offset:49184
	s_waitcnt lgkmcnt(13)
	v_fma_f32 v45, -v15, v112, v45
	v_fma_f32 v45, -v16, v113, v45
	v_fma_f32 v45, -v18, v114, v45
	v_fma_f32 v45, -v19, v115, v45
	ds_read_b128 v[112:115], v1 offset:49200
	s_waitcnt lgkmcnt(13)
	v_fma_f32 v45, -v20, v116, v45
	v_fma_f32 v45, -v22, v117, v45
	v_fma_f32 v45, -v23, v118, v45
	v_fma_f32 v45, -v24, v119, v45
	ds_read_b128 v[116:119], v1 offset:49216
	s_waitcnt lgkmcnt(13)
	v_fma_f32 v45, -v25, v120, v45
	v_fma_f32 v45, -v27, v121, v45
	v_fma_f32 v45, -v28, v122, v45
	v_fma_f32 v45, -v30, v123, v45
	ds_read_b128 v[120:123], v1 offset:49232
	s_waitcnt lgkmcnt(13)
	v_fma_f32 v45, -v31, v124, v45
	v_fma_f32 v45, -v33, v125, v45
	v_fma_f32 v45, -v34, v126, v45
	v_fma_f32 v45, -v36, v127, v45
	ds_read_b128 v[124:127], v1 offset:49248
	s_waitcnt lgkmcnt(13)
	v_fma_f32 v45, -v37, v128, v45
	v_fma_f32 v45, -v39, v129, v45
	v_fma_f32 v45, -v40, v130, v45
	v_fma_f32 v45, -v44, v131, v45
	ds_read_b128 v[128:131], v1 offset:49264
	s_waitcnt lgkmcnt(13)
	v_fma_f32 v45, -v46, v132, v45
	v_fma_f32 v45, -v47, v133, v45
	v_fma_f32 v45, -v49, v134, v45
	v_fma_f32 v45, -v51, v135, v45
	ds_read_b128 v[132:135], v1 offset:49280
	s_waitcnt lgkmcnt(13)
; DI void gdnprep_item(const Params& p, int item, unsigned char* ldsb) {
;     ...
;     for (int i = 1; i < 64; ++i) {
;       float a = x[i];
; #pragma unroll
;       for (int j4 = 0; j4 < (i + 3) / 4; ++j4) {
;         f32x4 Lv = *(const f32x4*)(Lm + i * 64 + j4 * 4);
; #pragma unroll
;         for (int e = 0; e < 4; ++e) if (j4 * 4 + e < i) a -= Lv[e] * x[j4 * 4 + e];
;       }
;       x[i] = a;
;       if ((i & 3) == 3) __builtin_amdgcn_sched_barrier(0);
;     }
	v_fma_f32 v45, -v58, v136, v45
	v_fma_f32 v45, -v59, v137, v45
	v_fma_f32 v45, -v61, v138, v45
	v_fma_f32 v45, -v63, v139, v45
	ds_read_b128 v[136:139], v1 offset:49296
	s_waitcnt lgkmcnt(13)
	v_fma_f32 v45, -v65, v140, v45
	v_fma_f32 v45, -v67, v141, v45
	v_fma_f32 v45, -v69, v142, v45
	v_fma_f32 v45, -v71, v143, v45
	ds_read_b128 v[140:143], v1 offset:49312
	s_waitcnt lgkmcnt(13)
	v_fma_f32 v45, -v73, v144, v45
	v_fma_f32 v45, -v72, v145, v45
	v_fma_f32 v45, -v70, v146, v45
	v_fma_f32 v45, -v68, v147, v45
	ds_read_b128 v[144:147], v1 offset:49328
	s_waitcnt lgkmcnt(13)
	v_fma_f32 v45, -v66, v148, v45
	v_fma_f32 v45, -v64, v149, v45
	v_fma_f32 v45, -v62, v150, v45
	v_fma_f32 v45, -v60, v151, v45
	ds_read_b128 v[148:151], v1 offset:49344
	s_waitcnt lgkmcnt(13)
	v_fma_f32 v45, -v57, v152, v45
	v_fma_f32 v45, -v153, v50, v45
	v_fma_f32 v45, -v154, v48, v45
	ds_read_b128 v[152:155], v1 offset:49360
	s_waitcnt lgkmcnt(13)
	v_fma_f32 v41, -v0, v100, v41
	v_fma_f32 v41, -v4, v101, v41
	v_fma_f32 v41, -v5, v102, v41
	v_fma_f32 v41, -v6, v103, v41
	ds_read_b128 v[100:103], v1 offset:49408
	s_waitcnt lgkmcnt(13)
	v_fma_f32 v41, -v7, v104, v41
	v_fma_f32 v41, -v8, v105, v41
	v_fma_f32 v41, -v9, v106, v41
	v_fma_f32 v41, -v10, v107, v41
	ds_read_b128 v[104:107], v1 offset:49424
	s_waitcnt lgkmcnt(13)
	v_fma_f32 v41, -v11, v108, v41
	v_fma_f32 v41, -v12, v109, v41
	v_fma_f32 v41, -v13, v110, v41
	v_fma_f32 v41, -v14, v111, v41
	ds_read_b128 v[108:111], v1 offset:49440
	s_waitcnt lgkmcnt(13)
	v_fma_f32 v41, -v15, v112, v41
	v_fma_f32 v41, -v16, v113, v41
	v_fma_f32 v41, -v18, v114, v41
	v_fma_f32 v41, -v19, v115, v41
	ds_read_b128 v[112:115], v1 offset:49456
	s_waitcnt lgkmcnt(13)
	v_fma_f32 v41, -v20, v116, v41
	v_fma_f32 v41, -v22, v117, v41
	v_fma_f32 v41, -v23, v118, v41
	v_fma_f32 v41, -v24, v119, v41
	ds_read_b128 v[116:119], v1 offset:49472
	s_waitcnt lgkmcnt(13)
	v_fma_f32 v41, -v25, v120, v41
	v_fma_f32 v41, -v27, v121, v41
	v_fma_f32 v41, -v28, v122, v41
	v_fma_f32 v41, -v30, v123, v41
	ds_read_b128 v[120:123], v1 offset:49488
	s_waitcnt lgkmcnt(13)
	v_fma_f32 v41, -v31, v124, v41
	v_fma_f32 v41, -v33, v125, v41
	v_fma_f32 v41, -v34, v126, v41
	v_fma_f32 v41, -v36, v127, v41
	ds_read_b128 v[124:127], v1 offset:49504
	s_waitcnt lgkmcnt(13)
	v_fma_f32 v41, -v37, v128, v41
	v_fma_f32 v41, -v39, v129, v41
	v_fma_f32 v41, -v40, v130, v41
	v_fma_f32 v41, -v44, v131, v41
	ds_read_b128 v[128:131], v1 offset:49520
	s_waitcnt lgkmcnt(13)
	v_fma_f32 v41, -v46, v132, v41
	v_fma_f32 v41, -v47, v133, v41
	v_fma_f32 v41, -v49, v134, v41
	v_fma_f32 v41, -v51, v135, v41
	ds_read_b128 v[132:135], v1 offset:49536
	s_waitcnt lgkmcnt(13)
	v_fma_f32 v41, -v58, v136, v41
	v_fma_f32 v41, -v59, v137, v41
	v_fma_f32 v41, -v61, v138, v41
	v_fma_f32 v41, -v63, v139, v41
	ds_read_b128 v[136:139], v1 offset:49552
	s_waitcnt lgkmcnt(13)
	v_fma_f32 v41, -v65, v140, v41
	v_fma_f32 v41, -v67, v141, v41
	v_fma_f32 v41, -v69, v142, v41
	v_fma_f32 v41, -v71, v143, v41
	ds_read_b128 v[140:143], v1 offset:49568
	s_waitcnt lgkmcnt(13)
	v_fma_f32 v41, -v73, v144, v41
	v_fma_f32 v41, -v72, v145, v41
	v_fma_f32 v41, -v70, v146, v41
	v_fma_f32 v41, -v68, v147, v41
	ds_read_b128 v[144:147], v1 offset:49584
	s_waitcnt lgkmcnt(13)
	v_fma_f32 v41, -v66, v148, v41
	v_fma_f32 v41, -v64, v149, v41
	v_fma_f32 v41, -v62, v150, v41
	v_fma_f32 v41, -v60, v151, v41
	ds_read_b128 v[148:151], v1 offset:49600
	s_waitcnt lgkmcnt(13)
	v_fma_f32 v41, -v57, v152, v41
	v_fma_f32 v41, -v50, v153, v41
	v_fma_f32 v41, -v154, v48, v41
	v_fma_f32 v41, -v155, v45, v41
	ds_read_b128 v[152:155], v1 offset:49616
	s_waitcnt lgkmcnt(13)
	v_fma_f32 v38, -v0, v100, v38
	v_fma_f32 v38, -v4, v101, v38
	v_fma_f32 v38, -v5, v102, v38
	v_fma_f32 v38, -v6, v103, v38
	ds_read_b128 v[100:103], v1 offset:49632
	s_waitcnt lgkmcnt(13)
	v_fma_f32 v38, -v7, v104, v38
	v_fma_f32 v38, -v8, v105, v38
	v_fma_f32 v38, -v9, v106, v38
	v_fma_f32 v38, -v10, v107, v38
	ds_read_b128 v[104:107], v1 offset:49664
	s_waitcnt lgkmcnt(13)
	v_fma_f32 v38, -v11, v108, v38
	v_fma_f32 v38, -v12, v109, v38
	v_fma_f32 v38, -v13, v110, v38
	v_fma_f32 v38, -v14, v111, v38
	ds_read_b128 v[108:111], v1 offset:49680
	s_waitcnt lgkmcnt(13)
	v_fma_f32 v38, -v15, v112, v38
	v_fma_f32 v38, -v16, v113, v38
	v_fma_f32 v38, -v18, v114, v38
	v_fma_f32 v38, -v19, v115, v38
	ds_read_b128 v[112:115], v1 offset:49696
	s_waitcnt lgkmcnt(13)
	v_fma_f32 v38, -v20, v116, v38
	v_fma_f32 v38, -v22, v117, v38
	v_fma_f32 v38, -v23, v118, v38
	v_fma_f32 v38, -v24, v119, v38
	ds_read_b128 v[116:119], v1 offset:49712
	s_waitcnt lgkmcnt(13)
	v_fma_f32 v38, -v25, v120, v38
	v_fma_f32 v38, -v27, v121, v38
	v_fma_f32 v38, -v28, v122, v38
	v_fma_f32 v38, -v30, v123, v38
	ds_read_b128 v[120:123], v1 offset:49728
	s_waitcnt lgkmcnt(13)
	v_fma_f32 v38, -v31, v124, v38
	v_fma_f32 v38, -v33, v125, v38
	v_fma_f32 v38, -v34, v126, v38
	v_fma_f32 v38, -v36, v127, v38
	ds_read_b128 v[124:127], v1 offset:49744
	s_waitcnt lgkmcnt(13)
	v_fma_f32 v38, -v37, v128, v38
	v_fma_f32 v38, -v39, v129, v38
	v_fma_f32 v38, -v40, v130, v38
	v_fma_f32 v38, -v44, v131, v38
	ds_read_b128 v[128:131], v1 offset:49760
	s_waitcnt lgkmcnt(13)
	v_fma_f32 v38, -v46, v132, v38
	v_fma_f32 v38, -v47, v133, v38
	v_fma_f32 v38, -v49, v134, v38
	v_fma_f32 v38, -v51, v135, v38
	ds_read_b128 v[132:135], v1 offset:49776
	s_waitcnt lgkmcnt(13)
	v_fma_f32 v38, -v58, v136, v38
	v_fma_f32 v38, -v59, v137, v38
	v_fma_f32 v38, -v61, v138, v38
	v_fma_f32 v38, -v63, v139, v38
	ds_read_b128 v[136:139], v1 offset:49792
	s_waitcnt lgkmcnt(13)
; DI void gdnprep_item(const Params& p, int item, unsigned char* ldsb) {
;     ...
;     for (int i = 1; i < 64; ++i) {
;       float a = x[i];
; #pragma unroll
;       for (int j4 = 0; j4 < (i + 3) / 4; ++j4) {
;         f32x4 Lv = *(const f32x4*)(Lm + i * 64 + j4 * 4);
; #pragma unroll
;         for (int e = 0; e < 4; ++e) if (j4 * 4 + e < i) a -= Lv[e] * x[j4 * 4 + e];
;       }
;       x[i] = a;
;       if ((i & 3) == 3) __builtin_amdgcn_sched_barrier(0);
;     }
	v_fma_f32 v38, -v65, v140, v38
	v_fma_f32 v38, -v67, v141, v38
	v_fma_f32 v38, -v69, v142, v38
	v_fma_f32 v38, -v71, v143, v38
	ds_read_b128 v[140:143], v1 offset:49808
	s_waitcnt lgkmcnt(13)
	v_fma_f32 v38, -v73, v144, v38
	v_fma_f32 v38, -v72, v145, v38
	v_fma_f32 v38, -v70, v146, v38
	v_fma_f32 v38, -v68, v147, v38
	ds_read_b128 v[144:147], v1 offset:49824
	s_waitcnt lgkmcnt(13)
	v_fma_f32 v38, -v66, v148, v38
	v_fma_f32 v38, -v64, v149, v38
	v_fma_f32 v38, -v62, v150, v38
	v_fma_f32 v38, -v60, v151, v38
	ds_read_b128 v[148:151], v1 offset:49840
	s_waitcnt lgkmcnt(13)
	v_fma_f32 v38, -v57, v152, v38
	v_fma_f32 v38, -v50, v153, v38
	v_fma_f32 v38, -v48, v154, v38
	v_fma_f32 v38, -v155, v45, v38
	ds_read_b128 v[152:155], v1 offset:49856
	s_waitcnt lgkmcnt(13)
	v_fma_f32 v38, -v100, v41, v38
	ds_read_b128 v[100:103], v1 offset:49872
	s_waitcnt lgkmcnt(13)
	v_fma_f32 v35, -v0, v104, v35
	v_fma_f32 v35, -v4, v105, v35
	v_fma_f32 v35, -v5, v106, v35
	v_fma_f32 v35, -v6, v107, v35
	ds_read_b128 v[104:107], v1 offset:49888
	s_waitcnt lgkmcnt(13)
	v_fma_f32 v35, -v7, v108, v35
	v_fma_f32 v35, -v8, v109, v35
	v_fma_f32 v35, -v9, v110, v35
	v_fma_f32 v35, -v10, v111, v35
	ds_read_b128 v[108:111], v1 offset:49920
	s_waitcnt lgkmcnt(13)
	v_fma_f32 v35, -v11, v112, v35
	v_fma_f32 v35, -v12, v113, v35
	v_fma_f32 v35, -v13, v114, v35
	v_fma_f32 v35, -v14, v115, v35
	ds_read_b128 v[112:115], v1 offset:49936
	s_waitcnt lgkmcnt(13)
	v_fma_f32 v35, -v15, v116, v35
	v_fma_f32 v35, -v16, v117, v35
	v_fma_f32 v35, -v18, v118, v35
	v_fma_f32 v35, -v19, v119, v35
	ds_read_b128 v[116:119], v1 offset:49952
	s_waitcnt lgkmcnt(13)
	v_fma_f32 v35, -v20, v120, v35
	v_fma_f32 v35, -v22, v121, v35
	v_fma_f32 v35, -v23, v122, v35
	v_fma_f32 v35, -v24, v123, v35
	ds_read_b128 v[120:123], v1 offset:49968
	s_waitcnt lgkmcnt(13)
	v_fma_f32 v35, -v25, v124, v35
	v_fma_f32 v35, -v27, v125, v35
	v_fma_f32 v35, -v28, v126, v35
	v_fma_f32 v35, -v30, v127, v35
	ds_read_b128 v[124:127], v1 offset:49984
	s_waitcnt lgkmcnt(13)
	v_fma_f32 v35, -v31, v128, v35
	v_fma_f32 v35, -v33, v129, v35
	v_fma_f32 v35, -v34, v130, v35
	v_fma_f32 v35, -v36, v131, v35
	ds_read_b128 v[128:131], v1 offset:50000
	s_waitcnt lgkmcnt(13)
	v_fma_f32 v35, -v37, v132, v35
	v_fma_f32 v35, -v39, v133, v35
	v_fma_f32 v35, -v40, v134, v35
	v_fma_f32 v35, -v44, v135, v35
	ds_read_b128 v[132:135], v1 offset:50016
	s_waitcnt lgkmcnt(13)
	v_fma_f32 v35, -v46, v136, v35
	v_fma_f32 v35, -v47, v137, v35
	v_fma_f32 v35, -v49, v138, v35
	v_fma_f32 v35, -v51, v139, v35
	ds_read_b128 v[136:139], v1 offset:50032
	s_waitcnt lgkmcnt(13)
	v_fma_f32 v35, -v58, v140, v35
	v_fma_f32 v35, -v59, v141, v35
	v_fma_f32 v35, -v61, v142, v35
	v_fma_f32 v35, -v63, v143, v35
	ds_read_b128 v[140:143], v1 offset:50048
	s_waitcnt lgkmcnt(13)
	v_fma_f32 v35, -v65, v144, v35
	v_fma_f32 v35, -v67, v145, v35
	v_fma_f32 v35, -v69, v146, v35
	v_fma_f32 v35, -v71, v147, v35
	ds_read_b128 v[144:147], v1 offset:50064
	s_waitcnt lgkmcnt(13)
	v_fma_f32 v35, -v73, v148, v35
	v_fma_f32 v35, -v72, v149, v35
	v_fma_f32 v35, -v70, v150, v35
	v_fma_f32 v35, -v68, v151, v35
	ds_read_b128 v[148:151], v1 offset:50080
	s_waitcnt lgkmcnt(13)
	v_fma_f32 v35, -v66, v152, v35
	v_fma_f32 v35, -v64, v153, v35
	v_fma_f32 v35, -v62, v154, v35
	v_fma_f32 v35, -v60, v155, v35
	ds_read_b128 v[152:155], v1 offset:50096
	s_waitcnt lgkmcnt(13)
	v_fma_f32 v35, -v57, v100, v35
	v_fma_f32 v35, -v50, v101, v35
	v_fma_f32 v35, -v48, v102, v35
	v_fma_f32 v35, -v45, v103, v35
	ds_read_b128 v[100:103], v1 offset:50112
	s_waitcnt lgkmcnt(13)
	v_fma_f32 v35, -v104, v41, v35
	v_fma_f32 v35, -v105, v38, v35
	ds_read_b128 v[104:107], v1 offset:50128
	s_waitcnt lgkmcnt(13)
	v_fma_f32 v32, -v0, v108, v32
	v_fma_f32 v32, -v4, v109, v32
	v_fma_f32 v32, -v5, v110, v32
	v_fma_f32 v32, -v6, v111, v32
	ds_read_b128 v[108:111], v1 offset:50144
	s_waitcnt lgkmcnt(13)
	v_fma_f32 v32, -v7, v112, v32
	v_fma_f32 v32, -v8, v113, v32
	v_fma_f32 v32, -v9, v114, v32
	v_fma_f32 v32, -v10, v115, v32
	ds_read_b128 v[112:115], v1 offset:50176
	s_waitcnt lgkmcnt(13)
	v_fma_f32 v32, -v11, v116, v32
	v_fma_f32 v32, -v12, v117, v32
	v_fma_f32 v32, -v13, v118, v32
	v_fma_f32 v32, -v14, v119, v32
	ds_read_b128 v[116:119], v1 offset:50192
	s_waitcnt lgkmcnt(13)
	v_fma_f32 v32, -v15, v120, v32
	v_fma_f32 v32, -v16, v121, v32
	v_fma_f32 v32, -v18, v122, v32
	v_fma_f32 v32, -v19, v123, v32
	ds_read_b128 v[120:123], v1 offset:50208
	s_waitcnt lgkmcnt(13)
	v_fma_f32 v32, -v20, v124, v32
	v_fma_f32 v32, -v22, v125, v32
	v_fma_f32 v32, -v23, v126, v32
	v_fma_f32 v32, -v24, v127, v32
	ds_read_b128 v[124:127], v1 offset:50224
	s_waitcnt lgkmcnt(13)
	v_fma_f32 v32, -v25, v128, v32
	v_fma_f32 v32, -v27, v129, v32
	v_fma_f32 v32, -v28, v130, v32
	v_fma_f32 v32, -v30, v131, v32
	ds_read_b128 v[128:131], v1 offset:50240
	s_waitcnt lgkmcnt(13)
	v_fma_f32 v32, -v31, v132, v32
	v_fma_f32 v32, -v33, v133, v32
	v_fma_f32 v32, -v34, v134, v32
	v_fma_f32 v32, -v36, v135, v32
	ds_read_b128 v[132:135], v1 offset:50256
	s_waitcnt lgkmcnt(13)
	v_fma_f32 v32, -v37, v136, v32
	v_fma_f32 v32, -v39, v137, v32
	v_fma_f32 v32, -v40, v138, v32
	v_fma_f32 v32, -v44, v139, v32
	ds_read_b128 v[136:139], v1 offset:50272
	s_waitcnt lgkmcnt(13)
	v_fma_f32 v32, -v46, v140, v32
	v_fma_f32 v32, -v47, v141, v32
	v_fma_f32 v32, -v49, v142, v32
	v_fma_f32 v32, -v51, v143, v32
	ds_read_b128 v[140:143], v1 offset:50288
	s_waitcnt lgkmcnt(13)
	v_fma_f32 v32, -v58, v144, v32
	v_fma_f32 v32, -v59, v145, v32
	v_fma_f32 v32, -v61, v146, v32
	v_fma_f32 v32, -v63, v147, v32
	ds_read_b128 v[144:147], v1 offset:50304
	s_waitcnt lgkmcnt(13)
; DI void gdnprep_item(const Params& p, int item, unsigned char* ldsb) {
;     ...
;     for (int i = 1; i < 64; ++i) {
;       float a = x[i];
; #pragma unroll
;       for (int j4 = 0; j4 < (i + 3) / 4; ++j4) {
;         f32x4 Lv = *(const f32x4*)(Lm + i * 64 + j4 * 4);
; #pragma unroll
;         for (int e = 0; e < 4; ++e) if (j4 * 4 + e < i) a -= Lv[e] * x[j4 * 4 + e];
;       }
;       x[i] = a;
;       if ((i & 3) == 3) __builtin_amdgcn_sched_barrier(0);
;     }
	v_fma_f32 v32, -v65, v148, v32
	v_fma_f32 v32, -v67, v149, v32
	v_fma_f32 v32, -v69, v150, v32
	v_fma_f32 v32, -v71, v151, v32
	ds_read_b128 v[148:151], v1 offset:50320
	s_waitcnt lgkmcnt(13)
	v_fma_f32 v32, -v73, v152, v32
	v_fma_f32 v32, -v72, v153, v32
	v_fma_f32 v32, -v70, v154, v32
	v_fma_f32 v32, -v68, v155, v32
	ds_read_b128 v[152:155], v1 offset:50336
	s_waitcnt lgkmcnt(13)
	v_fma_f32 v32, -v66, v100, v32
	v_fma_f32 v32, -v64, v101, v32
	v_fma_f32 v32, -v62, v102, v32
	v_fma_f32 v32, -v60, v103, v32
	ds_read_b128 v[100:103], v1 offset:50352
	s_waitcnt lgkmcnt(13)
	v_fma_f32 v32, -v57, v104, v32
	v_fma_f32 v32, -v50, v105, v32
	v_fma_f32 v32, -v48, v106, v32
	v_fma_f32 v32, -v45, v107, v32
	ds_read_b128 v[104:107], v1 offset:50368
	s_waitcnt lgkmcnt(13)
	v_fma_f32 v32, -v41, v108, v32
	v_fma_f32 v32, -v109, v38, v32
	v_fma_f32 v32, -v110, v35, v32
	ds_read_b128 v[108:111], v1 offset:50384
	s_waitcnt lgkmcnt(13)
	v_fma_f32 v29, -v0, v112, v29
	v_fma_f32 v29, -v4, v113, v29
	v_fma_f32 v29, -v5, v114, v29
	v_fma_f32 v29, -v6, v115, v29
	ds_read_b128 v[112:115], v1 offset:50400
	s_waitcnt lgkmcnt(13)
	v_fma_f32 v29, -v7, v116, v29
	v_fma_f32 v29, -v8, v117, v29
	v_fma_f32 v29, -v9, v118, v29
	v_fma_f32 v29, -v10, v119, v29
	ds_read_b128 v[116:119], v1 offset:50432
	s_waitcnt lgkmcnt(13)
	v_fma_f32 v29, -v11, v120, v29
	v_fma_f32 v29, -v12, v121, v29
	v_fma_f32 v29, -v13, v122, v29
	v_fma_f32 v29, -v14, v123, v29
	ds_read_b128 v[120:123], v1 offset:50448
	s_waitcnt lgkmcnt(13)
	v_fma_f32 v29, -v15, v124, v29
	v_fma_f32 v29, -v16, v125, v29
	v_fma_f32 v29, -v18, v126, v29
	v_fma_f32 v29, -v19, v127, v29
	ds_read_b128 v[124:127], v1 offset:50464
	s_waitcnt lgkmcnt(13)
	v_fma_f32 v29, -v20, v128, v29
	v_fma_f32 v29, -v22, v129, v29
	v_fma_f32 v29, -v23, v130, v29
	v_fma_f32 v29, -v24, v131, v29
	ds_read_b128 v[128:131], v1 offset:50480
	s_waitcnt lgkmcnt(13)
	v_fma_f32 v29, -v25, v132, v29
	v_fma_f32 v29, -v27, v133, v29
	v_fma_f32 v29, -v28, v134, v29
	v_fma_f32 v29, -v30, v135, v29
	ds_read_b128 v[132:135], v1 offset:50496
	s_waitcnt lgkmcnt(13)
	v_fma_f32 v29, -v31, v136, v29
	v_fma_f32 v29, -v33, v137, v29
	v_fma_f32 v29, -v34, v138, v29
	v_fma_f32 v29, -v36, v139, v29
	ds_read_b128 v[136:139], v1 offset:50512
	s_waitcnt lgkmcnt(13)
	v_fma_f32 v29, -v37, v140, v29
	v_fma_f32 v29, -v39, v141, v29
	v_fma_f32 v29, -v40, v142, v29
	v_fma_f32 v29, -v44, v143, v29
	ds_read_b128 v[140:143], v1 offset:50528
	s_waitcnt lgkmcnt(13)
	v_fma_f32 v29, -v46, v144, v29
	v_fma_f32 v29, -v47, v145, v29
	v_fma_f32 v29, -v49, v146, v29
	v_fma_f32 v29, -v51, v147, v29
	ds_read_b128 v[144:147], v1 offset:50544
	s_waitcnt lgkmcnt(13)
	v_fma_f32 v29, -v58, v148, v29
	v_fma_f32 v29, -v59, v149, v29
	v_fma_f32 v29, -v61, v150, v29
	v_fma_f32 v29, -v63, v151, v29
	ds_read_b128 v[148:151], v1 offset:50560
	s_waitcnt lgkmcnt(13)
	v_fma_f32 v29, -v65, v152, v29
	v_fma_f32 v29, -v67, v153, v29
	v_fma_f32 v29, -v69, v154, v29
	v_fma_f32 v29, -v71, v155, v29
	ds_read_b128 v[152:155], v1 offset:50576
	s_waitcnt lgkmcnt(13)
	v_fma_f32 v29, -v73, v100, v29
	v_fma_f32 v29, -v72, v101, v29
	v_fma_f32 v29, -v70, v102, v29
	v_fma_f32 v29, -v68, v103, v29
	ds_read_b128 v[100:103], v1 offset:50592
	s_waitcnt lgkmcnt(13)
	v_fma_f32 v29, -v66, v104, v29
	v_fma_f32 v29, -v64, v105, v29
	v_fma_f32 v29, -v62, v106, v29
	v_fma_f32 v29, -v60, v107, v29
	ds_read_b128 v[104:107], v1 offset:50608
	s_waitcnt lgkmcnt(13)
	v_fma_f32 v29, -v57, v108, v29
	v_fma_f32 v29, -v50, v109, v29
	v_fma_f32 v29, -v48, v110, v29
	v_fma_f32 v29, -v45, v111, v29
	ds_read_b128 v[108:111], v1 offset:50624
	s_waitcnt lgkmcnt(13)
	v_fma_f32 v29, -v41, v112, v29
	v_fma_f32 v29, -v38, v113, v29
	v_fma_f32 v29, -v114, v35, v29
	v_fma_f32 v29, -v115, v32, v29
	ds_read_b128 v[112:115], v1 offset:50640
	s_waitcnt lgkmcnt(13)
	v_fma_f32 v26, -v0, v116, v26
	v_fma_f32 v26, -v4, v117, v26
	v_fma_f32 v26, -v5, v118, v26
	v_fma_f32 v26, -v6, v119, v26
	ds_read_b128 v[116:119], v1 offset:50656
	s_waitcnt lgkmcnt(13)
	v_fma_f32 v26, -v7, v120, v26
	v_fma_f32 v26, -v8, v121, v26
	v_fma_f32 v26, -v9, v122, v26
	v_fma_f32 v26, -v10, v123, v26
	ds_read_b128 v[120:123], v1 offset:50672
	s_waitcnt lgkmcnt(13)
	v_fma_f32 v26, -v11, v124, v26
	v_fma_f32 v26, -v12, v125, v26
	v_fma_f32 v26, -v13, v126, v26
	v_fma_f32 v26, -v14, v127, v26
	ds_read_b128 v[124:127], v1 offset:50688
	s_waitcnt lgkmcnt(13)
	v_fma_f32 v26, -v15, v128, v26
	v_fma_f32 v26, -v16, v129, v26
	v_fma_f32 v26, -v18, v130, v26
	v_fma_f32 v26, -v19, v131, v26
	ds_read_b128 v[128:131], v1 offset:50704
	s_waitcnt lgkmcnt(13)
	v_fma_f32 v26, -v20, v132, v26
	v_fma_f32 v26, -v22, v133, v26
	v_fma_f32 v26, -v23, v134, v26
	v_fma_f32 v26, -v24, v135, v26
	ds_read_b128 v[132:135], v1 offset:50720
	s_waitcnt lgkmcnt(13)
	v_fma_f32 v26, -v25, v136, v26
	v_fma_f32 v26, -v27, v137, v26
	v_fma_f32 v26, -v28, v138, v26
	v_fma_f32 v26, -v30, v139, v26
	ds_read_b128 v[136:139], v1 offset:50736
	s_waitcnt lgkmcnt(13)
	v_fma_f32 v26, -v31, v140, v26
	v_fma_f32 v26, -v33, v141, v26
	v_fma_f32 v26, -v34, v142, v26
	v_fma_f32 v26, -v36, v143, v26
	ds_read_b128 v[140:143], v1 offset:50752
	s_waitcnt lgkmcnt(13)
	v_fma_f32 v26, -v37, v144, v26
	v_fma_f32 v26, -v39, v145, v26
	v_fma_f32 v26, -v40, v146, v26
	v_fma_f32 v26, -v44, v147, v26
	ds_read_b128 v[144:147], v1 offset:50768
	s_waitcnt lgkmcnt(13)
	v_fma_f32 v26, -v46, v148, v26
	v_fma_f32 v26, -v47, v149, v26
	v_fma_f32 v26, -v49, v150, v26
	v_fma_f32 v26, -v51, v151, v26
	ds_read_b128 v[148:151], v1 offset:50784
	s_waitcnt lgkmcnt(13)
; DI bf16_t f2bf(float f) { return (bf16_t)(pk2(f, 0.f) & 0xffffu); }
; DI int perm32(int x) { return ((x >> 2) & 3) * 8 + (x >> 4) * 4 + (x & 3); }
; DI void gdnprep_item(const Params& p, int item, unsigned char* ldsb) {
;     ...
;     for (int i = 1; i < 64; ++i) {
;       float a = x[i];
; #pragma unroll
;       for (int j4 = 0; j4 < (i + 3) / 4; ++j4) {
;         f32x4 Lv = *(const f32x4*)(Lm + i * 64 + j4 * 4);
; #pragma unroll
;         for (int e = 0; e < 4; ++e) if (j4 * 4 + e < i) a -= Lv[e] * x[j4 * 4 + e];
;       }
;       x[i] = a;
;       if ((i & 3) == 3) __builtin_amdgcn_sched_barrier(0);
;     }
;     if (!isw) {
; #pragma unroll
;       for (int i8 = 0; i8 < 8; ++i8)
;         *(bf16x8*)(UTp + c * 64 + i8 * 8) = pack8(x[i8 * 8], x[i8 * 8 + 1], x[i8 * 8 + 2], x[i8 * 8 + 3], x[i8 * 8 + 4], x[i8 * 8 + 5], x[i8 * 8 + 6], x[i8 * 8 + 7]);
;     } else {
;       const int pc = (c & ~31) + perm32(c & 31);
; #pragma unroll
;       for (int i = 0; i < 64; ++i) Wp[i * 128 + pc] = f2bf(-x[i]);
;     }
	v_fma_f32 v26, -v58, v152, v26
	v_fma_f32 v26, -v59, v153, v26
	v_fma_f32 v26, -v61, v154, v26
	v_fma_f32 v26, -v63, v155, v26
	ds_read_b128 v[152:155], v1 offset:50800
	s_waitcnt lgkmcnt(13)
	v_fma_f32 v26, -v65, v100, v26
	v_fma_f32 v26, -v67, v101, v26
	v_fma_f32 v26, -v69, v102, v26
	v_fma_f32 v26, -v71, v103, v26
	ds_read_b128 v[100:103], v1 offset:50816
	s_waitcnt lgkmcnt(13)
	v_fma_f32 v26, -v73, v104, v26
	v_fma_f32 v26, -v72, v105, v26
	v_fma_f32 v26, -v70, v106, v26
	v_fma_f32 v26, -v68, v107, v26
	ds_read_b128 v[104:107], v1 offset:50832
	s_waitcnt lgkmcnt(13)
	v_fma_f32 v26, -v66, v108, v26
	v_fma_f32 v26, -v64, v109, v26
	v_fma_f32 v26, -v62, v110, v26
	v_fma_f32 v26, -v60, v111, v26
	ds_read_b128 v[108:111], v1 offset:50848
	s_waitcnt lgkmcnt(13)
	v_fma_f32 v26, -v57, v112, v26
	v_fma_f32 v26, -v50, v113, v26
	v_fma_f32 v26, -v48, v114, v26
	v_fma_f32 v26, -v45, v115, v26
	ds_read_b128 v[112:115], v1 offset:50864
	s_waitcnt lgkmcnt(13)
	v_fma_f32 v26, -v41, v116, v26
	v_fma_f32 v26, -v38, v117, v26
	v_fma_f32 v26, -v35, v118, v26
	v_fma_f32 v26, -v119, v32, v26
	ds_read_b128 v[116:119], v1 offset:50880
	s_waitcnt lgkmcnt(13)
	v_fma_f32 v26, -v120, v29, v26
	ds_read_b128 v[120:123], v1 offset:50896
	s_waitcnt lgkmcnt(13)
	v_fma_f32 v21, -v0, v124, v21
	v_fma_f32 v21, -v4, v125, v21
	v_fma_f32 v21, -v5, v126, v21
	v_fma_f32 v21, -v6, v127, v21
	ds_read_b128 v[124:127], v1 offset:50912
	s_waitcnt lgkmcnt(13)
	v_fma_f32 v21, -v7, v128, v21
	v_fma_f32 v21, -v8, v129, v21
	v_fma_f32 v21, -v9, v130, v21
	v_fma_f32 v21, -v10, v131, v21
	ds_read_b128 v[128:131], v1 offset:50928
	s_waitcnt lgkmcnt(13)
	v_fma_f32 v21, -v11, v132, v21
	v_fma_f32 v21, -v12, v133, v21
	v_fma_f32 v21, -v13, v134, v21
	v_fma_f32 v21, -v14, v135, v21
	ds_read_b128 v[132:135], v1 offset:50944
	s_waitcnt lgkmcnt(13)
	v_fma_f32 v21, -v15, v136, v21
	v_fma_f32 v21, -v16, v137, v21
	v_fma_f32 v21, -v18, v138, v21
	v_fma_f32 v21, -v19, v139, v21
	ds_read_b128 v[136:139], v1 offset:50960
	s_waitcnt lgkmcnt(13)
	v_fma_f32 v21, -v20, v140, v21
	v_fma_f32 v21, -v22, v141, v21
	v_fma_f32 v21, -v23, v142, v21
	v_fma_f32 v21, -v24, v143, v21
	ds_read_b128 v[140:143], v1 offset:50976
	s_waitcnt lgkmcnt(13)
	v_fma_f32 v21, -v25, v144, v21
	v_fma_f32 v21, -v27, v145, v21
	v_fma_f32 v21, -v28, v146, v21
	v_fma_f32 v21, -v30, v147, v21
	ds_read_b128 v[144:147], v1 offset:50992
	s_waitcnt lgkmcnt(13)
	v_fma_f32 v21, -v31, v148, v21
	v_fma_f32 v21, -v33, v149, v21
	v_fma_f32 v21, -v34, v150, v21
	v_fma_f32 v21, -v36, v151, v21
	ds_read_b128 v[148:151], v1 offset:51008
	s_waitcnt lgkmcnt(13)
	v_fma_f32 v21, -v37, v152, v21
	v_fma_f32 v21, -v39, v153, v21
	v_fma_f32 v21, -v40, v154, v21
	v_fma_f32 v21, -v44, v155, v21
	ds_read_b128 v[152:155], v1 offset:51024
	s_waitcnt lgkmcnt(13)
	v_fma_f32 v21, -v46, v100, v21
	v_fma_f32 v21, -v47, v101, v21
	v_fma_f32 v21, -v49, v102, v21
	v_fma_f32 v21, -v51, v103, v21
	ds_read_b128 v[100:103], v1 offset:51040
	s_waitcnt lgkmcnt(13)
	v_fma_f32 v21, -v58, v104, v21
	v_fma_f32 v21, -v59, v105, v21
	v_fma_f32 v21, -v61, v106, v21
	v_fma_f32 v21, -v63, v107, v21
	ds_read_b128 v[104:107], v1 offset:51056
	s_waitcnt lgkmcnt(13)
	v_fma_f32 v21, -v65, v108, v21
	v_fma_f32 v21, -v67, v109, v21
	v_fma_f32 v21, -v69, v110, v21
	v_fma_f32 v21, -v71, v111, v21
	ds_read_b128 v[108:111], v1 offset:51072
	s_waitcnt lgkmcnt(13)
	v_fma_f32 v21, -v73, v112, v21
	v_fma_f32 v21, -v72, v113, v21
	v_fma_f32 v21, -v70, v114, v21
	v_fma_f32 v21, -v68, v115, v21
	ds_read_b128 v[112:115], v1 offset:51088
	s_waitcnt lgkmcnt(13)
	v_fma_f32 v21, -v66, v116, v21
	v_fma_f32 v21, -v64, v117, v21
	v_fma_f32 v21, -v62, v118, v21
	v_fma_f32 v21, -v60, v119, v21
	ds_read_b128 v[116:119], v1 offset:51104
	s_waitcnt lgkmcnt(13)
	v_fma_f32 v21, -v57, v120, v21
	v_fma_f32 v21, -v50, v121, v21
	v_fma_f32 v21, -v48, v122, v21
	v_fma_f32 v21, -v45, v123, v21
	ds_read_b128 v[120:123], v1 offset:51120
	s_waitcnt lgkmcnt(13)
	v_fma_f32 v21, -v41, v124, v21
	v_fma_f32 v21, -v38, v125, v21
	v_fma_f32 v21, -v35, v126, v21
	v_fma_f32 v21, -v32, v127, v21
	ds_read_b128 v[124:127], v1 offset:51136
	s_waitcnt lgkmcnt(13)
	v_fma_f32 v21, -v128, v29, v21
	s_waitcnt lgkmcnt(12)
	v_fma_f32 v17, -v0, v132, v17
	v_fma_f32 v17, -v4, v133, v17
	v_fma_f32 v17, -v5, v134, v17
	v_fma_f32 v17, -v6, v135, v17
	v_fma_f32 v74, -v129, v26, v21
	ds_read_b128 v[128:131], v1 offset:51152
	ds_read_b128 v[132:135], v1 offset:51168
	s_waitcnt lgkmcnt(13)
	v_fma_f32 v17, -v7, v136, v17
	v_fma_f32 v17, -v8, v137, v17
	v_fma_f32 v17, -v9, v138, v17
	v_fma_f32 v17, -v10, v139, v17
	ds_read_b128 v[136:139], v1 offset:51184
	s_waitcnt lgkmcnt(13)
	v_fma_f32 v17, -v11, v140, v17
	v_fma_f32 v17, -v12, v141, v17
	v_fma_f32 v17, -v13, v142, v17
	v_fma_f32 v17, -v14, v143, v17
	s_waitcnt lgkmcnt(12)
	v_fma_f32 v17, -v15, v144, v17
	v_fma_f32 v17, -v16, v145, v17
	v_fma_f32 v17, -v18, v146, v17
	v_fma_f32 v17, -v19, v147, v17
	s_waitcnt lgkmcnt(11)
	v_fma_f32 v17, -v20, v148, v17
	v_fma_f32 v17, -v22, v149, v17
	v_fma_f32 v17, -v23, v150, v17
	v_fma_f32 v17, -v24, v151, v17
	s_waitcnt lgkmcnt(10)
	v_fma_f32 v17, -v25, v152, v17
	v_fma_f32 v17, -v27, v153, v17
	v_fma_f32 v17, -v28, v154, v17
	v_fma_f32 v17, -v30, v155, v17
	s_waitcnt lgkmcnt(9)
	v_fma_f32 v17, -v31, v100, v17
	v_fma_f32 v17, -v33, v101, v17
	v_fma_f32 v17, -v34, v102, v17
	v_fma_f32 v17, -v36, v103, v17
	s_waitcnt lgkmcnt(8)
	v_fma_f32 v17, -v37, v104, v17
	v_fma_f32 v17, -v39, v105, v17
	v_fma_f32 v17, -v40, v106, v17
	v_fma_f32 v17, -v44, v107, v17
	s_waitcnt lgkmcnt(7)
	v_fma_f32 v17, -v46, v108, v17
	v_fma_f32 v17, -v47, v109, v17
	v_fma_f32 v17, -v49, v110, v17
	v_fma_f32 v17, -v51, v111, v17
	s_waitcnt lgkmcnt(6)
	v_fma_f32 v17, -v58, v112, v17
	v_fma_f32 v17, -v59, v113, v17
	v_fma_f32 v17, -v61, v114, v17
	v_fma_f32 v17, -v63, v115, v17
	s_waitcnt lgkmcnt(5)
	v_fma_f32 v17, -v65, v116, v17
	v_fma_f32 v17, -v67, v117, v17
	v_fma_f32 v17, -v69, v118, v17
	v_fma_f32 v17, -v71, v119, v17
	s_waitcnt lgkmcnt(4)
	v_fma_f32 v17, -v73, v120, v17
	v_fma_f32 v17, -v72, v121, v17
	v_fma_f32 v17, -v70, v122, v17
	v_fma_f32 v17, -v68, v123, v17
	s_waitcnt lgkmcnt(3)
	v_fma_f32 v17, -v66, v124, v17
	v_fma_f32 v17, -v64, v125, v17
	v_fma_f32 v17, -v62, v126, v17
	v_fma_f32 v17, -v60, v127, v17
	s_waitcnt lgkmcnt(2)
	v_fma_f32 v17, -v57, v128, v17
	v_fma_f32 v17, -v50, v129, v17
	v_fma_f32 v17, -v48, v130, v17
	v_fma_f32 v17, -v45, v131, v17
	s_waitcnt lgkmcnt(1)
	v_fma_f32 v17, -v41, v132, v17
	v_fma_f32 v17, -v38, v133, v17
	v_fma_f32 v17, -v35, v134, v17
	v_fma_f32 v17, -v32, v135, v17
	s_waitcnt lgkmcnt(0)
	v_fma_f32 v17, -v29, v136, v17
	v_fma_f32 v17, -v137, v26, v17
	v_fma_f32 v75, -v138, v74, v17
	v_lshlrev_b32_e32 v17, 1, v42
	v_lshrrev_b32_e32 v77, 2, v42
	v_and_b32_e32 v21, 0x60, v42
	v_and_b32_e32 v76, 24, v17
	v_and_b32_e32 v77, 4, v77
	s_and_saveexec_b64 s[0:1], vcc
	s_xor_b64 s[0:1], exec, s[0:1]
	s_cbranch_execz .LBB0_835
; DI unsigned pk2(float lo, float hi) { f32x2_t v; v[0] = lo; v[1] = hi; bf16x2_t b = __builtin_convertvector(v, bf16x2_t); return __builtin_bit_cast(unsigned, b); }
; DI bf16x8 pack8(float a0, float a1, float a2, float a3, float a4, float a5, float a6, float a7) {
;   u32x4 u; u.x = pk2(a0, a1); u.y = pk2(a2, a3); u.z = pk2(a4, a5); u.w = pk2(a6, a7);
;   return __builtin_bit_cast(bf16x8, u);
; DI void gdnprep_item(const Params& p, int item, unsigned char* ldsb) {
;     ...
;     if (!isw) {
; #pragma unroll
;       for (int i8 = 0; i8 < 8; ++i8)
;         *(bf16x8*)(UTp + c * 64 + i8 * 8) = pack8(x[i8 * 8], x[i8 * 8 + 1], x[i8 * 8 + 2], x[i8 * 8 + 3], x[i8 * 8 + 4], x[i8 * 8 + 5], x[i8 * 8 + 6], x[i8 * 8 + 7]);
;     } else {
	s_lshl_b64 s[4:5], s[38:39], 1
	s_add_u32 s4, s74, s4
	s_addc_u32 s5, s75, s5
	v_lshlrev_b32_e32 v3, 7, v3
	v_cvt_pk_bf16_f32 v4, v0, v4
	v_cvt_pk_bf16_f32 v5, v5, v6
	v_cvt_pk_bf16_f32 v6, v7, v8
	v_cvt_pk_bf16_f32 v7, v9, v10
	global_store_dwordx4 v3, v[4:7], s[4:5]
	v_and_b32_e32 v21, 0x60, v42
	v_or3_b32 v17, v77, v76, v56
	v_cvt_pk_bf16_f32 v4, v11, v12
	v_cvt_pk_bf16_f32 v5, v13, v14
	v_cvt_pk_bf16_f32 v6, v15, v16
	v_cvt_pk_bf16_f32 v7, v18, v19
	global_store_dwordx4 v3, v[4:7], s[4:5] offset:16
	s_nop 1
	v_cvt_pk_bf16_f32 v4, v20, v22
	v_cvt_pk_bf16_f32 v5, v23, v24
	v_cvt_pk_bf16_f32 v6, v25, v27
	v_cvt_pk_bf16_f32 v7, v28, v30
	global_store_dwordx4 v3, v[4:7], s[4:5] offset:32
	s_nop 1
	v_cvt_pk_bf16_f32 v4, v31, v33
	v_cvt_pk_bf16_f32 v5, v34, v36
	v_cvt_pk_bf16_f32 v6, v37, v39
	v_cvt_pk_bf16_f32 v7, v40, v44
	global_store_dwordx4 v3, v[4:7], s[4:5] offset:48
	s_nop 1
	v_cvt_pk_bf16_f32 v4, v46, v47
	v_cvt_pk_bf16_f32 v5, v49, v51
	v_cvt_pk_bf16_f32 v6, v58, v59
	v_cvt_pk_bf16_f32 v7, v61, v63
	global_store_dwordx4 v3, v[4:7], s[4:5] offset:64
	s_nop 1
	v_cvt_pk_bf16_f32 v4, v65, v67
	v_cvt_pk_bf16_f32 v5, v69, v71
	v_cvt_pk_bf16_f32 v6, v73, v72
	v_cvt_pk_bf16_f32 v7, v70, v68
	global_store_dwordx4 v3, v[4:7], s[4:5] offset:80
	s_nop 1
	v_cvt_pk_bf16_f32 v4, v66, v64
	v_cvt_pk_bf16_f32 v5, v62, v60
	v_cvt_pk_bf16_f32 v6, v57, v50
	v_cvt_pk_bf16_f32 v7, v48, v45
	global_store_dwordx4 v3, v[4:7], s[4:5] offset:96
	s_nop 1
	v_cvt_pk_bf16_f32 v4, v41, v38
	v_cvt_pk_bf16_f32 v5, v35, v32
	v_cvt_pk_bf16_f32 v6, v29, v26
	v_cvt_pk_bf16_f32 v7, v74, v75
	global_store_dwordx4 v3, v[4:7], s[4:5] offset:112
